# on v133: per-iteration LDS read-address v_add_u32 pair of five K-loops hoisted to once per unit
# speedup vs baseline: 1.0177x; 1.0018x over previous
.LBB0_244:
	s_ashr_i32 s37, s36, 31
	s_lshl_b64 s[38:39], s[36:37], 19
	s_add_u32 s38, s2, s38
	s_addc_u32 s39, s21, s39
	s_and_b64 s[40:41], s[4:5], exec
	s_cselect_b32 s7, s39, s45
	s_cselect_b32 s37, s38, s44
	s_ashr_i32 s25, s24, 31
	s_lshl_b64 s[40:41], s[24:25], 19
	s_add_u32 s40, s8, s40
	s_addc_u32 s41, s9, s41
	s_and_b64 s[48:49], s[4:5], exec
	s_cselect_b32 s25, s41, s47
	s_cselect_b32 s43, s40, s46
	s_add_u32 s44, s44, 0x40080
	s_addc_u32 s45, s45, 0
	s_add_u32 s61, s46, 0x100
	s_addc_u32 s62, s47, 0
	s_mov_b32 s63, -2
	ds_read_b128 v[144:147], v178
	ds_read_b128 v[148:151], v178 offset:1024
	ds_read_b128 v[152:155], v178 offset:2048
	ds_read_b128 v[156:159], v178 offset:3072
	ds_read_b128 v[160:163], v179
	ds_read_b128 v[164:167], v179 offset:1024
	ds_read_b128 v[168:171], v179 offset:2048
	ds_read_b128 v[182:185], v179 offset:3072
	s_add_u32 s46, s44, 0xfffc0080
	s_addc_u32 s47, s45, -1
	s_cmp_eq_u32 s63, 12
	s_cselect_b32 s49, s7, s47
	s_cselect_b32 s48, s37, s46
	s_cselect_b32 s47, s25, s62
	s_cselect_b32 s46, s43, s61
	s_add_i32 m0, s31, 0xc000
	ds_read_b128 v[186:189], v180
	ds_read_b128 v[190:193], v180 offset:1024
	ds_read_b128 v[194:197], v180 offset:2048
	ds_read_b128 v[198:201], v180 offset:3072
	ds_read_b128 v[202:205], v180 offset:4096
	ds_read_b128 v[210:213], v180 offset:5120
	ds_read_b128 v[214:217], v180 offset:6144
	ds_read_b128 v[218:221], v180 offset:7168
	global_load_lds_dwordx4 v136, s[44:45]
	s_add_i32 m0, s31, 0xe000
	s_nop 0
	global_load_lds_dwordx4 v138, s[44:45]
	s_waitcnt vmcnt(8)
	s_waitcnt lgkmcnt(0)
	s_barrier
	s_setprio 1
	s_waitcnt lgkmcnt(0)
	v_mfma_f32_16x16x32_bf16 v[124:127], v[144:147], v[186:189], 0
	v_mfma_f32_16x16x32_bf16 v[120:123], v[152:155], v[186:189], 0
	v_mfma_f32_16x16x32_bf16 v[108:111], v[144:147], v[194:197], 0
	v_mfma_f32_16x16x32_bf16 v[104:107], v[152:155], v[194:197], 0
	v_mfma_f32_16x16x32_bf16 v[92:95], v[144:147], v[202:205], 0
	v_mfma_f32_16x16x32_bf16 v[88:91], v[152:155], v[202:205], 0
	v_mfma_f32_16x16x32_bf16 v[76:79], v[144:147], v[214:217], 0
	v_mfma_f32_16x16x32_bf16 v[72:75], v[152:155], v[214:217], 0
	v_mfma_f32_16x16x32_bf16 v[124:127], v[148:151], v[190:193], v[124:127]
	v_mfma_f32_16x16x32_bf16 v[120:123], v[156:159], v[190:193], v[120:123]
	v_mfma_f32_16x16x32_bf16 v[108:111], v[148:151], v[198:201], v[108:111]
	v_mfma_f32_16x16x32_bf16 v[104:107], v[156:159], v[198:201], v[104:107]
	v_mfma_f32_16x16x32_bf16 v[92:95], v[148:151], v[210:213], v[92:95]
	v_mfma_f32_16x16x32_bf16 v[88:91], v[156:159], v[210:213], v[88:91]
	v_mfma_f32_16x16x32_bf16 v[76:79], v[148:151], v[218:221], v[76:79]
	v_mfma_f32_16x16x32_bf16 v[72:75], v[156:159], v[218:221], v[72:75]
	v_mfma_f32_16x16x32_bf16 v[116:119], v[160:163], v[186:189], 0
	v_mfma_f32_16x16x32_bf16 v[112:115], v[168:171], v[186:189], 0
	v_mfma_f32_16x16x32_bf16 v[100:103], v[160:163], v[194:197], 0
	v_mfma_f32_16x16x32_bf16 v[96:99], v[168:171], v[194:197], 0
	v_mfma_f32_16x16x32_bf16 v[84:87], v[160:163], v[202:205], 0
	v_mfma_f32_16x16x32_bf16 v[80:83], v[168:171], v[202:205], 0
	v_mfma_f32_16x16x32_bf16 v[68:71], v[160:163], v[214:217], 0
	v_mfma_f32_16x16x32_bf16 v[64:67], v[168:171], v[214:217], 0
	v_mfma_f32_16x16x32_bf16 v[116:119], v[164:167], v[190:193], v[116:119]
	v_mfma_f32_16x16x32_bf16 v[112:115], v[182:185], v[190:193], v[112:115]
	v_mfma_f32_16x16x32_bf16 v[100:103], v[164:167], v[198:201], v[100:103]
	v_mfma_f32_16x16x32_bf16 v[96:99], v[182:185], v[198:201], v[96:99]
	v_mfma_f32_16x16x32_bf16 v[84:87], v[164:167], v[210:213], v[84:87]
	v_mfma_f32_16x16x32_bf16 v[80:83], v[182:185], v[210:213], v[80:83]
	v_mfma_f32_16x16x32_bf16 v[68:71], v[164:167], v[218:221], v[68:71]
	v_mfma_f32_16x16x32_bf16 v[64:67], v[182:185], v[218:221], v[64:67]
	s_setprio 0
	s_barrier
	s_add_u32 s98, s46, s16
	s_addc_u32 s99, s47, s17
	s_add_u32 s100, s48, s16
	s_addc_u32 s101, s49, s17
	s_add_i32 s64, s35, s23
	s_mov_b32 m0, s64
	ds_read_b128 v[186:189], v180 offset:16384
	ds_read_b128 v[190:193], v180 offset:17408
	ds_read_b128 v[194:197], v180 offset:18432
	ds_read_b128 v[198:201], v180 offset:19456
	ds_read_b128 v[202:205], v180 offset:20480
	ds_read_b128 v[210:213], v180 offset:21504
	ds_read_b128 v[214:217], v180 offset:22528
	ds_read_b128 v[218:221], v180 offset:23552
	global_load_lds_dwordx4 v130, s[46:47]
	s_add_i32 m0, s64, 0x2000
	s_add_u32 s64, s46, 0x40000
	s_addc_u32 s65, s47, 0
	s_add_i32 s66, s59, s23
	global_load_lds_dwordx4 v134, s[46:47]
	s_mov_b32 m0, s66
	s_nop 0
	global_load_lds_dwordx4 v130, s[64:65]
	s_add_i32 m0, s66, 0x2000
	s_nop 0
	global_load_lds_dwordx4 v134, s[64:65]
	s_mov_b32 m0, s31
	s_nop 0
	global_load_lds_dwordx4 v128, s[48:49]
	s_mov_b32 m0, s50
	s_nop 0
	global_load_lds_dwordx4 v132, s[48:49]
	s_waitcnt vmcnt(8)
	s_waitcnt lgkmcnt(0)
	s_barrier
	s_setprio 1
	s_waitcnt lgkmcnt(0)
	v_mfma_f32_16x16x32_bf16 v[60:63], v[144:147], v[186:189], 0
	v_mfma_f32_16x16x32_bf16 v[56:59], v[152:155], v[186:189], 0
	v_mfma_f32_16x16x32_bf16 v[44:47], v[144:147], v[194:197], 0
	v_mfma_f32_16x16x32_bf16 v[40:43], v[152:155], v[194:197], 0
	v_mfma_f32_16x16x32_bf16 v[28:31], v[144:147], v[202:205], 0
	v_mfma_f32_16x16x32_bf16 v[24:27], v[152:155], v[202:205], 0
	v_mfma_f32_16x16x32_bf16 v[12:15], v[144:147], v[214:217], 0
	v_mfma_f32_16x16x32_bf16 v[8:11], v[152:155], v[214:217], 0
	v_mfma_f32_16x16x32_bf16 v[60:63], v[148:151], v[190:193], v[60:63]
	v_mfma_f32_16x16x32_bf16 v[56:59], v[156:159], v[190:193], v[56:59]
	v_mfma_f32_16x16x32_bf16 v[44:47], v[148:151], v[198:201], v[44:47]
	v_mfma_f32_16x16x32_bf16 v[40:43], v[156:159], v[198:201], v[40:43]
	v_mfma_f32_16x16x32_bf16 v[28:31], v[148:151], v[210:213], v[28:31]
	v_mfma_f32_16x16x32_bf16 v[24:27], v[156:159], v[210:213], v[24:27]
	v_mfma_f32_16x16x32_bf16 v[12:15], v[148:151], v[218:221], v[12:15]
	v_mfma_f32_16x16x32_bf16 v[8:11], v[156:159], v[218:221], v[8:11]
	v_mfma_f32_16x16x32_bf16 v[52:55], v[160:163], v[186:189], 0
	v_mfma_f32_16x16x32_bf16 v[48:51], v[168:171], v[186:189], 0
	v_mfma_f32_16x16x32_bf16 v[36:39], v[160:163], v[194:197], 0
	v_mfma_f32_16x16x32_bf16 v[32:35], v[168:171], v[194:197], 0
	v_mfma_f32_16x16x32_bf16 v[20:23], v[160:163], v[202:205], 0
	v_mfma_f32_16x16x32_bf16 v[16:19], v[168:171], v[202:205], 0
	v_mfma_f32_16x16x32_bf16 v[4:7], v[160:163], v[214:217], 0
	v_mfma_f32_16x16x32_bf16 v[0:3], v[168:171], v[214:217], 0
	v_mfma_f32_16x16x32_bf16 v[52:55], v[164:167], v[190:193], v[52:55]
	v_mfma_f32_16x16x32_bf16 v[48:51], v[182:185], v[190:193], v[48:51]
	v_mfma_f32_16x16x32_bf16 v[36:39], v[164:167], v[198:201], v[36:39]
	v_mfma_f32_16x16x32_bf16 v[32:35], v[182:185], v[198:201], v[32:35]
	v_mfma_f32_16x16x32_bf16 v[20:23], v[164:167], v[210:213], v[20:23]
	v_mfma_f32_16x16x32_bf16 v[16:19], v[182:185], v[210:213], v[16:19]
	v_mfma_f32_16x16x32_bf16 v[4:7], v[164:167], v[218:221], v[4:7]
	v_mfma_f32_16x16x32_bf16 v[0:3], v[182:185], v[218:221], v[0:3]
	s_setprio 0
	s_barrier
	s_add_i32 s64, 0, 0x18000
	s_add_i32 s65, 0, 0x1c000
	v_add_u32_e32 v156, s64, v176
	v_add_u32_e32 v181, s65, v176
	ds_read_b128 v[144:147], v156
	ds_read_b128 v[148:151], v156 offset:1024
	ds_read_b128 v[152:155], v156 offset:2048
	ds_read_b128 v[156:159], v156 offset:3072
	ds_read_b128 v[160:163], v181
	ds_read_b128 v[164:167], v181 offset:1024
	ds_read_b128 v[168:171], v181 offset:2048
	ds_read_b128 v[182:185], v181 offset:3072
	s_add_u32 s48, s48, 0x40000
	s_addc_u32 s49, s49, 0
	s_mov_b32 m0, s51
	ds_read_b128 v[186:189], v180 offset:32768
	ds_read_b128 v[190:193], v180 offset:33792
	ds_read_b128 v[194:197], v180 offset:34816
	ds_read_b128 v[198:201], v180 offset:35840
	ds_read_b128 v[202:205], v180 offset:36864
	ds_read_b128 v[210:213], v180 offset:37888
	ds_read_b128 v[214:217], v180 offset:38912
	ds_read_b128 v[218:221], v180 offset:39936
	global_load_lds_dwordx4 v128, s[48:49]
	s_mov_b32 m0, s52
	s_nop 0
	global_load_lds_dwordx4 v132, s[48:49]
	s_waitcnt vmcnt(8)
	s_waitcnt lgkmcnt(0)
	s_barrier
	s_setprio 1
	s_waitcnt lgkmcnt(0)
	v_mfma_f32_16x16x32_bf16 v[124:127], v[144:147], v[186:189], v[124:127]
	v_mfma_f32_16x16x32_bf16 v[120:123], v[152:155], v[186:189], v[120:123]
	v_mfma_f32_16x16x32_bf16 v[108:111], v[144:147], v[194:197], v[108:111]
	v_mfma_f32_16x16x32_bf16 v[104:107], v[152:155], v[194:197], v[104:107]
	v_mfma_f32_16x16x32_bf16 v[92:95], v[144:147], v[202:205], v[92:95]
	v_mfma_f32_16x16x32_bf16 v[88:91], v[152:155], v[202:205], v[88:91]
	v_mfma_f32_16x16x32_bf16 v[76:79], v[144:147], v[214:217], v[76:79]
	v_mfma_f32_16x16x32_bf16 v[72:75], v[152:155], v[214:217], v[72:75]
	v_mfma_f32_16x16x32_bf16 v[124:127], v[148:151], v[190:193], v[124:127]
	v_mfma_f32_16x16x32_bf16 v[120:123], v[156:159], v[190:193], v[120:123]
	v_mfma_f32_16x16x32_bf16 v[108:111], v[148:151], v[198:201], v[108:111]
	v_mfma_f32_16x16x32_bf16 v[104:107], v[156:159], v[198:201], v[104:107]
	v_mfma_f32_16x16x32_bf16 v[92:95], v[148:151], v[210:213], v[92:95]
	v_mfma_f32_16x16x32_bf16 v[88:91], v[156:159], v[210:213], v[88:91]
	v_mfma_f32_16x16x32_bf16 v[76:79], v[148:151], v[218:221], v[76:79]
	v_mfma_f32_16x16x32_bf16 v[72:75], v[156:159], v[218:221], v[72:75]
	v_mfma_f32_16x16x32_bf16 v[116:119], v[160:163], v[186:189], v[116:119]
	v_mfma_f32_16x16x32_bf16 v[112:115], v[168:171], v[186:189], v[112:115]
	v_mfma_f32_16x16x32_bf16 v[100:103], v[160:163], v[194:197], v[100:103]
	v_mfma_f32_16x16x32_bf16 v[96:99], v[168:171], v[194:197], v[96:99]
	v_mfma_f32_16x16x32_bf16 v[84:87], v[160:163], v[202:205], v[84:87]
	v_mfma_f32_16x16x32_bf16 v[80:83], v[168:171], v[202:205], v[80:83]
	v_mfma_f32_16x16x32_bf16 v[68:71], v[160:163], v[214:217], v[68:71]
	v_mfma_f32_16x16x32_bf16 v[64:67], v[168:171], v[214:217], v[64:67]
	v_mfma_f32_16x16x32_bf16 v[116:119], v[164:167], v[190:193], v[116:119]
	v_mfma_f32_16x16x32_bf16 v[112:115], v[182:185], v[190:193], v[112:115]
	v_mfma_f32_16x16x32_bf16 v[100:103], v[164:167], v[198:201], v[100:103]
	v_mfma_f32_16x16x32_bf16 v[96:99], v[182:185], v[198:201], v[96:99]
	v_mfma_f32_16x16x32_bf16 v[84:87], v[164:167], v[210:213], v[84:87]
	v_mfma_f32_16x16x32_bf16 v[80:83], v[182:185], v[210:213], v[80:83]
	v_mfma_f32_16x16x32_bf16 v[68:71], v[164:167], v[218:221], v[68:71]
	v_mfma_f32_16x16x32_bf16 v[64:67], v[182:185], v[218:221], v[64:67]
	s_setprio 0
	s_barrier
	s_add_i32 s48, s64, s23
	s_mov_b32 m0, s48
	ds_read_b128 v[186:189], v180 offset:49152
	ds_read_b128 v[190:193], v180 offset:50176
	ds_read_b128 v[194:197], v180 offset:51200
	ds_read_b128 v[198:201], v180 offset:52224
	ds_read_b128 v[202:205], v180 offset:53248
	ds_read_b128 v[210:213], v180 offset:54272
	ds_read_b128 v[214:217], v180 offset:55296
	ds_read_b128 v[218:221], v180 offset:56320
	global_load_lds_dwordx4 v130, s[98:99]
	s_add_i32 m0, s48, 0x2000
	s_add_u32 s46, s46, 0x40080
	s_addc_u32 s47, s47, 0
	s_add_i32 s48, s65, s23
	global_load_lds_dwordx4 v134, s[98:99]
	s_mov_b32 m0, s48
	s_nop 0
	global_load_lds_dwordx4 v130, s[46:47]
	s_add_i32 m0, s48, 0x2000
	s_nop 0
	global_load_lds_dwordx4 v134, s[46:47]
	s_mov_b32 m0, s54
	s_nop 0
	global_load_lds_dwordx4 v128, s[100:101]
	s_mov_b32 m0, s55
	s_nop 0
	global_load_lds_dwordx4 v132, s[100:101]
	s_waitcnt vmcnt(8)
	s_waitcnt lgkmcnt(0)
	s_barrier
	s_setprio 1
	s_waitcnt lgkmcnt(0)
	v_mfma_f32_16x16x32_bf16 v[60:63], v[144:147], v[186:189], v[60:63]
	v_mfma_f32_16x16x32_bf16 v[56:59], v[152:155], v[186:189], v[56:59]
	v_mfma_f32_16x16x32_bf16 v[44:47], v[144:147], v[194:197], v[44:47]
	v_mfma_f32_16x16x32_bf16 v[40:43], v[152:155], v[194:197], v[40:43]
	v_mfma_f32_16x16x32_bf16 v[28:31], v[144:147], v[202:205], v[28:31]
	v_mfma_f32_16x16x32_bf16 v[24:27], v[152:155], v[202:205], v[24:27]
	v_mfma_f32_16x16x32_bf16 v[12:15], v[144:147], v[214:217], v[12:15]
	v_mfma_f32_16x16x32_bf16 v[8:11], v[152:155], v[214:217], v[8:11]
	v_mfma_f32_16x16x32_bf16 v[60:63], v[148:151], v[190:193], v[60:63]
	v_mfma_f32_16x16x32_bf16 v[56:59], v[156:159], v[190:193], v[56:59]
	v_mfma_f32_16x16x32_bf16 v[44:47], v[148:151], v[198:201], v[44:47]
	v_mfma_f32_16x16x32_bf16 v[40:43], v[156:159], v[198:201], v[40:43]
	v_mfma_f32_16x16x32_bf16 v[28:31], v[148:151], v[210:213], v[28:31]
	v_mfma_f32_16x16x32_bf16 v[24:27], v[156:159], v[210:213], v[24:27]
	v_mfma_f32_16x16x32_bf16 v[12:15], v[148:151], v[218:221], v[12:15]
	v_mfma_f32_16x16x32_bf16 v[8:11], v[156:159], v[218:221], v[8:11]
	v_mfma_f32_16x16x32_bf16 v[52:55], v[160:163], v[186:189], v[52:55]
	v_mfma_f32_16x16x32_bf16 v[48:51], v[168:171], v[186:189], v[48:51]
	v_mfma_f32_16x16x32_bf16 v[36:39], v[160:163], v[194:197], v[36:39]
	v_mfma_f32_16x16x32_bf16 v[32:35], v[168:171], v[194:197], v[32:35]
	v_mfma_f32_16x16x32_bf16 v[20:23], v[160:163], v[202:205], v[20:23]
	v_mfma_f32_16x16x32_bf16 v[16:19], v[168:171], v[202:205], v[16:19]
	v_mfma_f32_16x16x32_bf16 v[4:7], v[160:163], v[214:217], v[4:7]
	v_mfma_f32_16x16x32_bf16 v[0:3], v[168:171], v[214:217], v[0:3]
	v_mfma_f32_16x16x32_bf16 v[52:55], v[164:167], v[190:193], v[52:55]
	v_mfma_f32_16x16x32_bf16 v[48:51], v[182:185], v[190:193], v[48:51]
	v_mfma_f32_16x16x32_bf16 v[36:39], v[164:167], v[198:201], v[36:39]
	v_mfma_f32_16x16x32_bf16 v[32:35], v[182:185], v[198:201], v[32:35]
	v_mfma_f32_16x16x32_bf16 v[20:23], v[164:167], v[210:213], v[20:23]
	v_mfma_f32_16x16x32_bf16 v[16:19], v[182:185], v[210:213], v[16:19]
	v_mfma_f32_16x16x32_bf16 v[4:7], v[164:167], v[218:221], v[4:7]
	v_mfma_f32_16x16x32_bf16 v[0:3], v[182:185], v[218:221], v[0:3]
	s_setprio 0
	s_barrier
	s_add_i32 s63, s63, 2
	s_add_u32 s44, s44, 0x100
	s_addc_u32 s45, s45, 0
	s_add_u32 s61, s61, 0x100
	s_addc_u32 s62, s62, 0
	s_cmp_gt_u32 s63, 13
	s_cbranch_scc1 .Lkexit_0
	v_add_u32_e32 v248, 0x18000, v176
	v_add_u32_e32 v249, 0x1c000, v176
.LBB0_245:
	ds_read_b128 v[144:147], v178
	ds_read_b128 v[148:151], v178 offset:1024
	ds_read_b128 v[152:155], v178 offset:2048
	ds_read_b128 v[156:159], v178 offset:3072
	ds_read_b128 v[160:163], v179
	ds_read_b128 v[164:167], v179 offset:1024
	ds_read_b128 v[168:171], v179 offset:2048
	ds_read_b128 v[182:185], v179 offset:3072
	s_add_u32 s46, s44, 0xfffc0080
	s_addc_u32 s47, s45, -1
	s_cmp_eq_u32 s63, 12
	s_cselect_b32 s49, s7, s47
	s_cselect_b32 s48, s37, s46
	s_cselect_b32 s47, s25, s62
	s_cselect_b32 s46, s43, s61
	s_add_i32 m0, s31, 0xc000
	ds_read_b128 v[186:189], v180
	ds_read_b128 v[190:193], v180 offset:1024
	ds_read_b128 v[194:197], v180 offset:2048
	ds_read_b128 v[198:201], v180 offset:3072
	ds_read_b128 v[202:205], v180 offset:4096
	ds_read_b128 v[210:213], v180 offset:5120
	ds_read_b128 v[214:217], v180 offset:6144
	ds_read_b128 v[218:221], v180 offset:7168
	global_load_lds_dwordx4 v136, s[44:45]
	s_add_i32 m0, s31, 0xe000
	s_nop 0
	global_load_lds_dwordx4 v138, s[44:45]
	s_waitcnt vmcnt(8)
	s_waitcnt lgkmcnt(0)
	s_barrier
	s_setprio 1
	s_waitcnt lgkmcnt(0)
	v_mfma_f32_16x16x32_bf16 v[124:127], v[144:147], v[186:189], v[124:127]
	v_mfma_f32_16x16x32_bf16 v[120:123], v[152:155], v[186:189], v[120:123]
	v_mfma_f32_16x16x32_bf16 v[108:111], v[144:147], v[194:197], v[108:111]
	v_mfma_f32_16x16x32_bf16 v[104:107], v[152:155], v[194:197], v[104:107]
	v_mfma_f32_16x16x32_bf16 v[92:95], v[144:147], v[202:205], v[92:95]
	v_mfma_f32_16x16x32_bf16 v[88:91], v[152:155], v[202:205], v[88:91]
	v_mfma_f32_16x16x32_bf16 v[76:79], v[144:147], v[214:217], v[76:79]
	v_mfma_f32_16x16x32_bf16 v[72:75], v[152:155], v[214:217], v[72:75]
	v_mfma_f32_16x16x32_bf16 v[124:127], v[148:151], v[190:193], v[124:127]
	v_mfma_f32_16x16x32_bf16 v[120:123], v[156:159], v[190:193], v[120:123]
	v_mfma_f32_16x16x32_bf16 v[108:111], v[148:151], v[198:201], v[108:111]
	v_mfma_f32_16x16x32_bf16 v[104:107], v[156:159], v[198:201], v[104:107]
	v_mfma_f32_16x16x32_bf16 v[92:95], v[148:151], v[210:213], v[92:95]
	v_mfma_f32_16x16x32_bf16 v[88:91], v[156:159], v[210:213], v[88:91]
	v_mfma_f32_16x16x32_bf16 v[76:79], v[148:151], v[218:221], v[76:79]
	v_mfma_f32_16x16x32_bf16 v[72:75], v[156:159], v[218:221], v[72:75]
	v_mfma_f32_16x16x32_bf16 v[116:119], v[160:163], v[186:189], v[116:119]
	v_mfma_f32_16x16x32_bf16 v[112:115], v[168:171], v[186:189], v[112:115]
	v_mfma_f32_16x16x32_bf16 v[100:103], v[160:163], v[194:197], v[100:103]
	v_mfma_f32_16x16x32_bf16 v[96:99], v[168:171], v[194:197], v[96:99]
	v_mfma_f32_16x16x32_bf16 v[84:87], v[160:163], v[202:205], v[84:87]
	v_mfma_f32_16x16x32_bf16 v[80:83], v[168:171], v[202:205], v[80:83]
	v_mfma_f32_16x16x32_bf16 v[68:71], v[160:163], v[214:217], v[68:71]
	v_mfma_f32_16x16x32_bf16 v[64:67], v[168:171], v[214:217], v[64:67]
	v_mfma_f32_16x16x32_bf16 v[116:119], v[164:167], v[190:193], v[116:119]
	v_mfma_f32_16x16x32_bf16 v[112:115], v[182:185], v[190:193], v[112:115]
	v_mfma_f32_16x16x32_bf16 v[100:103], v[164:167], v[198:201], v[100:103]
	v_mfma_f32_16x16x32_bf16 v[96:99], v[182:185], v[198:201], v[96:99]
	v_mfma_f32_16x16x32_bf16 v[84:87], v[164:167], v[210:213], v[84:87]
	v_mfma_f32_16x16x32_bf16 v[80:83], v[182:185], v[210:213], v[80:83]
	v_mfma_f32_16x16x32_bf16 v[68:71], v[164:167], v[218:221], v[68:71]
	v_mfma_f32_16x16x32_bf16 v[64:67], v[182:185], v[218:221], v[64:67]
	s_setprio 0
	s_barrier
	s_add_u32 s98, s46, s16
	s_addc_u32 s99, s47, s17
	s_add_u32 s100, s48, s16
	s_addc_u32 s101, s49, s17
	s_add_i32 s64, s35, s23
	s_mov_b32 m0, s64
	ds_read_b128 v[186:189], v180 offset:16384
	ds_read_b128 v[190:193], v180 offset:17408
	ds_read_b128 v[194:197], v180 offset:18432
	ds_read_b128 v[198:201], v180 offset:19456
	ds_read_b128 v[202:205], v180 offset:20480
	ds_read_b128 v[210:213], v180 offset:21504
	ds_read_b128 v[214:217], v180 offset:22528
	ds_read_b128 v[218:221], v180 offset:23552
	global_load_lds_dwordx4 v130, s[46:47]
	s_add_i32 m0, s64, 0x2000
	s_add_u32 s64, s46, 0x40000
	s_addc_u32 s65, s47, 0
	s_add_i32 s66, s59, s23
	global_load_lds_dwordx4 v134, s[46:47]
	s_mov_b32 m0, s66
	s_nop 0
	global_load_lds_dwordx4 v130, s[64:65]
	s_add_i32 m0, s66, 0x2000
	s_nop 0
	global_load_lds_dwordx4 v134, s[64:65]
	s_mov_b32 m0, s31
	s_nop 0
	global_load_lds_dwordx4 v128, s[48:49]
	s_mov_b32 m0, s50
	s_nop 0
	global_load_lds_dwordx4 v132, s[48:49]
	s_waitcnt vmcnt(8)
	s_waitcnt lgkmcnt(0)
	s_barrier
	s_setprio 1
	s_waitcnt lgkmcnt(0)
	v_mfma_f32_16x16x32_bf16 v[60:63], v[144:147], v[186:189], v[60:63]
	v_mfma_f32_16x16x32_bf16 v[56:59], v[152:155], v[186:189], v[56:59]
	v_mfma_f32_16x16x32_bf16 v[44:47], v[144:147], v[194:197], v[44:47]
	v_mfma_f32_16x16x32_bf16 v[40:43], v[152:155], v[194:197], v[40:43]
	v_mfma_f32_16x16x32_bf16 v[28:31], v[144:147], v[202:205], v[28:31]
	v_mfma_f32_16x16x32_bf16 v[24:27], v[152:155], v[202:205], v[24:27]
	v_mfma_f32_16x16x32_bf16 v[12:15], v[144:147], v[214:217], v[12:15]
	v_mfma_f32_16x16x32_bf16 v[8:11], v[152:155], v[214:217], v[8:11]
	v_mfma_f32_16x16x32_bf16 v[60:63], v[148:151], v[190:193], v[60:63]
	v_mfma_f32_16x16x32_bf16 v[56:59], v[156:159], v[190:193], v[56:59]
	v_mfma_f32_16x16x32_bf16 v[44:47], v[148:151], v[198:201], v[44:47]
	v_mfma_f32_16x16x32_bf16 v[40:43], v[156:159], v[198:201], v[40:43]
	v_mfma_f32_16x16x32_bf16 v[28:31], v[148:151], v[210:213], v[28:31]
	v_mfma_f32_16x16x32_bf16 v[24:27], v[156:159], v[210:213], v[24:27]
	v_mfma_f32_16x16x32_bf16 v[12:15], v[148:151], v[218:221], v[12:15]
	v_mfma_f32_16x16x32_bf16 v[8:11], v[156:159], v[218:221], v[8:11]
	v_mfma_f32_16x16x32_bf16 v[52:55], v[160:163], v[186:189], v[52:55]
	v_mfma_f32_16x16x32_bf16 v[48:51], v[168:171], v[186:189], v[48:51]
	v_mfma_f32_16x16x32_bf16 v[36:39], v[160:163], v[194:197], v[36:39]
	v_mfma_f32_16x16x32_bf16 v[32:35], v[168:171], v[194:197], v[32:35]
	v_mfma_f32_16x16x32_bf16 v[20:23], v[160:163], v[202:205], v[20:23]
	v_mfma_f32_16x16x32_bf16 v[16:19], v[168:171], v[202:205], v[16:19]
	v_mfma_f32_16x16x32_bf16 v[4:7], v[160:163], v[214:217], v[4:7]
	v_mfma_f32_16x16x32_bf16 v[0:3], v[168:171], v[214:217], v[0:3]
	v_mfma_f32_16x16x32_bf16 v[52:55], v[164:167], v[190:193], v[52:55]
	v_mfma_f32_16x16x32_bf16 v[48:51], v[182:185], v[190:193], v[48:51]
	v_mfma_f32_16x16x32_bf16 v[36:39], v[164:167], v[198:201], v[36:39]
	v_mfma_f32_16x16x32_bf16 v[32:35], v[182:185], v[198:201], v[32:35]
	v_mfma_f32_16x16x32_bf16 v[20:23], v[164:167], v[210:213], v[20:23]
	v_mfma_f32_16x16x32_bf16 v[16:19], v[182:185], v[210:213], v[16:19]
	v_mfma_f32_16x16x32_bf16 v[4:7], v[164:167], v[218:221], v[4:7]
	v_mfma_f32_16x16x32_bf16 v[0:3], v[182:185], v[218:221], v[0:3]
	s_setprio 0
	s_barrier
	s_add_i32 s64, 0, 0x18000
	s_add_i32 s65, 0, 0x1c000
	ds_read_b128 v[144:147], v248
	ds_read_b128 v[148:151], v248 offset:1024
	ds_read_b128 v[152:155], v248 offset:2048
	ds_read_b128 v[156:159], v248 offset:3072
	ds_read_b128 v[160:163], v249
	ds_read_b128 v[164:167], v249 offset:1024
	ds_read_b128 v[168:171], v249 offset:2048
	ds_read_b128 v[182:185], v249 offset:3072
	s_add_u32 s48, s48, 0x40000
	s_addc_u32 s49, s49, 0
	s_mov_b32 m0, s51
	ds_read_b128 v[186:189], v180 offset:32768
	ds_read_b128 v[190:193], v180 offset:33792
	ds_read_b128 v[194:197], v180 offset:34816
	ds_read_b128 v[198:201], v180 offset:35840
	ds_read_b128 v[202:205], v180 offset:36864
	ds_read_b128 v[210:213], v180 offset:37888
	ds_read_b128 v[214:217], v180 offset:38912
	ds_read_b128 v[218:221], v180 offset:39936
	global_load_lds_dwordx4 v128, s[48:49]
	s_mov_b32 m0, s52
	s_nop 0
	global_load_lds_dwordx4 v132, s[48:49]
	s_waitcnt vmcnt(8)
	s_waitcnt lgkmcnt(0)
	s_barrier
	s_setprio 1
	s_waitcnt lgkmcnt(0)
	v_mfma_f32_16x16x32_bf16 v[124:127], v[144:147], v[186:189], v[124:127]
	v_mfma_f32_16x16x32_bf16 v[120:123], v[152:155], v[186:189], v[120:123]
	v_mfma_f32_16x16x32_bf16 v[108:111], v[144:147], v[194:197], v[108:111]
	v_mfma_f32_16x16x32_bf16 v[104:107], v[152:155], v[194:197], v[104:107]
	v_mfma_f32_16x16x32_bf16 v[92:95], v[144:147], v[202:205], v[92:95]
	v_mfma_f32_16x16x32_bf16 v[88:91], v[152:155], v[202:205], v[88:91]
	v_mfma_f32_16x16x32_bf16 v[76:79], v[144:147], v[214:217], v[76:79]
	v_mfma_f32_16x16x32_bf16 v[72:75], v[152:155], v[214:217], v[72:75]
	v_mfma_f32_16x16x32_bf16 v[124:127], v[148:151], v[190:193], v[124:127]
	v_mfma_f32_16x16x32_bf16 v[120:123], v[156:159], v[190:193], v[120:123]
	v_mfma_f32_16x16x32_bf16 v[108:111], v[148:151], v[198:201], v[108:111]
	v_mfma_f32_16x16x32_bf16 v[104:107], v[156:159], v[198:201], v[104:107]
	v_mfma_f32_16x16x32_bf16 v[92:95], v[148:151], v[210:213], v[92:95]
	v_mfma_f32_16x16x32_bf16 v[88:91], v[156:159], v[210:213], v[88:91]
	v_mfma_f32_16x16x32_bf16 v[76:79], v[148:151], v[218:221], v[76:79]
	v_mfma_f32_16x16x32_bf16 v[72:75], v[156:159], v[218:221], v[72:75]
	v_mfma_f32_16x16x32_bf16 v[116:119], v[160:163], v[186:189], v[116:119]
	v_mfma_f32_16x16x32_bf16 v[112:115], v[168:171], v[186:189], v[112:115]
	v_mfma_f32_16x16x32_bf16 v[100:103], v[160:163], v[194:197], v[100:103]
	v_mfma_f32_16x16x32_bf16 v[96:99], v[168:171], v[194:197], v[96:99]
	v_mfma_f32_16x16x32_bf16 v[84:87], v[160:163], v[202:205], v[84:87]
	v_mfma_f32_16x16x32_bf16 v[80:83], v[168:171], v[202:205], v[80:83]
	v_mfma_f32_16x16x32_bf16 v[68:71], v[160:163], v[214:217], v[68:71]
	v_mfma_f32_16x16x32_bf16 v[64:67], v[168:171], v[214:217], v[64:67]
	v_mfma_f32_16x16x32_bf16 v[116:119], v[164:167], v[190:193], v[116:119]
	v_mfma_f32_16x16x32_bf16 v[112:115], v[182:185], v[190:193], v[112:115]
	v_mfma_f32_16x16x32_bf16 v[100:103], v[164:167], v[198:201], v[100:103]
	v_mfma_f32_16x16x32_bf16 v[96:99], v[182:185], v[198:201], v[96:99]
	v_mfma_f32_16x16x32_bf16 v[84:87], v[164:167], v[210:213], v[84:87]
	v_mfma_f32_16x16x32_bf16 v[80:83], v[182:185], v[210:213], v[80:83]
	v_mfma_f32_16x16x32_bf16 v[68:71], v[164:167], v[218:221], v[68:71]
	v_mfma_f32_16x16x32_bf16 v[64:67], v[182:185], v[218:221], v[64:67]
	s_setprio 0
	s_barrier
	s_add_i32 s48, s64, s23
	s_mov_b32 m0, s48
	ds_read_b128 v[186:189], v180 offset:49152
	ds_read_b128 v[190:193], v180 offset:50176
	ds_read_b128 v[194:197], v180 offset:51200
	ds_read_b128 v[198:201], v180 offset:52224
	ds_read_b128 v[202:205], v180 offset:53248
	ds_read_b128 v[210:213], v180 offset:54272
	ds_read_b128 v[214:217], v180 offset:55296
	ds_read_b128 v[218:221], v180 offset:56320
	global_load_lds_dwordx4 v130, s[98:99]
	s_add_i32 m0, s48, 0x2000
	s_add_u32 s46, s46, 0x40080
	s_addc_u32 s47, s47, 0
	s_add_i32 s48, s65, s23
	global_load_lds_dwordx4 v134, s[98:99]
	s_mov_b32 m0, s48
	s_nop 0
	global_load_lds_dwordx4 v130, s[46:47]
	s_add_i32 m0, s48, 0x2000
	s_nop 0
	global_load_lds_dwordx4 v134, s[46:47]
	s_mov_b32 m0, s54
	s_nop 0
	global_load_lds_dwordx4 v128, s[100:101]
	s_mov_b32 m0, s55
	s_nop 0
	global_load_lds_dwordx4 v132, s[100:101]
	s_waitcnt vmcnt(8)
	s_waitcnt lgkmcnt(0)
	s_barrier
	s_setprio 1
	s_waitcnt lgkmcnt(0)
	v_mfma_f32_16x16x32_bf16 v[60:63], v[144:147], v[186:189], v[60:63]
	v_mfma_f32_16x16x32_bf16 v[56:59], v[152:155], v[186:189], v[56:59]
	v_mfma_f32_16x16x32_bf16 v[44:47], v[144:147], v[194:197], v[44:47]
	v_mfma_f32_16x16x32_bf16 v[40:43], v[152:155], v[194:197], v[40:43]
	v_mfma_f32_16x16x32_bf16 v[28:31], v[144:147], v[202:205], v[28:31]
	v_mfma_f32_16x16x32_bf16 v[24:27], v[152:155], v[202:205], v[24:27]
	v_mfma_f32_16x16x32_bf16 v[12:15], v[144:147], v[214:217], v[12:15]
	v_mfma_f32_16x16x32_bf16 v[8:11], v[152:155], v[214:217], v[8:11]
	v_mfma_f32_16x16x32_bf16 v[60:63], v[148:151], v[190:193], v[60:63]
	v_mfma_f32_16x16x32_bf16 v[56:59], v[156:159], v[190:193], v[56:59]
	v_mfma_f32_16x16x32_bf16 v[44:47], v[148:151], v[198:201], v[44:47]
	v_mfma_f32_16x16x32_bf16 v[40:43], v[156:159], v[198:201], v[40:43]
	v_mfma_f32_16x16x32_bf16 v[28:31], v[148:151], v[210:213], v[28:31]
	v_mfma_f32_16x16x32_bf16 v[24:27], v[156:159], v[210:213], v[24:27]
	v_mfma_f32_16x16x32_bf16 v[12:15], v[148:151], v[218:221], v[12:15]
	v_mfma_f32_16x16x32_bf16 v[8:11], v[156:159], v[218:221], v[8:11]
	v_mfma_f32_16x16x32_bf16 v[52:55], v[160:163], v[186:189], v[52:55]
	v_mfma_f32_16x16x32_bf16 v[48:51], v[168:171], v[186:189], v[48:51]
	v_mfma_f32_16x16x32_bf16 v[36:39], v[160:163], v[194:197], v[36:39]
	v_mfma_f32_16x16x32_bf16 v[32:35], v[168:171], v[194:197], v[32:35]
	v_mfma_f32_16x16x32_bf16 v[20:23], v[160:163], v[202:205], v[20:23]
	v_mfma_f32_16x16x32_bf16 v[16:19], v[168:171], v[202:205], v[16:19]
	v_mfma_f32_16x16x32_bf16 v[4:7], v[160:163], v[214:217], v[4:7]
	v_mfma_f32_16x16x32_bf16 v[0:3], v[168:171], v[214:217], v[0:3]
	v_mfma_f32_16x16x32_bf16 v[52:55], v[164:167], v[190:193], v[52:55]
	v_mfma_f32_16x16x32_bf16 v[48:51], v[182:185], v[190:193], v[48:51]
	v_mfma_f32_16x16x32_bf16 v[36:39], v[164:167], v[198:201], v[36:39]
	v_mfma_f32_16x16x32_bf16 v[32:35], v[182:185], v[198:201], v[32:35]
	v_mfma_f32_16x16x32_bf16 v[20:23], v[164:167], v[210:213], v[20:23]
	v_mfma_f32_16x16x32_bf16 v[16:19], v[182:185], v[210:213], v[16:19]
	v_mfma_f32_16x16x32_bf16 v[4:7], v[164:167], v[218:221], v[4:7]
	v_mfma_f32_16x16x32_bf16 v[0:3], v[182:185], v[218:221], v[0:3]
	s_setprio 0
	s_barrier
	s_add_i32 s63, s63, 2
	s_add_u32 s44, s44, 0x100
	s_addc_u32 s45, s45, 0
	s_add_u32 s61, s61, 0x100
	s_addc_u32 s62, s62, 0
	s_cmp_gt_u32 s63, 13
	s_cbranch_scc0 .LBB0_245

.LBB0_491:
	s_ashr_i32 s37, s36, 31
	s_lshl_b64 s[38:39], s[36:37], 19
	s_add_u32 s38, s2, s38
	s_addc_u32 s39, s31, s39
	s_and_b64 s[40:41], s[8:9], exec
	s_cselect_b32 s37, s39, s47
	s_cselect_b32 s43, s38, s46
	s_ashr_i32 s25, s24, 31
	s_lshl_b64 s[40:41], s[24:25], 19
	s_add_u32 s40, s34, s40
	s_addc_u32 s41, s35, s41
	s_and_b64 s[50:51], s[8:9], exec
	s_cselect_b32 s25, s41, s49
	s_cselect_b32 s63, s40, s48
	s_add_u32 s46, s46, 0x40080
	s_addc_u32 s47, s47, 0
	s_add_u32 s64, s48, 0x100
	s_addc_u32 s65, s49, 0
	s_mov_b32 s66, -2
	s_waitcnt lgkmcnt(0)
	ds_read_b128 v[128:131], v179
	ds_read_b128 v[132:135], v179 offset:1024
	ds_read_b128 v[136:139], v179 offset:2048
	ds_read_b128 v[140:143], v179 offset:3072
	ds_read_b128 v[144:147], v187
	ds_read_b128 v[148:151], v187 offset:1024
	ds_read_b128 v[180:183], v187 offset:2048
	ds_read_b128 v[188:191], v187 offset:3072
	s_add_u32 s48, s46, 0xfffc0080
	s_addc_u32 s49, s47, -1
	s_cmp_eq_u32 s66, 12
	s_cselect_b32 s51, s37, s49
	s_cselect_b32 s50, s43, s48
	s_cselect_b32 s49, s25, s65
	s_cselect_b32 s48, s63, s64
	s_add_i32 m0, s45, 0xc000
	ds_read_b128 v[196:199], v195
	ds_read_b128 v[202:205], v195 offset:1024
	ds_read_b128 v[210:213], v195 offset:2048
	ds_read_b128 v[214:217], v195 offset:3072
	ds_read_b128 v[218:221], v195 offset:4096
	ds_read_b128 v[222:225], v195 offset:5120
	ds_read_b128 v[226:229], v195 offset:6144
	ds_read_b128 v[230:233], v195 offset:7168
	global_load_lds_dwordx4 v160, s[46:47]
	s_add_i32 m0, s45, 0xe000
	s_nop 0
	global_load_lds_dwordx4 v162, s[46:47]
	s_waitcnt vmcnt(8)
	s_waitcnt lgkmcnt(0)
	s_barrier
	s_setprio 1
	s_waitcnt lgkmcnt(0)
	v_mfma_f32_16x16x32_bf16 v[124:127], v[128:131], v[196:199], 0
	v_mfma_f32_16x16x32_bf16 v[120:123], v[136:139], v[196:199], 0
	v_mfma_f32_16x16x32_bf16 v[108:111], v[128:131], v[210:213], 0
	v_mfma_f32_16x16x32_bf16 v[104:107], v[136:139], v[210:213], 0
	v_mfma_f32_16x16x32_bf16 v[92:95], v[128:131], v[218:221], 0
	v_mfma_f32_16x16x32_bf16 v[88:91], v[136:139], v[218:221], 0
	v_mfma_f32_16x16x32_bf16 v[76:79], v[128:131], v[226:229], 0
	v_mfma_f32_16x16x32_bf16 v[72:75], v[136:139], v[226:229], 0
	v_mfma_f32_16x16x32_bf16 v[124:127], v[132:135], v[202:205], v[124:127]
	v_mfma_f32_16x16x32_bf16 v[120:123], v[140:143], v[202:205], v[120:123]
	v_mfma_f32_16x16x32_bf16 v[108:111], v[132:135], v[214:217], v[108:111]
	v_mfma_f32_16x16x32_bf16 v[104:107], v[140:143], v[214:217], v[104:107]
	v_mfma_f32_16x16x32_bf16 v[92:95], v[132:135], v[222:225], v[92:95]
	v_mfma_f32_16x16x32_bf16 v[88:91], v[140:143], v[222:225], v[88:91]
	v_mfma_f32_16x16x32_bf16 v[76:79], v[132:135], v[230:233], v[76:79]
	v_mfma_f32_16x16x32_bf16 v[72:75], v[140:143], v[230:233], v[72:75]
	v_mfma_f32_16x16x32_bf16 v[116:119], v[144:147], v[196:199], 0
	v_mfma_f32_16x16x32_bf16 v[112:115], v[180:183], v[196:199], 0
	v_mfma_f32_16x16x32_bf16 v[100:103], v[144:147], v[210:213], 0
	v_mfma_f32_16x16x32_bf16 v[96:99], v[180:183], v[210:213], 0
	v_mfma_f32_16x16x32_bf16 v[84:87], v[144:147], v[218:221], 0
	v_mfma_f32_16x16x32_bf16 v[80:83], v[180:183], v[218:221], 0
	v_mfma_f32_16x16x32_bf16 v[68:71], v[144:147], v[226:229], 0
	v_mfma_f32_16x16x32_bf16 v[64:67], v[180:183], v[226:229], 0
	v_mfma_f32_16x16x32_bf16 v[116:119], v[148:151], v[202:205], v[116:119]
	v_mfma_f32_16x16x32_bf16 v[112:115], v[188:191], v[202:205], v[112:115]
	v_mfma_f32_16x16x32_bf16 v[100:103], v[148:151], v[214:217], v[100:103]
	v_mfma_f32_16x16x32_bf16 v[96:99], v[188:191], v[214:217], v[96:99]
	v_mfma_f32_16x16x32_bf16 v[84:87], v[148:151], v[222:225], v[84:87]
	v_mfma_f32_16x16x32_bf16 v[80:83], v[188:191], v[222:225], v[80:83]
	v_mfma_f32_16x16x32_bf16 v[68:71], v[148:151], v[230:233], v[68:71]
	v_mfma_f32_16x16x32_bf16 v[64:67], v[188:191], v[230:233], v[64:67]
	s_setprio 0
	s_barrier
	s_add_u32 s98, s48, s20
	s_addc_u32 s99, s49, s21
	s_add_u32 s100, s50, s20
	s_addc_u32 s101, s51, s21
	s_add_i32 s67, s61, s52
	s_mov_b32 m0, s67
	ds_read_b128 v[196:199], v195 offset:16384
	ds_read_b128 v[202:205], v195 offset:17408
	ds_read_b128 v[210:213], v195 offset:18432
	ds_read_b128 v[214:217], v195 offset:19456
	ds_read_b128 v[218:221], v195 offset:20480
	ds_read_b128 v[222:225], v195 offset:21504
	ds_read_b128 v[226:229], v195 offset:22528
	ds_read_b128 v[230:233], v195 offset:23552
	global_load_lds_dwordx4 v154, s[48:49]
	s_add_i32 m0, s67, 0x2000
	s_add_u32 s68, s48, 0x40000
	s_addc_u32 s69, s49, 0
	s_add_i32 s67, s62, s52
	global_load_lds_dwordx4 v158, s[48:49]
	s_mov_b32 m0, s67
	s_nop 0
	global_load_lds_dwordx4 v154, s[68:69]
	s_add_i32 m0, s67, 0x2000
	s_nop 0
	global_load_lds_dwordx4 v158, s[68:69]
	s_mov_b32 m0, s45
	s_nop 0
	global_load_lds_dwordx4 v152, s[50:51]
	s_mov_b32 m0, s53
	s_nop 0
	global_load_lds_dwordx4 v156, s[50:51]
	s_waitcnt vmcnt(8)
	s_waitcnt lgkmcnt(0)
	s_barrier
	s_setprio 1
	s_waitcnt lgkmcnt(0)
	v_mfma_f32_16x16x32_bf16 v[60:63], v[128:131], v[196:199], 0
	v_mfma_f32_16x16x32_bf16 v[56:59], v[136:139], v[196:199], 0
	v_mfma_f32_16x16x32_bf16 v[44:47], v[128:131], v[210:213], 0
	v_mfma_f32_16x16x32_bf16 v[40:43], v[136:139], v[210:213], 0
	v_mfma_f32_16x16x32_bf16 v[28:31], v[128:131], v[218:221], 0
	v_mfma_f32_16x16x32_bf16 v[24:27], v[136:139], v[218:221], 0
	v_mfma_f32_16x16x32_bf16 v[12:15], v[128:131], v[226:229], 0
	v_mfma_f32_16x16x32_bf16 v[8:11], v[136:139], v[226:229], 0
	v_mfma_f32_16x16x32_bf16 v[60:63], v[132:135], v[202:205], v[60:63]
	v_mfma_f32_16x16x32_bf16 v[56:59], v[140:143], v[202:205], v[56:59]
	v_mfma_f32_16x16x32_bf16 v[44:47], v[132:135], v[214:217], v[44:47]
	v_mfma_f32_16x16x32_bf16 v[40:43], v[140:143], v[214:217], v[40:43]
	v_mfma_f32_16x16x32_bf16 v[28:31], v[132:135], v[222:225], v[28:31]
	v_mfma_f32_16x16x32_bf16 v[24:27], v[140:143], v[222:225], v[24:27]
	v_mfma_f32_16x16x32_bf16 v[12:15], v[132:135], v[230:233], v[12:15]
	v_mfma_f32_16x16x32_bf16 v[8:11], v[140:143], v[230:233], v[8:11]
	v_mfma_f32_16x16x32_bf16 v[52:55], v[144:147], v[196:199], 0
	v_mfma_f32_16x16x32_bf16 v[48:51], v[180:183], v[196:199], 0
	v_mfma_f32_16x16x32_bf16 v[36:39], v[144:147], v[210:213], 0
	v_mfma_f32_16x16x32_bf16 v[32:35], v[180:183], v[210:213], 0
	v_mfma_f32_16x16x32_bf16 v[20:23], v[144:147], v[218:221], 0
	v_mfma_f32_16x16x32_bf16 v[16:19], v[180:183], v[218:221], 0
	v_mfma_f32_16x16x32_bf16 v[4:7], v[144:147], v[226:229], 0
	v_mfma_f32_16x16x32_bf16 v[0:3], v[180:183], v[226:229], 0
	v_mfma_f32_16x16x32_bf16 v[52:55], v[148:151], v[202:205], v[52:55]
	v_mfma_f32_16x16x32_bf16 v[48:51], v[188:191], v[202:205], v[48:51]
	v_mfma_f32_16x16x32_bf16 v[36:39], v[148:151], v[214:217], v[36:39]
	v_mfma_f32_16x16x32_bf16 v[32:35], v[188:191], v[214:217], v[32:35]
	v_mfma_f32_16x16x32_bf16 v[20:23], v[148:151], v[222:225], v[20:23]
	v_mfma_f32_16x16x32_bf16 v[16:19], v[188:191], v[222:225], v[16:19]
	v_mfma_f32_16x16x32_bf16 v[4:7], v[148:151], v[230:233], v[4:7]
	v_mfma_f32_16x16x32_bf16 v[0:3], v[188:191], v[230:233], v[0:3]
	s_setprio 0
	s_barrier
	s_add_i32 s67, 0, 0x18000
	s_add_i32 s68, 0, 0x1c000
	v_add_u32_e32 v140, s67, v173
	v_add_u32_e32 v170, s68, v173
	ds_read_b128 v[128:131], v140
	ds_read_b128 v[132:135], v140 offset:1024
	ds_read_b128 v[136:139], v140 offset:2048
	ds_read_b128 v[140:143], v140 offset:3072
	ds_read_b128 v[144:147], v170
	ds_read_b128 v[148:151], v170 offset:1024
	ds_read_b128 v[180:183], v170 offset:2048
	ds_read_b128 v[188:191], v170 offset:3072
	s_add_u32 s50, s50, 0x40000
	s_addc_u32 s51, s51, 0
	s_mov_b32 m0, s54
	ds_read_b128 v[196:199], v195 offset:32768
	ds_read_b128 v[202:205], v195 offset:33792
	ds_read_b128 v[210:213], v195 offset:34816
	ds_read_b128 v[214:217], v195 offset:35840
	ds_read_b128 v[218:221], v195 offset:36864
	ds_read_b128 v[222:225], v195 offset:37888
	ds_read_b128 v[226:229], v195 offset:38912
	ds_read_b128 v[230:233], v195 offset:39936
	global_load_lds_dwordx4 v152, s[50:51]
	s_mov_b32 m0, s55
	s_nop 0
	global_load_lds_dwordx4 v156, s[50:51]
	s_waitcnt vmcnt(8)
	s_waitcnt lgkmcnt(0)
	s_barrier
	s_setprio 1
	s_waitcnt lgkmcnt(0)
	v_mfma_f32_16x16x32_bf16 v[124:127], v[128:131], v[196:199], v[124:127]
	v_mfma_f32_16x16x32_bf16 v[120:123], v[136:139], v[196:199], v[120:123]
	v_mfma_f32_16x16x32_bf16 v[108:111], v[128:131], v[210:213], v[108:111]
	v_mfma_f32_16x16x32_bf16 v[104:107], v[136:139], v[210:213], v[104:107]
	v_mfma_f32_16x16x32_bf16 v[92:95], v[128:131], v[218:221], v[92:95]
	v_mfma_f32_16x16x32_bf16 v[88:91], v[136:139], v[218:221], v[88:91]
	v_mfma_f32_16x16x32_bf16 v[76:79], v[128:131], v[226:229], v[76:79]
	v_mfma_f32_16x16x32_bf16 v[72:75], v[136:139], v[226:229], v[72:75]
	v_mfma_f32_16x16x32_bf16 v[124:127], v[132:135], v[202:205], v[124:127]
	v_mfma_f32_16x16x32_bf16 v[120:123], v[140:143], v[202:205], v[120:123]
	v_mfma_f32_16x16x32_bf16 v[108:111], v[132:135], v[214:217], v[108:111]
	v_mfma_f32_16x16x32_bf16 v[104:107], v[140:143], v[214:217], v[104:107]
	v_mfma_f32_16x16x32_bf16 v[92:95], v[132:135], v[222:225], v[92:95]
	v_mfma_f32_16x16x32_bf16 v[88:91], v[140:143], v[222:225], v[88:91]
	v_mfma_f32_16x16x32_bf16 v[76:79], v[132:135], v[230:233], v[76:79]
	v_mfma_f32_16x16x32_bf16 v[72:75], v[140:143], v[230:233], v[72:75]
	v_mfma_f32_16x16x32_bf16 v[116:119], v[144:147], v[196:199], v[116:119]
	v_mfma_f32_16x16x32_bf16 v[112:115], v[180:183], v[196:199], v[112:115]
	v_mfma_f32_16x16x32_bf16 v[100:103], v[144:147], v[210:213], v[100:103]
	v_mfma_f32_16x16x32_bf16 v[96:99], v[180:183], v[210:213], v[96:99]
	v_mfma_f32_16x16x32_bf16 v[84:87], v[144:147], v[218:221], v[84:87]
	v_mfma_f32_16x16x32_bf16 v[80:83], v[180:183], v[218:221], v[80:83]
	v_mfma_f32_16x16x32_bf16 v[68:71], v[144:147], v[226:229], v[68:71]
	v_mfma_f32_16x16x32_bf16 v[64:67], v[180:183], v[226:229], v[64:67]
	v_mfma_f32_16x16x32_bf16 v[116:119], v[148:151], v[202:205], v[116:119]
	v_mfma_f32_16x16x32_bf16 v[112:115], v[188:191], v[202:205], v[112:115]
	v_mfma_f32_16x16x32_bf16 v[100:103], v[148:151], v[214:217], v[100:103]
	v_mfma_f32_16x16x32_bf16 v[96:99], v[188:191], v[214:217], v[96:99]
	v_mfma_f32_16x16x32_bf16 v[84:87], v[148:151], v[222:225], v[84:87]
	v_mfma_f32_16x16x32_bf16 v[80:83], v[188:191], v[222:225], v[80:83]
	v_mfma_f32_16x16x32_bf16 v[68:71], v[148:151], v[230:233], v[68:71]
	v_mfma_f32_16x16x32_bf16 v[64:67], v[188:191], v[230:233], v[64:67]
	s_setprio 0
	s_barrier
	s_add_i32 s50, s67, s52
	s_mov_b32 m0, s50
	ds_read_b128 v[196:199], v195 offset:49152
	ds_read_b128 v[202:205], v195 offset:50176
	ds_read_b128 v[210:213], v195 offset:51200
	ds_read_b128 v[214:217], v195 offset:52224
	ds_read_b128 v[218:221], v195 offset:53248
	ds_read_b128 v[222:225], v195 offset:54272
	ds_read_b128 v[226:229], v195 offset:55296
	ds_read_b128 v[230:233], v195 offset:56320
	global_load_lds_dwordx4 v154, s[98:99]
	s_add_i32 m0, s50, 0x2000
	s_add_u32 s48, s48, 0x40080
	s_addc_u32 s49, s49, 0
	s_add_i32 s50, s68, s52
	global_load_lds_dwordx4 v158, s[98:99]
	s_mov_b32 m0, s50
	s_nop 0
	global_load_lds_dwordx4 v154, s[48:49]
	s_add_i32 m0, s50, 0x2000
	s_nop 0
	global_load_lds_dwordx4 v158, s[48:49]
	s_mov_b32 m0, s57
	s_nop 0
	global_load_lds_dwordx4 v152, s[100:101]
	s_mov_b32 m0, s58
	s_nop 0
	global_load_lds_dwordx4 v156, s[100:101]
	s_waitcnt vmcnt(8)
	s_waitcnt lgkmcnt(0)
	s_barrier
	s_setprio 1
	s_waitcnt lgkmcnt(0)
	v_mfma_f32_16x16x32_bf16 v[60:63], v[128:131], v[196:199], v[60:63]
	v_mfma_f32_16x16x32_bf16 v[56:59], v[136:139], v[196:199], v[56:59]
	v_mfma_f32_16x16x32_bf16 v[44:47], v[128:131], v[210:213], v[44:47]
	v_mfma_f32_16x16x32_bf16 v[40:43], v[136:139], v[210:213], v[40:43]
	v_mfma_f32_16x16x32_bf16 v[28:31], v[128:131], v[218:221], v[28:31]
	v_mfma_f32_16x16x32_bf16 v[24:27], v[136:139], v[218:221], v[24:27]
	v_mfma_f32_16x16x32_bf16 v[12:15], v[128:131], v[226:229], v[12:15]
	v_mfma_f32_16x16x32_bf16 v[8:11], v[136:139], v[226:229], v[8:11]
	v_mfma_f32_16x16x32_bf16 v[60:63], v[132:135], v[202:205], v[60:63]
	v_mfma_f32_16x16x32_bf16 v[56:59], v[140:143], v[202:205], v[56:59]
	v_mfma_f32_16x16x32_bf16 v[44:47], v[132:135], v[214:217], v[44:47]
	v_mfma_f32_16x16x32_bf16 v[40:43], v[140:143], v[214:217], v[40:43]
	v_mfma_f32_16x16x32_bf16 v[28:31], v[132:135], v[222:225], v[28:31]
	v_mfma_f32_16x16x32_bf16 v[24:27], v[140:143], v[222:225], v[24:27]
	v_mfma_f32_16x16x32_bf16 v[12:15], v[132:135], v[230:233], v[12:15]
	v_mfma_f32_16x16x32_bf16 v[8:11], v[140:143], v[230:233], v[8:11]
	v_mfma_f32_16x16x32_bf16 v[52:55], v[144:147], v[196:199], v[52:55]
	v_mfma_f32_16x16x32_bf16 v[48:51], v[180:183], v[196:199], v[48:51]
	v_mfma_f32_16x16x32_bf16 v[36:39], v[144:147], v[210:213], v[36:39]
	v_mfma_f32_16x16x32_bf16 v[32:35], v[180:183], v[210:213], v[32:35]
	v_mfma_f32_16x16x32_bf16 v[20:23], v[144:147], v[218:221], v[20:23]
	v_mfma_f32_16x16x32_bf16 v[16:19], v[180:183], v[218:221], v[16:19]
	v_mfma_f32_16x16x32_bf16 v[4:7], v[144:147], v[226:229], v[4:7]
	v_mfma_f32_16x16x32_bf16 v[0:3], v[180:183], v[226:229], v[0:3]
	v_mfma_f32_16x16x32_bf16 v[52:55], v[148:151], v[202:205], v[52:55]
	v_mfma_f32_16x16x32_bf16 v[48:51], v[188:191], v[202:205], v[48:51]
	v_mfma_f32_16x16x32_bf16 v[36:39], v[148:151], v[214:217], v[36:39]
	v_mfma_f32_16x16x32_bf16 v[32:35], v[188:191], v[214:217], v[32:35]
	v_mfma_f32_16x16x32_bf16 v[20:23], v[148:151], v[222:225], v[20:23]
	v_mfma_f32_16x16x32_bf16 v[16:19], v[188:191], v[222:225], v[16:19]
	v_mfma_f32_16x16x32_bf16 v[4:7], v[148:151], v[230:233], v[4:7]
	v_mfma_f32_16x16x32_bf16 v[0:3], v[188:191], v[230:233], v[0:3]
	s_setprio 0
	s_barrier
	s_add_i32 s66, s66, 2
	s_add_u32 s46, s46, 0x100
	s_addc_u32 s47, s47, 0
	s_add_u32 s64, s64, 0x100
	s_addc_u32 s65, s65, 0
	s_cmp_gt_u32 s66, 13
	s_cbranch_scc1 .Lkexit_1
	v_add_u32_e32 v248, 0x18000, v173
	v_add_u32_e32 v249, 0x1c000, v173
.LBB0_492:
	ds_read_b128 v[128:131], v179
	ds_read_b128 v[132:135], v179 offset:1024
	ds_read_b128 v[136:139], v179 offset:2048
	ds_read_b128 v[140:143], v179 offset:3072
	ds_read_b128 v[144:147], v187
	ds_read_b128 v[148:151], v187 offset:1024
	ds_read_b128 v[180:183], v187 offset:2048
	ds_read_b128 v[188:191], v187 offset:3072
	s_add_u32 s48, s46, 0xfffc0080
	s_addc_u32 s49, s47, -1
	s_cmp_eq_u32 s66, 12
	s_cselect_b32 s51, s37, s49
	s_cselect_b32 s50, s43, s48
	s_cselect_b32 s49, s25, s65
	s_cselect_b32 s48, s63, s64
	s_add_i32 m0, s45, 0xc000
	ds_read_b128 v[196:199], v195
	ds_read_b128 v[202:205], v195 offset:1024
	ds_read_b128 v[210:213], v195 offset:2048
	ds_read_b128 v[214:217], v195 offset:3072
	ds_read_b128 v[218:221], v195 offset:4096
	ds_read_b128 v[222:225], v195 offset:5120
	ds_read_b128 v[226:229], v195 offset:6144
	ds_read_b128 v[230:233], v195 offset:7168
	global_load_lds_dwordx4 v160, s[46:47]
	s_add_i32 m0, s45, 0xe000
	s_nop 0
	global_load_lds_dwordx4 v162, s[46:47]
	s_waitcnt vmcnt(8)
	s_waitcnt lgkmcnt(0)
	s_barrier
	s_setprio 1
	s_waitcnt lgkmcnt(0)
	v_mfma_f32_16x16x32_bf16 v[124:127], v[128:131], v[196:199], v[124:127]
	v_mfma_f32_16x16x32_bf16 v[120:123], v[136:139], v[196:199], v[120:123]
	v_mfma_f32_16x16x32_bf16 v[108:111], v[128:131], v[210:213], v[108:111]
	v_mfma_f32_16x16x32_bf16 v[104:107], v[136:139], v[210:213], v[104:107]
	v_mfma_f32_16x16x32_bf16 v[92:95], v[128:131], v[218:221], v[92:95]
	v_mfma_f32_16x16x32_bf16 v[88:91], v[136:139], v[218:221], v[88:91]
	v_mfma_f32_16x16x32_bf16 v[76:79], v[128:131], v[226:229], v[76:79]
	v_mfma_f32_16x16x32_bf16 v[72:75], v[136:139], v[226:229], v[72:75]
	v_mfma_f32_16x16x32_bf16 v[124:127], v[132:135], v[202:205], v[124:127]
	v_mfma_f32_16x16x32_bf16 v[120:123], v[140:143], v[202:205], v[120:123]
	v_mfma_f32_16x16x32_bf16 v[108:111], v[132:135], v[214:217], v[108:111]
	v_mfma_f32_16x16x32_bf16 v[104:107], v[140:143], v[214:217], v[104:107]
	v_mfma_f32_16x16x32_bf16 v[92:95], v[132:135], v[222:225], v[92:95]
	v_mfma_f32_16x16x32_bf16 v[88:91], v[140:143], v[222:225], v[88:91]
	v_mfma_f32_16x16x32_bf16 v[76:79], v[132:135], v[230:233], v[76:79]
	v_mfma_f32_16x16x32_bf16 v[72:75], v[140:143], v[230:233], v[72:75]
	v_mfma_f32_16x16x32_bf16 v[116:119], v[144:147], v[196:199], v[116:119]
	v_mfma_f32_16x16x32_bf16 v[112:115], v[180:183], v[196:199], v[112:115]
	v_mfma_f32_16x16x32_bf16 v[100:103], v[144:147], v[210:213], v[100:103]
	v_mfma_f32_16x16x32_bf16 v[96:99], v[180:183], v[210:213], v[96:99]
	v_mfma_f32_16x16x32_bf16 v[84:87], v[144:147], v[218:221], v[84:87]
	v_mfma_f32_16x16x32_bf16 v[80:83], v[180:183], v[218:221], v[80:83]
	v_mfma_f32_16x16x32_bf16 v[68:71], v[144:147], v[226:229], v[68:71]
	v_mfma_f32_16x16x32_bf16 v[64:67], v[180:183], v[226:229], v[64:67]
	v_mfma_f32_16x16x32_bf16 v[116:119], v[148:151], v[202:205], v[116:119]
	v_mfma_f32_16x16x32_bf16 v[112:115], v[188:191], v[202:205], v[112:115]
	v_mfma_f32_16x16x32_bf16 v[100:103], v[148:151], v[214:217], v[100:103]
	v_mfma_f32_16x16x32_bf16 v[96:99], v[188:191], v[214:217], v[96:99]
	v_mfma_f32_16x16x32_bf16 v[84:87], v[148:151], v[222:225], v[84:87]
	v_mfma_f32_16x16x32_bf16 v[80:83], v[188:191], v[222:225], v[80:83]
	v_mfma_f32_16x16x32_bf16 v[68:71], v[148:151], v[230:233], v[68:71]
	v_mfma_f32_16x16x32_bf16 v[64:67], v[188:191], v[230:233], v[64:67]
	s_setprio 0
	s_barrier
	s_add_u32 s98, s48, s20
	s_addc_u32 s99, s49, s21
	s_add_u32 s100, s50, s20
	s_addc_u32 s101, s51, s21
	s_add_i32 s67, s61, s52
	s_mov_b32 m0, s67
	ds_read_b128 v[196:199], v195 offset:16384
	ds_read_b128 v[202:205], v195 offset:17408
	ds_read_b128 v[210:213], v195 offset:18432
	ds_read_b128 v[214:217], v195 offset:19456
	ds_read_b128 v[218:221], v195 offset:20480
	ds_read_b128 v[222:225], v195 offset:21504
	ds_read_b128 v[226:229], v195 offset:22528
	ds_read_b128 v[230:233], v195 offset:23552
	global_load_lds_dwordx4 v154, s[48:49]
	s_add_i32 m0, s67, 0x2000
	s_add_u32 s68, s48, 0x40000
	s_addc_u32 s69, s49, 0
	s_add_i32 s67, s62, s52
	global_load_lds_dwordx4 v158, s[48:49]
	s_mov_b32 m0, s67
	s_nop 0
	global_load_lds_dwordx4 v154, s[68:69]
	s_add_i32 m0, s67, 0x2000
	s_nop 0
	global_load_lds_dwordx4 v158, s[68:69]
	s_mov_b32 m0, s45
	s_nop 0
	global_load_lds_dwordx4 v152, s[50:51]
	s_mov_b32 m0, s53
	s_nop 0
	global_load_lds_dwordx4 v156, s[50:51]
	s_waitcnt vmcnt(8)
	s_waitcnt lgkmcnt(0)
	s_barrier
	s_setprio 1
	s_waitcnt lgkmcnt(0)
	v_mfma_f32_16x16x32_bf16 v[60:63], v[128:131], v[196:199], v[60:63]
	v_mfma_f32_16x16x32_bf16 v[56:59], v[136:139], v[196:199], v[56:59]
	v_mfma_f32_16x16x32_bf16 v[44:47], v[128:131], v[210:213], v[44:47]
	v_mfma_f32_16x16x32_bf16 v[40:43], v[136:139], v[210:213], v[40:43]
	v_mfma_f32_16x16x32_bf16 v[28:31], v[128:131], v[218:221], v[28:31]
	v_mfma_f32_16x16x32_bf16 v[24:27], v[136:139], v[218:221], v[24:27]
	v_mfma_f32_16x16x32_bf16 v[12:15], v[128:131], v[226:229], v[12:15]
	v_mfma_f32_16x16x32_bf16 v[8:11], v[136:139], v[226:229], v[8:11]
	v_mfma_f32_16x16x32_bf16 v[60:63], v[132:135], v[202:205], v[60:63]
	v_mfma_f32_16x16x32_bf16 v[56:59], v[140:143], v[202:205], v[56:59]
	v_mfma_f32_16x16x32_bf16 v[44:47], v[132:135], v[214:217], v[44:47]
	v_mfma_f32_16x16x32_bf16 v[40:43], v[140:143], v[214:217], v[40:43]
	v_mfma_f32_16x16x32_bf16 v[28:31], v[132:135], v[222:225], v[28:31]
	v_mfma_f32_16x16x32_bf16 v[24:27], v[140:143], v[222:225], v[24:27]
	v_mfma_f32_16x16x32_bf16 v[12:15], v[132:135], v[230:233], v[12:15]
	v_mfma_f32_16x16x32_bf16 v[8:11], v[140:143], v[230:233], v[8:11]
	v_mfma_f32_16x16x32_bf16 v[52:55], v[144:147], v[196:199], v[52:55]
	v_mfma_f32_16x16x32_bf16 v[48:51], v[180:183], v[196:199], v[48:51]
	v_mfma_f32_16x16x32_bf16 v[36:39], v[144:147], v[210:213], v[36:39]
	v_mfma_f32_16x16x32_bf16 v[32:35], v[180:183], v[210:213], v[32:35]
	v_mfma_f32_16x16x32_bf16 v[20:23], v[144:147], v[218:221], v[20:23]
	v_mfma_f32_16x16x32_bf16 v[16:19], v[180:183], v[218:221], v[16:19]
	v_mfma_f32_16x16x32_bf16 v[4:7], v[144:147], v[226:229], v[4:7]
	v_mfma_f32_16x16x32_bf16 v[0:3], v[180:183], v[226:229], v[0:3]
	v_mfma_f32_16x16x32_bf16 v[52:55], v[148:151], v[202:205], v[52:55]
	v_mfma_f32_16x16x32_bf16 v[48:51], v[188:191], v[202:205], v[48:51]
	v_mfma_f32_16x16x32_bf16 v[36:39], v[148:151], v[214:217], v[36:39]
	v_mfma_f32_16x16x32_bf16 v[32:35], v[188:191], v[214:217], v[32:35]
	v_mfma_f32_16x16x32_bf16 v[20:23], v[148:151], v[222:225], v[20:23]
	v_mfma_f32_16x16x32_bf16 v[16:19], v[188:191], v[222:225], v[16:19]
	v_mfma_f32_16x16x32_bf16 v[4:7], v[148:151], v[230:233], v[4:7]
	v_mfma_f32_16x16x32_bf16 v[0:3], v[188:191], v[230:233], v[0:3]
	s_setprio 0
	s_barrier
	s_add_i32 s67, 0, 0x18000
	s_add_i32 s68, 0, 0x1c000
	ds_read_b128 v[128:131], v248
	ds_read_b128 v[132:135], v248 offset:1024
	ds_read_b128 v[136:139], v248 offset:2048
	ds_read_b128 v[140:143], v248 offset:3072
	ds_read_b128 v[144:147], v249
	ds_read_b128 v[148:151], v249 offset:1024
	ds_read_b128 v[180:183], v249 offset:2048
	ds_read_b128 v[188:191], v249 offset:3072
	s_add_u32 s50, s50, 0x40000
	s_addc_u32 s51, s51, 0
	s_mov_b32 m0, s54
	ds_read_b128 v[196:199], v195 offset:32768
	ds_read_b128 v[202:205], v195 offset:33792
	ds_read_b128 v[210:213], v195 offset:34816
	ds_read_b128 v[214:217], v195 offset:35840
	ds_read_b128 v[218:221], v195 offset:36864
	ds_read_b128 v[222:225], v195 offset:37888
	ds_read_b128 v[226:229], v195 offset:38912
	ds_read_b128 v[230:233], v195 offset:39936
	global_load_lds_dwordx4 v152, s[50:51]
	s_mov_b32 m0, s55
	s_nop 0
	global_load_lds_dwordx4 v156, s[50:51]
	s_waitcnt vmcnt(8)
	s_waitcnt lgkmcnt(0)
	s_barrier
	s_setprio 1
	s_waitcnt lgkmcnt(0)
	v_mfma_f32_16x16x32_bf16 v[124:127], v[128:131], v[196:199], v[124:127]
	v_mfma_f32_16x16x32_bf16 v[120:123], v[136:139], v[196:199], v[120:123]
	v_mfma_f32_16x16x32_bf16 v[108:111], v[128:131], v[210:213], v[108:111]
	v_mfma_f32_16x16x32_bf16 v[104:107], v[136:139], v[210:213], v[104:107]
	v_mfma_f32_16x16x32_bf16 v[92:95], v[128:131], v[218:221], v[92:95]
	v_mfma_f32_16x16x32_bf16 v[88:91], v[136:139], v[218:221], v[88:91]
	v_mfma_f32_16x16x32_bf16 v[76:79], v[128:131], v[226:229], v[76:79]
	v_mfma_f32_16x16x32_bf16 v[72:75], v[136:139], v[226:229], v[72:75]
	v_mfma_f32_16x16x32_bf16 v[124:127], v[132:135], v[202:205], v[124:127]
	v_mfma_f32_16x16x32_bf16 v[120:123], v[140:143], v[202:205], v[120:123]
	v_mfma_f32_16x16x32_bf16 v[108:111], v[132:135], v[214:217], v[108:111]
	v_mfma_f32_16x16x32_bf16 v[104:107], v[140:143], v[214:217], v[104:107]
	v_mfma_f32_16x16x32_bf16 v[92:95], v[132:135], v[222:225], v[92:95]
	v_mfma_f32_16x16x32_bf16 v[88:91], v[140:143], v[222:225], v[88:91]
	v_mfma_f32_16x16x32_bf16 v[76:79], v[132:135], v[230:233], v[76:79]
	v_mfma_f32_16x16x32_bf16 v[72:75], v[140:143], v[230:233], v[72:75]
	v_mfma_f32_16x16x32_bf16 v[116:119], v[144:147], v[196:199], v[116:119]
	v_mfma_f32_16x16x32_bf16 v[112:115], v[180:183], v[196:199], v[112:115]
	v_mfma_f32_16x16x32_bf16 v[100:103], v[144:147], v[210:213], v[100:103]
	v_mfma_f32_16x16x32_bf16 v[96:99], v[180:183], v[210:213], v[96:99]
	v_mfma_f32_16x16x32_bf16 v[84:87], v[144:147], v[218:221], v[84:87]
	v_mfma_f32_16x16x32_bf16 v[80:83], v[180:183], v[218:221], v[80:83]
	v_mfma_f32_16x16x32_bf16 v[68:71], v[144:147], v[226:229], v[68:71]
	v_mfma_f32_16x16x32_bf16 v[64:67], v[180:183], v[226:229], v[64:67]
	v_mfma_f32_16x16x32_bf16 v[116:119], v[148:151], v[202:205], v[116:119]
	v_mfma_f32_16x16x32_bf16 v[112:115], v[188:191], v[202:205], v[112:115]
	v_mfma_f32_16x16x32_bf16 v[100:103], v[148:151], v[214:217], v[100:103]
	v_mfma_f32_16x16x32_bf16 v[96:99], v[188:191], v[214:217], v[96:99]
	v_mfma_f32_16x16x32_bf16 v[84:87], v[148:151], v[222:225], v[84:87]
	v_mfma_f32_16x16x32_bf16 v[80:83], v[188:191], v[222:225], v[80:83]
	v_mfma_f32_16x16x32_bf16 v[68:71], v[148:151], v[230:233], v[68:71]
	v_mfma_f32_16x16x32_bf16 v[64:67], v[188:191], v[230:233], v[64:67]
	s_setprio 0
	s_barrier
	s_add_i32 s50, s67, s52
	s_mov_b32 m0, s50
	ds_read_b128 v[196:199], v195 offset:49152
	ds_read_b128 v[202:205], v195 offset:50176
	ds_read_b128 v[210:213], v195 offset:51200
	ds_read_b128 v[214:217], v195 offset:52224
	ds_read_b128 v[218:221], v195 offset:53248
	ds_read_b128 v[222:225], v195 offset:54272
	ds_read_b128 v[226:229], v195 offset:55296
	ds_read_b128 v[230:233], v195 offset:56320
	global_load_lds_dwordx4 v154, s[98:99]
	s_add_i32 m0, s50, 0x2000
	s_add_u32 s48, s48, 0x40080
	s_addc_u32 s49, s49, 0
	s_add_i32 s50, s68, s52
	global_load_lds_dwordx4 v158, s[98:99]
	s_mov_b32 m0, s50
	s_nop 0
	global_load_lds_dwordx4 v154, s[48:49]
	s_add_i32 m0, s50, 0x2000
	s_nop 0
	global_load_lds_dwordx4 v158, s[48:49]
	s_mov_b32 m0, s57
	s_nop 0
	global_load_lds_dwordx4 v152, s[100:101]
	s_mov_b32 m0, s58
	s_nop 0
	global_load_lds_dwordx4 v156, s[100:101]
	s_waitcnt vmcnt(8)
	s_waitcnt lgkmcnt(0)
	s_barrier
	s_setprio 1
	s_waitcnt lgkmcnt(0)
	v_mfma_f32_16x16x32_bf16 v[60:63], v[128:131], v[196:199], v[60:63]
	v_mfma_f32_16x16x32_bf16 v[56:59], v[136:139], v[196:199], v[56:59]
	v_mfma_f32_16x16x32_bf16 v[44:47], v[128:131], v[210:213], v[44:47]
	v_mfma_f32_16x16x32_bf16 v[40:43], v[136:139], v[210:213], v[40:43]
	v_mfma_f32_16x16x32_bf16 v[28:31], v[128:131], v[218:221], v[28:31]
	v_mfma_f32_16x16x32_bf16 v[24:27], v[136:139], v[218:221], v[24:27]
	v_mfma_f32_16x16x32_bf16 v[12:15], v[128:131], v[226:229], v[12:15]
	v_mfma_f32_16x16x32_bf16 v[8:11], v[136:139], v[226:229], v[8:11]
	v_mfma_f32_16x16x32_bf16 v[60:63], v[132:135], v[202:205], v[60:63]
	v_mfma_f32_16x16x32_bf16 v[56:59], v[140:143], v[202:205], v[56:59]
	v_mfma_f32_16x16x32_bf16 v[44:47], v[132:135], v[214:217], v[44:47]
	v_mfma_f32_16x16x32_bf16 v[40:43], v[140:143], v[214:217], v[40:43]
	v_mfma_f32_16x16x32_bf16 v[28:31], v[132:135], v[222:225], v[28:31]
	v_mfma_f32_16x16x32_bf16 v[24:27], v[140:143], v[222:225], v[24:27]
	v_mfma_f32_16x16x32_bf16 v[12:15], v[132:135], v[230:233], v[12:15]
	v_mfma_f32_16x16x32_bf16 v[8:11], v[140:143], v[230:233], v[8:11]
	v_mfma_f32_16x16x32_bf16 v[52:55], v[144:147], v[196:199], v[52:55]
	v_mfma_f32_16x16x32_bf16 v[48:51], v[180:183], v[196:199], v[48:51]
	v_mfma_f32_16x16x32_bf16 v[36:39], v[144:147], v[210:213], v[36:39]
	v_mfma_f32_16x16x32_bf16 v[32:35], v[180:183], v[210:213], v[32:35]
	v_mfma_f32_16x16x32_bf16 v[20:23], v[144:147], v[218:221], v[20:23]
	v_mfma_f32_16x16x32_bf16 v[16:19], v[180:183], v[218:221], v[16:19]
	v_mfma_f32_16x16x32_bf16 v[4:7], v[144:147], v[226:229], v[4:7]
	v_mfma_f32_16x16x32_bf16 v[0:3], v[180:183], v[226:229], v[0:3]
	v_mfma_f32_16x16x32_bf16 v[52:55], v[148:151], v[202:205], v[52:55]
	v_mfma_f32_16x16x32_bf16 v[48:51], v[188:191], v[202:205], v[48:51]
	v_mfma_f32_16x16x32_bf16 v[36:39], v[148:151], v[214:217], v[36:39]
	v_mfma_f32_16x16x32_bf16 v[32:35], v[188:191], v[214:217], v[32:35]
	v_mfma_f32_16x16x32_bf16 v[20:23], v[148:151], v[222:225], v[20:23]
	v_mfma_f32_16x16x32_bf16 v[16:19], v[188:191], v[222:225], v[16:19]
	v_mfma_f32_16x16x32_bf16 v[4:7], v[148:151], v[230:233], v[4:7]
	v_mfma_f32_16x16x32_bf16 v[0:3], v[188:191], v[230:233], v[0:3]
	s_setprio 0
	s_barrier
	s_add_i32 s66, s66, 2
	s_add_u32 s46, s46, 0x100
	s_addc_u32 s47, s47, 0
	s_add_u32 s64, s64, 0x100
	s_addc_u32 s65, s65, 0
	s_cmp_gt_u32 s66, 13
	s_cbranch_scc0 .LBB0_492

.LBB0_577:
	s_ashr_i32 s47, s46, 31
	s_lshl_b64 s[48:49], s[46:47], 19
	s_add_u32 s48, s2, s48
	s_addc_u32 s49, s31, s49
	s_and_b64 s[50:51], s[10:11], exec
	s_cselect_b32 s47, s49, s57
	s_cselect_b32 s53, s48, s56
	s_ashr_i32 s45, s44, 31
	s_lshl_b64 s[50:51], s[44:45], 19
	s_add_u32 s50, s34, s50
	s_addc_u32 s51, s35, s51
	s_and_b64 s[60:61], s[10:11], exec
	s_cselect_b32 s45, s51, s59
	s_cselect_b32 s76, s50, s58
	s_add_u32 s77, s58, 0x100
	s_addc_u32 s78, s59, 0
	s_mov_b32 s79, -2
	ds_read_b128 v[72:75], v206
	ds_read_b128 v[76:79], v206 offset:1024
	ds_read_b128 v[80:83], v206 offset:2048
	ds_read_b128 v[84:87], v206 offset:3072
	ds_read_b128 v[116:119], v207
	ds_read_b128 v[120:123], v207 offset:1024
	ds_read_b128 v[124:127], v207 offset:2048
	ds_read_b128 v[128:131], v207 offset:3072
	s_add_u32 s58, s56, 0x100
	s_addc_u32 s59, s57, 0
	s_cmp_eq_u32 s79, 12
	s_cselect_b32 s63, s47, s59
	s_cselect_b32 s62, s53, s58
	s_cselect_b32 s61, s45, s78
	s_cselect_b32 s60, s76, s77
	s_add_i32 m0, s43, 0xc000
	ds_read_b128 v[140:143], v209
	ds_read_b128 v[164:167], v209 offset:1024
	ds_read_b128 v[168:171], v209 offset:2048
	ds_read_b128 v[192:195], v209 offset:3072
	ds_read_b128 v[196:199], v209 offset:4096
	ds_read_b128 v[200:203], v209 offset:5120
	ds_read_b128 v[212:215], v209 offset:6144
	ds_read_b128 v[216:219], v209 offset:7168
	global_load_lds_dwordx4 v184, s[56:57]
	s_add_i32 m0, s43, 0xe000
	s_nop 0
	global_load_lds_dwordx4 v186, s[56:57]
	s_waitcnt vmcnt(8)
	s_waitcnt lgkmcnt(0)
	s_barrier
	s_setprio 1
	s_waitcnt lgkmcnt(0)
	v_mfma_f32_16x16x32_bf16 v[160:163], v[72:75], v[140:143], 0
	v_mfma_f32_16x16x32_bf16 v[108:111], v[80:83], v[140:143], 0
	v_mfma_f32_16x16x32_bf16 v[156:159], v[72:75], v[168:171], 0
	v_mfma_f32_16x16x32_bf16 v[104:107], v[80:83], v[168:171], 0
	v_mfma_f32_16x16x32_bf16 v[144:147], v[72:75], v[196:199], 0
	v_mfma_f32_16x16x32_bf16 v[92:95], v[80:83], v[196:199], 0
	v_mfma_f32_16x16x32_bf16 v[152:155], v[72:75], v[212:215], 0
	v_mfma_f32_16x16x32_bf16 v[100:103], v[80:83], v[212:215], 0
	v_mfma_f32_16x16x32_bf16 v[160:163], v[76:79], v[164:167], v[160:163]
	v_mfma_f32_16x16x32_bf16 v[108:111], v[84:87], v[164:167], v[108:111]
	v_mfma_f32_16x16x32_bf16 v[156:159], v[76:79], v[192:195], v[156:159]
	v_mfma_f32_16x16x32_bf16 v[104:107], v[84:87], v[192:195], v[104:107]
	v_mfma_f32_16x16x32_bf16 v[144:147], v[76:79], v[200:203], v[144:147]
	v_mfma_f32_16x16x32_bf16 v[92:95], v[84:87], v[200:203], v[92:95]
	v_mfma_f32_16x16x32_bf16 v[152:155], v[76:79], v[216:219], v[152:155]
	v_mfma_f32_16x16x32_bf16 v[100:103], v[84:87], v[216:219], v[100:103]
	v_mfma_f32_16x16x32_bf16 v[148:151], v[116:119], v[140:143], 0
	v_mfma_f32_16x16x32_bf16 v[96:99], v[124:127], v[140:143], 0
	v_mfma_f32_16x16x32_bf16 v[136:139], v[116:119], v[168:171], 0
	v_mfma_f32_16x16x32_bf16 v[88:91], v[124:127], v[168:171], 0
	v_mfma_f32_16x16x32_bf16 v[132:135], v[116:119], v[196:199], 0
	v_mfma_f32_16x16x32_bf16 v[68:71], v[124:127], v[196:199], 0
	v_mfma_f32_16x16x32_bf16 v[112:115], v[116:119], v[212:215], 0
	v_mfma_f32_16x16x32_bf16 v[64:67], v[124:127], v[212:215], 0
	v_mfma_f32_16x16x32_bf16 v[148:151], v[120:123], v[164:167], v[148:151]
	v_mfma_f32_16x16x32_bf16 v[96:99], v[128:131], v[164:167], v[96:99]
	v_mfma_f32_16x16x32_bf16 v[136:139], v[120:123], v[192:195], v[136:139]
	v_mfma_f32_16x16x32_bf16 v[88:91], v[128:131], v[192:195], v[88:91]
	v_mfma_f32_16x16x32_bf16 v[132:135], v[120:123], v[200:203], v[132:135]
	v_mfma_f32_16x16x32_bf16 v[68:71], v[128:131], v[200:203], v[68:71]
	v_mfma_f32_16x16x32_bf16 v[112:115], v[120:123], v[216:219], v[112:115]
	v_mfma_f32_16x16x32_bf16 v[64:67], v[128:131], v[216:219], v[64:67]
	s_setprio 0
	s_barrier
	s_add_u32 s98, s60, s22
	s_addc_u32 s99, s61, s23
	s_add_u32 s100, s62, s22
	s_addc_u32 s101, s63, s23
	s_add_i32 s56, s73, s41
	s_mov_b32 m0, s56
	ds_read_b128 v[140:143], v209 offset:16384
	ds_read_b128 v[164:167], v209 offset:17408
	ds_read_b128 v[168:171], v209 offset:18432
	ds_read_b128 v[192:195], v209 offset:19456
	ds_read_b128 v[196:199], v209 offset:20480
	ds_read_b128 v[200:203], v209 offset:21504
	ds_read_b128 v[212:215], v209 offset:22528
	ds_read_b128 v[216:219], v209 offset:23552
	global_load_lds_dwordx4 v176, s[60:61]
	s_add_i32 m0, s56, 0x2000
	s_add_u32 s56, s60, 0x40000
	s_addc_u32 s57, s61, 0
	s_add_i32 s80, s74, s41
	global_load_lds_dwordx4 v180, s[60:61]
	s_mov_b32 m0, s80
	s_nop 0
	global_load_lds_dwordx4 v176, s[56:57]
	s_add_i32 m0, s80, 0x2000
	s_nop 0
	global_load_lds_dwordx4 v180, s[56:57]
	s_mov_b32 m0, s43
	s_nop 0
	global_load_lds_dwordx4 v174, s[62:63]
	s_mov_b32 m0, s55
	s_nop 0
	global_load_lds_dwordx4 v178, s[62:63]
	s_waitcnt vmcnt(8)
	s_waitcnt lgkmcnt(0)
	s_barrier
	s_setprio 1
	s_waitcnt lgkmcnt(0)
	v_mfma_f32_16x16x32_bf16 v[60:63], v[72:75], v[140:143], 0
	v_mfma_f32_16x16x32_bf16 v[28:31], v[80:83], v[140:143], 0
	v_mfma_f32_16x16x32_bf16 v[56:59], v[72:75], v[168:171], 0
	v_mfma_f32_16x16x32_bf16 v[24:27], v[80:83], v[168:171], 0
	v_mfma_f32_16x16x32_bf16 v[44:47], v[72:75], v[196:199], 0
	v_mfma_f32_16x16x32_bf16 v[12:15], v[80:83], v[196:199], 0
	v_mfma_f32_16x16x32_bf16 v[52:55], v[72:75], v[212:215], 0
	v_mfma_f32_16x16x32_bf16 v[20:23], v[80:83], v[212:215], 0
	v_mfma_f32_16x16x32_bf16 v[60:63], v[76:79], v[164:167], v[60:63]
	v_mfma_f32_16x16x32_bf16 v[28:31], v[84:87], v[164:167], v[28:31]
	v_mfma_f32_16x16x32_bf16 v[56:59], v[76:79], v[192:195], v[56:59]
	v_mfma_f32_16x16x32_bf16 v[24:27], v[84:87], v[192:195], v[24:27]
	v_mfma_f32_16x16x32_bf16 v[44:47], v[76:79], v[200:203], v[44:47]
	v_mfma_f32_16x16x32_bf16 v[12:15], v[84:87], v[200:203], v[12:15]
	v_mfma_f32_16x16x32_bf16 v[52:55], v[76:79], v[216:219], v[52:55]
	v_mfma_f32_16x16x32_bf16 v[20:23], v[84:87], v[216:219], v[20:23]
	v_mfma_f32_16x16x32_bf16 v[48:51], v[116:119], v[140:143], 0
	v_mfma_f32_16x16x32_bf16 v[16:19], v[124:127], v[140:143], 0
	v_mfma_f32_16x16x32_bf16 v[40:43], v[116:119], v[168:171], 0
	v_mfma_f32_16x16x32_bf16 v[8:11], v[124:127], v[168:171], 0
	v_mfma_f32_16x16x32_bf16 v[36:39], v[116:119], v[196:199], 0
	v_mfma_f32_16x16x32_bf16 v[4:7], v[124:127], v[196:199], 0
	v_mfma_f32_16x16x32_bf16 v[32:35], v[116:119], v[212:215], 0
	v_mfma_f32_16x16x32_bf16 v[0:3], v[124:127], v[212:215], 0
	v_mfma_f32_16x16x32_bf16 v[48:51], v[120:123], v[164:167], v[48:51]
	v_mfma_f32_16x16x32_bf16 v[16:19], v[128:131], v[164:167], v[16:19]
	v_mfma_f32_16x16x32_bf16 v[40:43], v[120:123], v[192:195], v[40:43]
	v_mfma_f32_16x16x32_bf16 v[8:11], v[128:131], v[192:195], v[8:11]
	v_mfma_f32_16x16x32_bf16 v[36:39], v[120:123], v[200:203], v[36:39]
	v_mfma_f32_16x16x32_bf16 v[4:7], v[128:131], v[200:203], v[4:7]
	v_mfma_f32_16x16x32_bf16 v[32:35], v[120:123], v[216:219], v[32:35]
	v_mfma_f32_16x16x32_bf16 v[0:3], v[128:131], v[216:219], v[0:3]
	s_setprio 0
	s_barrier
	s_add_i32 s80, 0, 0x18000
	s_add_i32 s81, 0, 0x1c000
	v_add_u32_e32 v84, s80, v204
	v_add_u32_e32 v128, s81, v204
	ds_read_b128 v[72:75], v84
	ds_read_b128 v[76:79], v84 offset:1024
	ds_read_b128 v[80:83], v84 offset:2048
	ds_read_b128 v[84:87], v84 offset:3072
	ds_read_b128 v[116:119], v128
	ds_read_b128 v[120:123], v128 offset:1024
	ds_read_b128 v[124:127], v128 offset:2048
	ds_read_b128 v[128:131], v128 offset:3072
	s_add_u32 s56, s62, 0x40000
	s_addc_u32 s57, s63, 0
	s_mov_b32 m0, s64
	ds_read_b128 v[140:143], v209 offset:32768
	ds_read_b128 v[164:167], v209 offset:33792
	ds_read_b128 v[168:171], v209 offset:34816
	ds_read_b128 v[192:195], v209 offset:35840
	ds_read_b128 v[196:199], v209 offset:36864
	ds_read_b128 v[200:203], v209 offset:37888
	ds_read_b128 v[212:215], v209 offset:38912
	ds_read_b128 v[216:219], v209 offset:39936
	global_load_lds_dwordx4 v174, s[56:57]
	s_mov_b32 m0, s65
	s_nop 0
	global_load_lds_dwordx4 v178, s[56:57]
	s_waitcnt vmcnt(8)
	s_waitcnt lgkmcnt(0)
	s_barrier
	s_setprio 1
	s_waitcnt lgkmcnt(0)
	v_mfma_f32_16x16x32_bf16 v[160:163], v[72:75], v[140:143], v[160:163]
	v_mfma_f32_16x16x32_bf16 v[108:111], v[80:83], v[140:143], v[108:111]
	v_mfma_f32_16x16x32_bf16 v[156:159], v[72:75], v[168:171], v[156:159]
	v_mfma_f32_16x16x32_bf16 v[104:107], v[80:83], v[168:171], v[104:107]
	v_mfma_f32_16x16x32_bf16 v[144:147], v[72:75], v[196:199], v[144:147]
	v_mfma_f32_16x16x32_bf16 v[92:95], v[80:83], v[196:199], v[92:95]
	v_mfma_f32_16x16x32_bf16 v[152:155], v[72:75], v[212:215], v[152:155]
	v_mfma_f32_16x16x32_bf16 v[100:103], v[80:83], v[212:215], v[100:103]
	v_mfma_f32_16x16x32_bf16 v[160:163], v[76:79], v[164:167], v[160:163]
	v_mfma_f32_16x16x32_bf16 v[108:111], v[84:87], v[164:167], v[108:111]
	v_mfma_f32_16x16x32_bf16 v[156:159], v[76:79], v[192:195], v[156:159]
	v_mfma_f32_16x16x32_bf16 v[104:107], v[84:87], v[192:195], v[104:107]
	v_mfma_f32_16x16x32_bf16 v[144:147], v[76:79], v[200:203], v[144:147]
	v_mfma_f32_16x16x32_bf16 v[92:95], v[84:87], v[200:203], v[92:95]
	v_mfma_f32_16x16x32_bf16 v[152:155], v[76:79], v[216:219], v[152:155]
	v_mfma_f32_16x16x32_bf16 v[100:103], v[84:87], v[216:219], v[100:103]
	v_mfma_f32_16x16x32_bf16 v[148:151], v[116:119], v[140:143], v[148:151]
	v_mfma_f32_16x16x32_bf16 v[96:99], v[124:127], v[140:143], v[96:99]
	v_mfma_f32_16x16x32_bf16 v[136:139], v[116:119], v[168:171], v[136:139]
	v_mfma_f32_16x16x32_bf16 v[88:91], v[124:127], v[168:171], v[88:91]
	v_mfma_f32_16x16x32_bf16 v[132:135], v[116:119], v[196:199], v[132:135]
	v_mfma_f32_16x16x32_bf16 v[68:71], v[124:127], v[196:199], v[68:71]
	v_mfma_f32_16x16x32_bf16 v[112:115], v[116:119], v[212:215], v[112:115]
	v_mfma_f32_16x16x32_bf16 v[64:67], v[124:127], v[212:215], v[64:67]
	v_mfma_f32_16x16x32_bf16 v[148:151], v[120:123], v[164:167], v[148:151]
	v_mfma_f32_16x16x32_bf16 v[96:99], v[128:131], v[164:167], v[96:99]
	v_mfma_f32_16x16x32_bf16 v[136:139], v[120:123], v[192:195], v[136:139]
	v_mfma_f32_16x16x32_bf16 v[88:91], v[128:131], v[192:195], v[88:91]
	v_mfma_f32_16x16x32_bf16 v[132:135], v[120:123], v[200:203], v[132:135]
	v_mfma_f32_16x16x32_bf16 v[68:71], v[128:131], v[200:203], v[68:71]
	v_mfma_f32_16x16x32_bf16 v[112:115], v[120:123], v[216:219], v[112:115]
	v_mfma_f32_16x16x32_bf16 v[64:67], v[128:131], v[216:219], v[64:67]
	s_setprio 0
	s_barrier
	s_add_i32 s56, s80, s41
	s_mov_b32 m0, s56
	ds_read_b128 v[140:143], v209 offset:49152
	ds_read_b128 v[164:167], v209 offset:50176
	ds_read_b128 v[168:171], v209 offset:51200
	ds_read_b128 v[192:195], v209 offset:52224
	ds_read_b128 v[196:199], v209 offset:53248
	ds_read_b128 v[200:203], v209 offset:54272
	ds_read_b128 v[212:215], v209 offset:55296
	ds_read_b128 v[216:219], v209 offset:56320
	global_load_lds_dwordx4 v176, s[98:99]
	s_add_i32 m0, s56, 0x2000
	s_add_u32 s56, s60, 0x40080
	s_addc_u32 s57, s61, 0
	s_add_i32 s60, s81, s41
	global_load_lds_dwordx4 v180, s[98:99]
	s_mov_b32 m0, s60
	s_nop 0
	global_load_lds_dwordx4 v176, s[56:57]
	s_add_i32 m0, s60, 0x2000
	s_nop 0
	global_load_lds_dwordx4 v180, s[56:57]
	s_mov_b32 m0, s69
	s_nop 0
	global_load_lds_dwordx4 v174, s[100:101]
	s_mov_b32 m0, s70
	s_nop 0
	global_load_lds_dwordx4 v178, s[100:101]
	s_waitcnt vmcnt(8)
	s_waitcnt lgkmcnt(0)
	s_barrier
	s_setprio 1
	s_waitcnt lgkmcnt(0)
	v_mfma_f32_16x16x32_bf16 v[60:63], v[72:75], v[140:143], v[60:63]
	v_mfma_f32_16x16x32_bf16 v[28:31], v[80:83], v[140:143], v[28:31]
	v_mfma_f32_16x16x32_bf16 v[56:59], v[72:75], v[168:171], v[56:59]
	v_mfma_f32_16x16x32_bf16 v[24:27], v[80:83], v[168:171], v[24:27]
	v_mfma_f32_16x16x32_bf16 v[44:47], v[72:75], v[196:199], v[44:47]
	v_mfma_f32_16x16x32_bf16 v[12:15], v[80:83], v[196:199], v[12:15]
	v_mfma_f32_16x16x32_bf16 v[52:55], v[72:75], v[212:215], v[52:55]
	v_mfma_f32_16x16x32_bf16 v[20:23], v[80:83], v[212:215], v[20:23]
	v_mfma_f32_16x16x32_bf16 v[60:63], v[76:79], v[164:167], v[60:63]
	v_mfma_f32_16x16x32_bf16 v[28:31], v[84:87], v[164:167], v[28:31]
	v_mfma_f32_16x16x32_bf16 v[56:59], v[76:79], v[192:195], v[56:59]
	v_mfma_f32_16x16x32_bf16 v[24:27], v[84:87], v[192:195], v[24:27]
	v_mfma_f32_16x16x32_bf16 v[44:47], v[76:79], v[200:203], v[44:47]
	v_mfma_f32_16x16x32_bf16 v[12:15], v[84:87], v[200:203], v[12:15]
	v_mfma_f32_16x16x32_bf16 v[52:55], v[76:79], v[216:219], v[52:55]
	v_mfma_f32_16x16x32_bf16 v[20:23], v[84:87], v[216:219], v[20:23]
	v_mfma_f32_16x16x32_bf16 v[48:51], v[116:119], v[140:143], v[48:51]
	v_mfma_f32_16x16x32_bf16 v[16:19], v[124:127], v[140:143], v[16:19]
	v_mfma_f32_16x16x32_bf16 v[40:43], v[116:119], v[168:171], v[40:43]
	v_mfma_f32_16x16x32_bf16 v[8:11], v[124:127], v[168:171], v[8:11]
	v_mfma_f32_16x16x32_bf16 v[36:39], v[116:119], v[196:199], v[36:39]
	v_mfma_f32_16x16x32_bf16 v[4:7], v[124:127], v[196:199], v[4:7]
	v_mfma_f32_16x16x32_bf16 v[32:35], v[116:119], v[212:215], v[32:35]
	v_mfma_f32_16x16x32_bf16 v[0:3], v[124:127], v[212:215], v[0:3]
	v_mfma_f32_16x16x32_bf16 v[48:51], v[120:123], v[164:167], v[48:51]
	v_mfma_f32_16x16x32_bf16 v[16:19], v[128:131], v[164:167], v[16:19]
	v_mfma_f32_16x16x32_bf16 v[40:43], v[120:123], v[192:195], v[40:43]
	v_mfma_f32_16x16x32_bf16 v[8:11], v[128:131], v[192:195], v[8:11]
	v_mfma_f32_16x16x32_bf16 v[36:39], v[120:123], v[200:203], v[36:39]
	v_mfma_f32_16x16x32_bf16 v[4:7], v[128:131], v[200:203], v[4:7]
	v_mfma_f32_16x16x32_bf16 v[32:35], v[120:123], v[216:219], v[32:35]
	v_mfma_f32_16x16x32_bf16 v[0:3], v[128:131], v[216:219], v[0:3]
	s_setprio 0
	s_barrier
	s_add_i32 s79, s79, 2
	s_add_u32 s77, s77, 0x100
	s_addc_u32 s78, s78, 0
	s_cmp_gt_u32 s79, 13
	s_mov_b64 s[56:57], s[58:59]
	s_cbranch_scc1 .Lkexit_2
	v_add_u32_e32 v248, 0x18000, v204
	v_add_u32_e32 v249, 0x1c000, v204
.LBB0_578:
	ds_read_b128 v[72:75], v206
	ds_read_b128 v[76:79], v206 offset:1024
	ds_read_b128 v[80:83], v206 offset:2048
	ds_read_b128 v[84:87], v206 offset:3072
	ds_read_b128 v[116:119], v207
	ds_read_b128 v[120:123], v207 offset:1024
	ds_read_b128 v[124:127], v207 offset:2048
	ds_read_b128 v[128:131], v207 offset:3072
	s_add_u32 s58, s56, 0x100
	s_addc_u32 s59, s57, 0
	s_cmp_eq_u32 s79, 12
	s_cselect_b32 s63, s47, s59
	s_cselect_b32 s62, s53, s58
	s_cselect_b32 s61, s45, s78
	s_cselect_b32 s60, s76, s77
	s_add_i32 m0, s43, 0xc000
	ds_read_b128 v[140:143], v209
	ds_read_b128 v[164:167], v209 offset:1024
	ds_read_b128 v[168:171], v209 offset:2048
	ds_read_b128 v[192:195], v209 offset:3072
	ds_read_b128 v[196:199], v209 offset:4096
	ds_read_b128 v[200:203], v209 offset:5120
	ds_read_b128 v[212:215], v209 offset:6144
	ds_read_b128 v[216:219], v209 offset:7168
	global_load_lds_dwordx4 v184, s[56:57]
	s_add_i32 m0, s43, 0xe000
	s_nop 0
	global_load_lds_dwordx4 v186, s[56:57]
	s_waitcnt vmcnt(8)
	s_waitcnt lgkmcnt(0)
	s_barrier
	s_setprio 1
	s_waitcnt lgkmcnt(0)
	v_mfma_f32_16x16x32_bf16 v[160:163], v[72:75], v[140:143], v[160:163]
	v_mfma_f32_16x16x32_bf16 v[108:111], v[80:83], v[140:143], v[108:111]
	v_mfma_f32_16x16x32_bf16 v[156:159], v[72:75], v[168:171], v[156:159]
	v_mfma_f32_16x16x32_bf16 v[104:107], v[80:83], v[168:171], v[104:107]
	v_mfma_f32_16x16x32_bf16 v[144:147], v[72:75], v[196:199], v[144:147]
	v_mfma_f32_16x16x32_bf16 v[92:95], v[80:83], v[196:199], v[92:95]
	v_mfma_f32_16x16x32_bf16 v[152:155], v[72:75], v[212:215], v[152:155]
	v_mfma_f32_16x16x32_bf16 v[100:103], v[80:83], v[212:215], v[100:103]
	v_mfma_f32_16x16x32_bf16 v[160:163], v[76:79], v[164:167], v[160:163]
	v_mfma_f32_16x16x32_bf16 v[108:111], v[84:87], v[164:167], v[108:111]
	v_mfma_f32_16x16x32_bf16 v[156:159], v[76:79], v[192:195], v[156:159]
	v_mfma_f32_16x16x32_bf16 v[104:107], v[84:87], v[192:195], v[104:107]
	v_mfma_f32_16x16x32_bf16 v[144:147], v[76:79], v[200:203], v[144:147]
	v_mfma_f32_16x16x32_bf16 v[92:95], v[84:87], v[200:203], v[92:95]
	v_mfma_f32_16x16x32_bf16 v[152:155], v[76:79], v[216:219], v[152:155]
	v_mfma_f32_16x16x32_bf16 v[100:103], v[84:87], v[216:219], v[100:103]
	v_mfma_f32_16x16x32_bf16 v[148:151], v[116:119], v[140:143], v[148:151]
	v_mfma_f32_16x16x32_bf16 v[96:99], v[124:127], v[140:143], v[96:99]
	v_mfma_f32_16x16x32_bf16 v[136:139], v[116:119], v[168:171], v[136:139]
	v_mfma_f32_16x16x32_bf16 v[88:91], v[124:127], v[168:171], v[88:91]
	v_mfma_f32_16x16x32_bf16 v[132:135], v[116:119], v[196:199], v[132:135]
	v_mfma_f32_16x16x32_bf16 v[68:71], v[124:127], v[196:199], v[68:71]
	v_mfma_f32_16x16x32_bf16 v[112:115], v[116:119], v[212:215], v[112:115]
	v_mfma_f32_16x16x32_bf16 v[64:67], v[124:127], v[212:215], v[64:67]
	v_mfma_f32_16x16x32_bf16 v[148:151], v[120:123], v[164:167], v[148:151]
	v_mfma_f32_16x16x32_bf16 v[96:99], v[128:131], v[164:167], v[96:99]
	v_mfma_f32_16x16x32_bf16 v[136:139], v[120:123], v[192:195], v[136:139]
	v_mfma_f32_16x16x32_bf16 v[88:91], v[128:131], v[192:195], v[88:91]
	v_mfma_f32_16x16x32_bf16 v[132:135], v[120:123], v[200:203], v[132:135]
	v_mfma_f32_16x16x32_bf16 v[68:71], v[128:131], v[200:203], v[68:71]
	v_mfma_f32_16x16x32_bf16 v[112:115], v[120:123], v[216:219], v[112:115]
	v_mfma_f32_16x16x32_bf16 v[64:67], v[128:131], v[216:219], v[64:67]
	s_setprio 0
	s_barrier
	s_add_u32 s98, s60, s22
	s_addc_u32 s99, s61, s23
	s_add_u32 s100, s62, s22
	s_addc_u32 s101, s63, s23
	s_add_i32 s56, s73, s41
	s_mov_b32 m0, s56
	ds_read_b128 v[140:143], v209 offset:16384
	ds_read_b128 v[164:167], v209 offset:17408
	ds_read_b128 v[168:171], v209 offset:18432
	ds_read_b128 v[192:195], v209 offset:19456
	ds_read_b128 v[196:199], v209 offset:20480
	ds_read_b128 v[200:203], v209 offset:21504
	ds_read_b128 v[212:215], v209 offset:22528
	ds_read_b128 v[216:219], v209 offset:23552
	global_load_lds_dwordx4 v176, s[60:61]
	s_add_i32 m0, s56, 0x2000
	s_add_u32 s56, s60, 0x40000
	s_addc_u32 s57, s61, 0
	s_add_i32 s80, s74, s41
	global_load_lds_dwordx4 v180, s[60:61]
	s_mov_b32 m0, s80
	s_nop 0
	global_load_lds_dwordx4 v176, s[56:57]
	s_add_i32 m0, s80, 0x2000
	s_nop 0
	global_load_lds_dwordx4 v180, s[56:57]
	s_mov_b32 m0, s43
	s_nop 0
	global_load_lds_dwordx4 v174, s[62:63]
	s_mov_b32 m0, s55
	s_nop 0
	global_load_lds_dwordx4 v178, s[62:63]
	s_waitcnt vmcnt(8)
	s_waitcnt lgkmcnt(0)
	s_barrier
	s_setprio 1
	s_waitcnt lgkmcnt(0)
	v_mfma_f32_16x16x32_bf16 v[60:63], v[72:75], v[140:143], v[60:63]
	v_mfma_f32_16x16x32_bf16 v[28:31], v[80:83], v[140:143], v[28:31]
	v_mfma_f32_16x16x32_bf16 v[56:59], v[72:75], v[168:171], v[56:59]
	v_mfma_f32_16x16x32_bf16 v[24:27], v[80:83], v[168:171], v[24:27]
	v_mfma_f32_16x16x32_bf16 v[44:47], v[72:75], v[196:199], v[44:47]
	v_mfma_f32_16x16x32_bf16 v[12:15], v[80:83], v[196:199], v[12:15]
	v_mfma_f32_16x16x32_bf16 v[52:55], v[72:75], v[212:215], v[52:55]
	v_mfma_f32_16x16x32_bf16 v[20:23], v[80:83], v[212:215], v[20:23]
	v_mfma_f32_16x16x32_bf16 v[60:63], v[76:79], v[164:167], v[60:63]
	v_mfma_f32_16x16x32_bf16 v[28:31], v[84:87], v[164:167], v[28:31]
	v_mfma_f32_16x16x32_bf16 v[56:59], v[76:79], v[192:195], v[56:59]
	v_mfma_f32_16x16x32_bf16 v[24:27], v[84:87], v[192:195], v[24:27]
	v_mfma_f32_16x16x32_bf16 v[44:47], v[76:79], v[200:203], v[44:47]
	v_mfma_f32_16x16x32_bf16 v[12:15], v[84:87], v[200:203], v[12:15]
	v_mfma_f32_16x16x32_bf16 v[52:55], v[76:79], v[216:219], v[52:55]
	v_mfma_f32_16x16x32_bf16 v[20:23], v[84:87], v[216:219], v[20:23]
	v_mfma_f32_16x16x32_bf16 v[48:51], v[116:119], v[140:143], v[48:51]
	v_mfma_f32_16x16x32_bf16 v[16:19], v[124:127], v[140:143], v[16:19]
	v_mfma_f32_16x16x32_bf16 v[40:43], v[116:119], v[168:171], v[40:43]
	v_mfma_f32_16x16x32_bf16 v[8:11], v[124:127], v[168:171], v[8:11]
	v_mfma_f32_16x16x32_bf16 v[36:39], v[116:119], v[196:199], v[36:39]
	v_mfma_f32_16x16x32_bf16 v[4:7], v[124:127], v[196:199], v[4:7]
	v_mfma_f32_16x16x32_bf16 v[32:35], v[116:119], v[212:215], v[32:35]
	v_mfma_f32_16x16x32_bf16 v[0:3], v[124:127], v[212:215], v[0:3]
	v_mfma_f32_16x16x32_bf16 v[48:51], v[120:123], v[164:167], v[48:51]
	v_mfma_f32_16x16x32_bf16 v[16:19], v[128:131], v[164:167], v[16:19]
	v_mfma_f32_16x16x32_bf16 v[40:43], v[120:123], v[192:195], v[40:43]
	v_mfma_f32_16x16x32_bf16 v[8:11], v[128:131], v[192:195], v[8:11]
	v_mfma_f32_16x16x32_bf16 v[36:39], v[120:123], v[200:203], v[36:39]
	v_mfma_f32_16x16x32_bf16 v[4:7], v[128:131], v[200:203], v[4:7]
	v_mfma_f32_16x16x32_bf16 v[32:35], v[120:123], v[216:219], v[32:35]
	v_mfma_f32_16x16x32_bf16 v[0:3], v[128:131], v[216:219], v[0:3]
	s_setprio 0
	s_barrier
	s_add_i32 s80, 0, 0x18000
	s_add_i32 s81, 0, 0x1c000
	ds_read_b128 v[72:75], v248
	ds_read_b128 v[76:79], v248 offset:1024
	ds_read_b128 v[80:83], v248 offset:2048
	ds_read_b128 v[84:87], v248 offset:3072
	ds_read_b128 v[116:119], v249
	ds_read_b128 v[120:123], v249 offset:1024
	ds_read_b128 v[124:127], v249 offset:2048
	ds_read_b128 v[128:131], v249 offset:3072
	s_add_u32 s56, s62, 0x40000
	s_addc_u32 s57, s63, 0
	s_mov_b32 m0, s64
	ds_read_b128 v[140:143], v209 offset:32768
	ds_read_b128 v[164:167], v209 offset:33792
	ds_read_b128 v[168:171], v209 offset:34816
	ds_read_b128 v[192:195], v209 offset:35840
	ds_read_b128 v[196:199], v209 offset:36864
	ds_read_b128 v[200:203], v209 offset:37888
	ds_read_b128 v[212:215], v209 offset:38912
	ds_read_b128 v[216:219], v209 offset:39936
	global_load_lds_dwordx4 v174, s[56:57]
	s_mov_b32 m0, s65
	s_nop 0
	global_load_lds_dwordx4 v178, s[56:57]
	s_waitcnt vmcnt(8)
	s_waitcnt lgkmcnt(0)
	s_barrier
	s_setprio 1
	s_waitcnt lgkmcnt(0)
	v_mfma_f32_16x16x32_bf16 v[160:163], v[72:75], v[140:143], v[160:163]
	v_mfma_f32_16x16x32_bf16 v[108:111], v[80:83], v[140:143], v[108:111]
	v_mfma_f32_16x16x32_bf16 v[156:159], v[72:75], v[168:171], v[156:159]
	v_mfma_f32_16x16x32_bf16 v[104:107], v[80:83], v[168:171], v[104:107]
	v_mfma_f32_16x16x32_bf16 v[144:147], v[72:75], v[196:199], v[144:147]
	v_mfma_f32_16x16x32_bf16 v[92:95], v[80:83], v[196:199], v[92:95]
	v_mfma_f32_16x16x32_bf16 v[152:155], v[72:75], v[212:215], v[152:155]
	v_mfma_f32_16x16x32_bf16 v[100:103], v[80:83], v[212:215], v[100:103]
	v_mfma_f32_16x16x32_bf16 v[160:163], v[76:79], v[164:167], v[160:163]
	v_mfma_f32_16x16x32_bf16 v[108:111], v[84:87], v[164:167], v[108:111]
	v_mfma_f32_16x16x32_bf16 v[156:159], v[76:79], v[192:195], v[156:159]
	v_mfma_f32_16x16x32_bf16 v[104:107], v[84:87], v[192:195], v[104:107]
	v_mfma_f32_16x16x32_bf16 v[144:147], v[76:79], v[200:203], v[144:147]
	v_mfma_f32_16x16x32_bf16 v[92:95], v[84:87], v[200:203], v[92:95]
	v_mfma_f32_16x16x32_bf16 v[152:155], v[76:79], v[216:219], v[152:155]
	v_mfma_f32_16x16x32_bf16 v[100:103], v[84:87], v[216:219], v[100:103]
	v_mfma_f32_16x16x32_bf16 v[148:151], v[116:119], v[140:143], v[148:151]
	v_mfma_f32_16x16x32_bf16 v[96:99], v[124:127], v[140:143], v[96:99]
	v_mfma_f32_16x16x32_bf16 v[136:139], v[116:119], v[168:171], v[136:139]
	v_mfma_f32_16x16x32_bf16 v[88:91], v[124:127], v[168:171], v[88:91]
	v_mfma_f32_16x16x32_bf16 v[132:135], v[116:119], v[196:199], v[132:135]
	v_mfma_f32_16x16x32_bf16 v[68:71], v[124:127], v[196:199], v[68:71]
	v_mfma_f32_16x16x32_bf16 v[112:115], v[116:119], v[212:215], v[112:115]
	v_mfma_f32_16x16x32_bf16 v[64:67], v[124:127], v[212:215], v[64:67]
	v_mfma_f32_16x16x32_bf16 v[148:151], v[120:123], v[164:167], v[148:151]
	v_mfma_f32_16x16x32_bf16 v[96:99], v[128:131], v[164:167], v[96:99]
	v_mfma_f32_16x16x32_bf16 v[136:139], v[120:123], v[192:195], v[136:139]
	v_mfma_f32_16x16x32_bf16 v[88:91], v[128:131], v[192:195], v[88:91]
	v_mfma_f32_16x16x32_bf16 v[132:135], v[120:123], v[200:203], v[132:135]
	v_mfma_f32_16x16x32_bf16 v[68:71], v[128:131], v[200:203], v[68:71]
	v_mfma_f32_16x16x32_bf16 v[112:115], v[120:123], v[216:219], v[112:115]
	v_mfma_f32_16x16x32_bf16 v[64:67], v[128:131], v[216:219], v[64:67]
	s_setprio 0
	s_barrier
	s_add_i32 s56, s80, s41
	s_mov_b32 m0, s56
	ds_read_b128 v[140:143], v209 offset:49152
	ds_read_b128 v[164:167], v209 offset:50176
	ds_read_b128 v[168:171], v209 offset:51200
	ds_read_b128 v[192:195], v209 offset:52224
	ds_read_b128 v[196:199], v209 offset:53248
	ds_read_b128 v[200:203], v209 offset:54272
	ds_read_b128 v[212:215], v209 offset:55296
	ds_read_b128 v[216:219], v209 offset:56320
	global_load_lds_dwordx4 v176, s[98:99]
	s_add_i32 m0, s56, 0x2000
	s_add_u32 s56, s60, 0x40080
	s_addc_u32 s57, s61, 0
	s_add_i32 s60, s81, s41
	global_load_lds_dwordx4 v180, s[98:99]
	s_mov_b32 m0, s60
	s_nop 0
	global_load_lds_dwordx4 v176, s[56:57]
	s_add_i32 m0, s60, 0x2000
	s_nop 0
	global_load_lds_dwordx4 v180, s[56:57]
	s_mov_b32 m0, s69
	s_nop 0
	global_load_lds_dwordx4 v174, s[100:101]
	s_mov_b32 m0, s70
	s_nop 0
	global_load_lds_dwordx4 v178, s[100:101]
	s_waitcnt vmcnt(8)
	s_waitcnt lgkmcnt(0)
	s_barrier
	s_setprio 1
	s_waitcnt lgkmcnt(0)
	v_mfma_f32_16x16x32_bf16 v[60:63], v[72:75], v[140:143], v[60:63]
	v_mfma_f32_16x16x32_bf16 v[28:31], v[80:83], v[140:143], v[28:31]
	v_mfma_f32_16x16x32_bf16 v[56:59], v[72:75], v[168:171], v[56:59]
	v_mfma_f32_16x16x32_bf16 v[24:27], v[80:83], v[168:171], v[24:27]
	v_mfma_f32_16x16x32_bf16 v[44:47], v[72:75], v[196:199], v[44:47]
	v_mfma_f32_16x16x32_bf16 v[12:15], v[80:83], v[196:199], v[12:15]
	v_mfma_f32_16x16x32_bf16 v[52:55], v[72:75], v[212:215], v[52:55]
	v_mfma_f32_16x16x32_bf16 v[20:23], v[80:83], v[212:215], v[20:23]
	v_mfma_f32_16x16x32_bf16 v[60:63], v[76:79], v[164:167], v[60:63]
	v_mfma_f32_16x16x32_bf16 v[28:31], v[84:87], v[164:167], v[28:31]
	v_mfma_f32_16x16x32_bf16 v[56:59], v[76:79], v[192:195], v[56:59]
	v_mfma_f32_16x16x32_bf16 v[24:27], v[84:87], v[192:195], v[24:27]
	v_mfma_f32_16x16x32_bf16 v[44:47], v[76:79], v[200:203], v[44:47]
	v_mfma_f32_16x16x32_bf16 v[12:15], v[84:87], v[200:203], v[12:15]
	v_mfma_f32_16x16x32_bf16 v[52:55], v[76:79], v[216:219], v[52:55]
	v_mfma_f32_16x16x32_bf16 v[20:23], v[84:87], v[216:219], v[20:23]
	v_mfma_f32_16x16x32_bf16 v[48:51], v[116:119], v[140:143], v[48:51]
	v_mfma_f32_16x16x32_bf16 v[16:19], v[124:127], v[140:143], v[16:19]
	v_mfma_f32_16x16x32_bf16 v[40:43], v[116:119], v[168:171], v[40:43]
	v_mfma_f32_16x16x32_bf16 v[8:11], v[124:127], v[168:171], v[8:11]
	v_mfma_f32_16x16x32_bf16 v[36:39], v[116:119], v[196:199], v[36:39]
	v_mfma_f32_16x16x32_bf16 v[4:7], v[124:127], v[196:199], v[4:7]
	v_mfma_f32_16x16x32_bf16 v[32:35], v[116:119], v[212:215], v[32:35]
	v_mfma_f32_16x16x32_bf16 v[0:3], v[124:127], v[212:215], v[0:3]
	v_mfma_f32_16x16x32_bf16 v[48:51], v[120:123], v[164:167], v[48:51]
	v_mfma_f32_16x16x32_bf16 v[16:19], v[128:131], v[164:167], v[16:19]
	v_mfma_f32_16x16x32_bf16 v[40:43], v[120:123], v[192:195], v[40:43]
	v_mfma_f32_16x16x32_bf16 v[8:11], v[128:131], v[192:195], v[8:11]
	v_mfma_f32_16x16x32_bf16 v[36:39], v[120:123], v[200:203], v[36:39]
	v_mfma_f32_16x16x32_bf16 v[4:7], v[128:131], v[200:203], v[4:7]
	v_mfma_f32_16x16x32_bf16 v[32:35], v[120:123], v[216:219], v[32:35]
	v_mfma_f32_16x16x32_bf16 v[0:3], v[128:131], v[216:219], v[0:3]
	s_setprio 0
	s_barrier
	s_add_i32 s79, s79, 2
	s_add_u32 s77, s77, 0x100
	s_addc_u32 s78, s78, 0
	s_cmp_gt_u32 s79, 13
	s_mov_b64 s[56:57], s[58:59]
	s_cbranch_scc0 .LBB0_578

.LBB0_740:
	s_add_u32 s60, s38, 0x100
	s_addc_u32 s61, s39, 0
	s_mov_b32 s62, -2
	s_waitcnt lgkmcnt(0)
	ds_read_b128 v[128:131], v194
	ds_read_b128 v[132:135], v194 offset:1024
	ds_read_b128 v[136:139], v194 offset:2048
	ds_read_b128 v[140:143], v194 offset:3072
	ds_read_b128 v[144:147], v195
	ds_read_b128 v[148:151], v195 offset:1024
	ds_read_b128 v[168:171], v195 offset:2048
	ds_read_b128 v[174:177], v195 offset:3072
	s_add_u32 s38, s36, 0x100
	s_addc_u32 s39, s37, 0
	s_cmp_eq_u32 s62, 40
	s_cselect_b32 s43, s11, s39
	s_cselect_b32 s42, s10, s38
	s_cselect_b32 s41, s25, s61
	s_cselect_b32 s40, s24, s60
	s_add_i32 m0, s45, 0xc000
	ds_read_b128 v[178:181], v196
	ds_read_b128 v[182:185], v196 offset:1024
	ds_read_b128 v[186:189], v196 offset:2048
	ds_read_b128 v[198:201], v196 offset:3072
	ds_read_b128 v[202:205], v196 offset:4096
	ds_read_b128 v[210:213], v196 offset:5120
	ds_read_b128 v[214:217], v196 offset:6144
	ds_read_b128 v[218:221], v196 offset:7168
	global_load_lds_dwordx4 v160, s[36:37]
	s_add_i32 m0, s45, 0xe000
	s_nop 0
	global_load_lds_dwordx4 v162, s[36:37]
	s_waitcnt vmcnt(8)
	s_waitcnt lgkmcnt(0)
	s_barrier
	s_setprio 1
	s_waitcnt lgkmcnt(0)
	v_mfma_f32_16x16x32_bf16 v[124:127], v[128:131], v[178:181], 0
	v_mfma_f32_16x16x32_bf16 v[120:123], v[136:139], v[178:181], 0
	v_mfma_f32_16x16x32_bf16 v[108:111], v[128:131], v[186:189], 0
	v_mfma_f32_16x16x32_bf16 v[104:107], v[136:139], v[186:189], 0
	v_mfma_f32_16x16x32_bf16 v[92:95], v[128:131], v[202:205], 0
	v_mfma_f32_16x16x32_bf16 v[88:91], v[136:139], v[202:205], 0
	v_mfma_f32_16x16x32_bf16 v[76:79], v[128:131], v[214:217], 0
	v_mfma_f32_16x16x32_bf16 v[72:75], v[136:139], v[214:217], 0
	v_mfma_f32_16x16x32_bf16 v[124:127], v[132:135], v[182:185], v[124:127]
	v_mfma_f32_16x16x32_bf16 v[120:123], v[140:143], v[182:185], v[120:123]
	v_mfma_f32_16x16x32_bf16 v[108:111], v[132:135], v[198:201], v[108:111]
	v_mfma_f32_16x16x32_bf16 v[104:107], v[140:143], v[198:201], v[104:107]
	v_mfma_f32_16x16x32_bf16 v[92:95], v[132:135], v[210:213], v[92:95]
	v_mfma_f32_16x16x32_bf16 v[88:91], v[140:143], v[210:213], v[88:91]
	v_mfma_f32_16x16x32_bf16 v[76:79], v[132:135], v[218:221], v[76:79]
	v_mfma_f32_16x16x32_bf16 v[72:75], v[140:143], v[218:221], v[72:75]
	v_mfma_f32_16x16x32_bf16 v[116:119], v[144:147], v[178:181], 0
	v_mfma_f32_16x16x32_bf16 v[112:115], v[168:171], v[178:181], 0
	v_mfma_f32_16x16x32_bf16 v[100:103], v[144:147], v[186:189], 0
	v_mfma_f32_16x16x32_bf16 v[96:99], v[168:171], v[186:189], 0
	v_mfma_f32_16x16x32_bf16 v[84:87], v[144:147], v[202:205], 0
	v_mfma_f32_16x16x32_bf16 v[80:83], v[168:171], v[202:205], 0
	v_mfma_f32_16x16x32_bf16 v[68:71], v[144:147], v[214:217], 0
	v_mfma_f32_16x16x32_bf16 v[64:67], v[168:171], v[214:217], 0
	v_mfma_f32_16x16x32_bf16 v[116:119], v[148:151], v[182:185], v[116:119]
	v_mfma_f32_16x16x32_bf16 v[112:115], v[174:177], v[182:185], v[112:115]
	v_mfma_f32_16x16x32_bf16 v[100:103], v[148:151], v[198:201], v[100:103]
	v_mfma_f32_16x16x32_bf16 v[96:99], v[174:177], v[198:201], v[96:99]
	v_mfma_f32_16x16x32_bf16 v[84:87], v[148:151], v[210:213], v[84:87]
	v_mfma_f32_16x16x32_bf16 v[80:83], v[174:177], v[210:213], v[80:83]
	v_mfma_f32_16x16x32_bf16 v[68:71], v[148:151], v[218:221], v[68:71]
	v_mfma_f32_16x16x32_bf16 v[64:67], v[174:177], v[218:221], v[64:67]
	s_setprio 0
	s_barrier
	s_add_u32 s98, s40, s20
	s_addc_u32 s99, s41, s21
	s_add_u32 s100, s42, s20
	s_addc_u32 s101, s43, s21
	s_add_i32 s36, s54, s44
	s_mov_b32 m0, s36
	ds_read_b128 v[178:181], v196 offset:16384
	ds_read_b128 v[182:185], v196 offset:17408
	ds_read_b128 v[186:189], v196 offset:18432
	ds_read_b128 v[198:201], v196 offset:19456
	ds_read_b128 v[202:205], v196 offset:20480
	ds_read_b128 v[210:213], v196 offset:21504
	ds_read_b128 v[214:217], v196 offset:22528
	ds_read_b128 v[218:221], v196 offset:23552
	global_load_lds_dwordx4 v154, s[40:41]
	s_add_i32 m0, s36, 0x2000
	s_add_u32 s36, s40, 0xb0000
	s_addc_u32 s37, s41, 0
	s_add_i32 s63, s55, s44
	global_load_lds_dwordx4 v158, s[40:41]
	s_mov_b32 m0, s63
	s_nop 0
	global_load_lds_dwordx4 v154, s[36:37]
	s_add_i32 m0, s63, 0x2000
	s_nop 0
	global_load_lds_dwordx4 v158, s[36:37]
	s_mov_b32 m0, s45
	s_nop 0
	global_load_lds_dwordx4 v152, s[42:43]
	s_mov_b32 m0, s46
	s_nop 0
	global_load_lds_dwordx4 v156, s[42:43]
	s_waitcnt vmcnt(8)
	s_waitcnt lgkmcnt(0)
	s_barrier
	s_setprio 1
	s_waitcnt lgkmcnt(0)
	v_mfma_f32_16x16x32_bf16 v[60:63], v[128:131], v[178:181], 0
	v_mfma_f32_16x16x32_bf16 v[56:59], v[136:139], v[178:181], 0
	v_mfma_f32_16x16x32_bf16 v[44:47], v[128:131], v[186:189], 0
	v_mfma_f32_16x16x32_bf16 v[40:43], v[136:139], v[186:189], 0
	v_mfma_f32_16x16x32_bf16 v[28:31], v[128:131], v[202:205], 0
	v_mfma_f32_16x16x32_bf16 v[24:27], v[136:139], v[202:205], 0
	v_mfma_f32_16x16x32_bf16 v[12:15], v[128:131], v[214:217], 0
	v_mfma_f32_16x16x32_bf16 v[8:11], v[136:139], v[214:217], 0
	v_mfma_f32_16x16x32_bf16 v[60:63], v[132:135], v[182:185], v[60:63]
	v_mfma_f32_16x16x32_bf16 v[56:59], v[140:143], v[182:185], v[56:59]
	v_mfma_f32_16x16x32_bf16 v[44:47], v[132:135], v[198:201], v[44:47]
	v_mfma_f32_16x16x32_bf16 v[40:43], v[140:143], v[198:201], v[40:43]
	v_mfma_f32_16x16x32_bf16 v[28:31], v[132:135], v[210:213], v[28:31]
	v_mfma_f32_16x16x32_bf16 v[24:27], v[140:143], v[210:213], v[24:27]
	v_mfma_f32_16x16x32_bf16 v[12:15], v[132:135], v[218:221], v[12:15]
	v_mfma_f32_16x16x32_bf16 v[8:11], v[140:143], v[218:221], v[8:11]
	v_mfma_f32_16x16x32_bf16 v[52:55], v[144:147], v[178:181], 0
	v_mfma_f32_16x16x32_bf16 v[48:51], v[168:171], v[178:181], 0
	v_mfma_f32_16x16x32_bf16 v[36:39], v[144:147], v[186:189], 0
	v_mfma_f32_16x16x32_bf16 v[32:35], v[168:171], v[186:189], 0
	v_mfma_f32_16x16x32_bf16 v[20:23], v[144:147], v[202:205], 0
	v_mfma_f32_16x16x32_bf16 v[16:19], v[168:171], v[202:205], 0
	v_mfma_f32_16x16x32_bf16 v[4:7], v[144:147], v[214:217], 0
	v_mfma_f32_16x16x32_bf16 v[0:3], v[168:171], v[214:217], 0
	v_mfma_f32_16x16x32_bf16 v[52:55], v[148:151], v[182:185], v[52:55]
	v_mfma_f32_16x16x32_bf16 v[48:51], v[174:177], v[182:185], v[48:51]
	v_mfma_f32_16x16x32_bf16 v[36:39], v[148:151], v[198:201], v[36:39]
	v_mfma_f32_16x16x32_bf16 v[32:35], v[174:177], v[198:201], v[32:35]
	v_mfma_f32_16x16x32_bf16 v[20:23], v[148:151], v[210:213], v[20:23]
	v_mfma_f32_16x16x32_bf16 v[16:19], v[174:177], v[210:213], v[16:19]
	v_mfma_f32_16x16x32_bf16 v[4:7], v[148:151], v[218:221], v[4:7]
	v_mfma_f32_16x16x32_bf16 v[0:3], v[174:177], v[218:221], v[0:3]
	s_setprio 0
	s_barrier
	s_add_i32 s63, 0, 0x18000
	s_add_i32 s64, 0, 0x1c000
	v_add_u32_e32 v140, s63, v192
	v_add_u32_e32 v174, s64, v192
	ds_read_b128 v[128:131], v140
	ds_read_b128 v[132:135], v140 offset:1024
	ds_read_b128 v[136:139], v140 offset:2048
	ds_read_b128 v[140:143], v140 offset:3072
	ds_read_b128 v[144:147], v174
	ds_read_b128 v[148:151], v174 offset:1024
	ds_read_b128 v[168:171], v174 offset:2048
	ds_read_b128 v[174:177], v174 offset:3072
	s_add_u32 s36, s42, 0xb0000
	s_addc_u32 s37, s43, 0
	s_mov_b32 m0, s47
	ds_read_b128 v[178:181], v196 offset:32768
	ds_read_b128 v[182:185], v196 offset:33792
	ds_read_b128 v[186:189], v196 offset:34816
	ds_read_b128 v[198:201], v196 offset:35840
	ds_read_b128 v[202:205], v196 offset:36864
	ds_read_b128 v[210:213], v196 offset:37888
	ds_read_b128 v[214:217], v196 offset:38912
	ds_read_b128 v[218:221], v196 offset:39936
	global_load_lds_dwordx4 v152, s[36:37]
	s_mov_b32 m0, s48
	s_nop 0
	global_load_lds_dwordx4 v156, s[36:37]
	s_waitcnt vmcnt(8)
	s_waitcnt lgkmcnt(0)
	s_barrier
	s_setprio 1
	s_waitcnt lgkmcnt(0)
	v_mfma_f32_16x16x32_bf16 v[124:127], v[128:131], v[178:181], v[124:127]
	v_mfma_f32_16x16x32_bf16 v[120:123], v[136:139], v[178:181], v[120:123]
	v_mfma_f32_16x16x32_bf16 v[108:111], v[128:131], v[186:189], v[108:111]
	v_mfma_f32_16x16x32_bf16 v[104:107], v[136:139], v[186:189], v[104:107]
	v_mfma_f32_16x16x32_bf16 v[92:95], v[128:131], v[202:205], v[92:95]
	v_mfma_f32_16x16x32_bf16 v[88:91], v[136:139], v[202:205], v[88:91]
	v_mfma_f32_16x16x32_bf16 v[76:79], v[128:131], v[214:217], v[76:79]
	v_mfma_f32_16x16x32_bf16 v[72:75], v[136:139], v[214:217], v[72:75]
	v_mfma_f32_16x16x32_bf16 v[124:127], v[132:135], v[182:185], v[124:127]
	v_mfma_f32_16x16x32_bf16 v[120:123], v[140:143], v[182:185], v[120:123]
	v_mfma_f32_16x16x32_bf16 v[108:111], v[132:135], v[198:201], v[108:111]
	v_mfma_f32_16x16x32_bf16 v[104:107], v[140:143], v[198:201], v[104:107]
	v_mfma_f32_16x16x32_bf16 v[92:95], v[132:135], v[210:213], v[92:95]
	v_mfma_f32_16x16x32_bf16 v[88:91], v[140:143], v[210:213], v[88:91]
	v_mfma_f32_16x16x32_bf16 v[76:79], v[132:135], v[218:221], v[76:79]
	v_mfma_f32_16x16x32_bf16 v[72:75], v[140:143], v[218:221], v[72:75]
	v_mfma_f32_16x16x32_bf16 v[116:119], v[144:147], v[178:181], v[116:119]
	v_mfma_f32_16x16x32_bf16 v[112:115], v[168:171], v[178:181], v[112:115]
	v_mfma_f32_16x16x32_bf16 v[100:103], v[144:147], v[186:189], v[100:103]
	v_mfma_f32_16x16x32_bf16 v[96:99], v[168:171], v[186:189], v[96:99]
	v_mfma_f32_16x16x32_bf16 v[84:87], v[144:147], v[202:205], v[84:87]
	v_mfma_f32_16x16x32_bf16 v[80:83], v[168:171], v[202:205], v[80:83]
	v_mfma_f32_16x16x32_bf16 v[68:71], v[144:147], v[214:217], v[68:71]
	v_mfma_f32_16x16x32_bf16 v[64:67], v[168:171], v[214:217], v[64:67]
	v_mfma_f32_16x16x32_bf16 v[116:119], v[148:151], v[182:185], v[116:119]
	v_mfma_f32_16x16x32_bf16 v[112:115], v[174:177], v[182:185], v[112:115]
	v_mfma_f32_16x16x32_bf16 v[100:103], v[148:151], v[198:201], v[100:103]
	v_mfma_f32_16x16x32_bf16 v[96:99], v[174:177], v[198:201], v[96:99]
	v_mfma_f32_16x16x32_bf16 v[84:87], v[148:151], v[210:213], v[84:87]
	v_mfma_f32_16x16x32_bf16 v[80:83], v[174:177], v[210:213], v[80:83]
	v_mfma_f32_16x16x32_bf16 v[68:71], v[148:151], v[218:221], v[68:71]
	v_mfma_f32_16x16x32_bf16 v[64:67], v[174:177], v[218:221], v[64:67]
	s_setprio 0
	s_barrier
	s_add_i32 s36, s63, s44
	s_mov_b32 m0, s36
	ds_read_b128 v[178:181], v196 offset:49152
	ds_read_b128 v[182:185], v196 offset:50176
	ds_read_b128 v[186:189], v196 offset:51200
	ds_read_b128 v[198:201], v196 offset:52224
	ds_read_b128 v[202:205], v196 offset:53248
	ds_read_b128 v[210:213], v196 offset:54272
	ds_read_b128 v[214:217], v196 offset:55296
	ds_read_b128 v[218:221], v196 offset:56320
	global_load_lds_dwordx4 v154, s[98:99]
	s_add_i32 m0, s36, 0x2000
	s_add_u32 s36, s40, 0xb0080
	s_addc_u32 s37, s41, 0
	s_add_i32 s40, s64, s44
	global_load_lds_dwordx4 v158, s[98:99]
	s_mov_b32 m0, s40
	s_nop 0
	global_load_lds_dwordx4 v154, s[36:37]
	s_add_i32 m0, s40, 0x2000
	s_nop 0
	global_load_lds_dwordx4 v158, s[36:37]
	s_mov_b32 m0, s50
	s_nop 0
	global_load_lds_dwordx4 v152, s[100:101]
	s_mov_b32 m0, s51
	s_nop 0
	global_load_lds_dwordx4 v156, s[100:101]
	s_waitcnt vmcnt(8)
	s_waitcnt lgkmcnt(0)
	s_barrier
	s_setprio 1
	s_waitcnt lgkmcnt(0)
	v_mfma_f32_16x16x32_bf16 v[60:63], v[128:131], v[178:181], v[60:63]
	v_mfma_f32_16x16x32_bf16 v[56:59], v[136:139], v[178:181], v[56:59]
	v_mfma_f32_16x16x32_bf16 v[44:47], v[128:131], v[186:189], v[44:47]
	v_mfma_f32_16x16x32_bf16 v[40:43], v[136:139], v[186:189], v[40:43]
	v_mfma_f32_16x16x32_bf16 v[28:31], v[128:131], v[202:205], v[28:31]
	v_mfma_f32_16x16x32_bf16 v[24:27], v[136:139], v[202:205], v[24:27]
	v_mfma_f32_16x16x32_bf16 v[12:15], v[128:131], v[214:217], v[12:15]
	v_mfma_f32_16x16x32_bf16 v[8:11], v[136:139], v[214:217], v[8:11]
	v_mfma_f32_16x16x32_bf16 v[60:63], v[132:135], v[182:185], v[60:63]
	v_mfma_f32_16x16x32_bf16 v[56:59], v[140:143], v[182:185], v[56:59]
	v_mfma_f32_16x16x32_bf16 v[44:47], v[132:135], v[198:201], v[44:47]
	v_mfma_f32_16x16x32_bf16 v[40:43], v[140:143], v[198:201], v[40:43]
	v_mfma_f32_16x16x32_bf16 v[28:31], v[132:135], v[210:213], v[28:31]
	v_mfma_f32_16x16x32_bf16 v[24:27], v[140:143], v[210:213], v[24:27]
	v_mfma_f32_16x16x32_bf16 v[12:15], v[132:135], v[218:221], v[12:15]
	v_mfma_f32_16x16x32_bf16 v[8:11], v[140:143], v[218:221], v[8:11]
	v_mfma_f32_16x16x32_bf16 v[52:55], v[144:147], v[178:181], v[52:55]
	v_mfma_f32_16x16x32_bf16 v[48:51], v[168:171], v[178:181], v[48:51]
	v_mfma_f32_16x16x32_bf16 v[36:39], v[144:147], v[186:189], v[36:39]
	v_mfma_f32_16x16x32_bf16 v[32:35], v[168:171], v[186:189], v[32:35]
	v_mfma_f32_16x16x32_bf16 v[20:23], v[144:147], v[202:205], v[20:23]
	v_mfma_f32_16x16x32_bf16 v[16:19], v[168:171], v[202:205], v[16:19]
	v_mfma_f32_16x16x32_bf16 v[4:7], v[144:147], v[214:217], v[4:7]
	v_mfma_f32_16x16x32_bf16 v[0:3], v[168:171], v[214:217], v[0:3]
	v_mfma_f32_16x16x32_bf16 v[52:55], v[148:151], v[182:185], v[52:55]
	v_mfma_f32_16x16x32_bf16 v[48:51], v[174:177], v[182:185], v[48:51]
	v_mfma_f32_16x16x32_bf16 v[36:39], v[148:151], v[198:201], v[36:39]
	v_mfma_f32_16x16x32_bf16 v[32:35], v[174:177], v[198:201], v[32:35]
	v_mfma_f32_16x16x32_bf16 v[20:23], v[148:151], v[210:213], v[20:23]
	v_mfma_f32_16x16x32_bf16 v[16:19], v[174:177], v[210:213], v[16:19]
	v_mfma_f32_16x16x32_bf16 v[4:7], v[148:151], v[218:221], v[4:7]
	v_mfma_f32_16x16x32_bf16 v[0:3], v[174:177], v[218:221], v[0:3]
	s_setprio 0
	s_barrier
	s_add_i32 s62, s62, 2
	s_add_u32 s60, s60, 0x100
	s_addc_u32 s61, s61, 0
	s_cmp_gt_u32 s62, 41
	s_mov_b64 s[36:37], s[38:39]
	s_cbranch_scc1 .Lkexit_3
	v_add_u32_e32 v248, 0x18000, v192
	v_add_u32_e32 v249, 0x1c000, v192
.LBB0_741:
	ds_read_b128 v[128:131], v194
	ds_read_b128 v[132:135], v194 offset:1024
	ds_read_b128 v[136:139], v194 offset:2048
	ds_read_b128 v[140:143], v194 offset:3072
	ds_read_b128 v[144:147], v195
	ds_read_b128 v[148:151], v195 offset:1024
	ds_read_b128 v[168:171], v195 offset:2048
	ds_read_b128 v[174:177], v195 offset:3072
	s_add_u32 s38, s36, 0x100
	s_addc_u32 s39, s37, 0
	s_cmp_eq_u32 s62, 40
	s_cselect_b32 s43, s11, s39
	s_cselect_b32 s42, s10, s38
	s_cselect_b32 s41, s25, s61
	s_cselect_b32 s40, s24, s60
	s_add_i32 m0, s45, 0xc000
	ds_read_b128 v[178:181], v196
	ds_read_b128 v[182:185], v196 offset:1024
	ds_read_b128 v[186:189], v196 offset:2048
	ds_read_b128 v[198:201], v196 offset:3072
	ds_read_b128 v[202:205], v196 offset:4096
	ds_read_b128 v[210:213], v196 offset:5120
	ds_read_b128 v[214:217], v196 offset:6144
	ds_read_b128 v[218:221], v196 offset:7168
	global_load_lds_dwordx4 v160, s[36:37]
	s_add_i32 m0, s45, 0xe000
	s_nop 0
	global_load_lds_dwordx4 v162, s[36:37]
	s_waitcnt vmcnt(8)
	s_waitcnt lgkmcnt(0)
	s_barrier
	s_setprio 1
	s_waitcnt lgkmcnt(0)
	v_mfma_f32_16x16x32_bf16 v[124:127], v[128:131], v[178:181], v[124:127]
	v_mfma_f32_16x16x32_bf16 v[120:123], v[136:139], v[178:181], v[120:123]
	v_mfma_f32_16x16x32_bf16 v[108:111], v[128:131], v[186:189], v[108:111]
	v_mfma_f32_16x16x32_bf16 v[104:107], v[136:139], v[186:189], v[104:107]
	v_mfma_f32_16x16x32_bf16 v[92:95], v[128:131], v[202:205], v[92:95]
	v_mfma_f32_16x16x32_bf16 v[88:91], v[136:139], v[202:205], v[88:91]
	v_mfma_f32_16x16x32_bf16 v[76:79], v[128:131], v[214:217], v[76:79]
	v_mfma_f32_16x16x32_bf16 v[72:75], v[136:139], v[214:217], v[72:75]
	v_mfma_f32_16x16x32_bf16 v[124:127], v[132:135], v[182:185], v[124:127]
	v_mfma_f32_16x16x32_bf16 v[120:123], v[140:143], v[182:185], v[120:123]
	v_mfma_f32_16x16x32_bf16 v[108:111], v[132:135], v[198:201], v[108:111]
	v_mfma_f32_16x16x32_bf16 v[104:107], v[140:143], v[198:201], v[104:107]
	v_mfma_f32_16x16x32_bf16 v[92:95], v[132:135], v[210:213], v[92:95]
	v_mfma_f32_16x16x32_bf16 v[88:91], v[140:143], v[210:213], v[88:91]
	v_mfma_f32_16x16x32_bf16 v[76:79], v[132:135], v[218:221], v[76:79]
	v_mfma_f32_16x16x32_bf16 v[72:75], v[140:143], v[218:221], v[72:75]
	v_mfma_f32_16x16x32_bf16 v[116:119], v[144:147], v[178:181], v[116:119]
	v_mfma_f32_16x16x32_bf16 v[112:115], v[168:171], v[178:181], v[112:115]
	v_mfma_f32_16x16x32_bf16 v[100:103], v[144:147], v[186:189], v[100:103]
	v_mfma_f32_16x16x32_bf16 v[96:99], v[168:171], v[186:189], v[96:99]
	v_mfma_f32_16x16x32_bf16 v[84:87], v[144:147], v[202:205], v[84:87]
	v_mfma_f32_16x16x32_bf16 v[80:83], v[168:171], v[202:205], v[80:83]
	v_mfma_f32_16x16x32_bf16 v[68:71], v[144:147], v[214:217], v[68:71]
	v_mfma_f32_16x16x32_bf16 v[64:67], v[168:171], v[214:217], v[64:67]
	v_mfma_f32_16x16x32_bf16 v[116:119], v[148:151], v[182:185], v[116:119]
	v_mfma_f32_16x16x32_bf16 v[112:115], v[174:177], v[182:185], v[112:115]
	v_mfma_f32_16x16x32_bf16 v[100:103], v[148:151], v[198:201], v[100:103]
	v_mfma_f32_16x16x32_bf16 v[96:99], v[174:177], v[198:201], v[96:99]
	v_mfma_f32_16x16x32_bf16 v[84:87], v[148:151], v[210:213], v[84:87]
	v_mfma_f32_16x16x32_bf16 v[80:83], v[174:177], v[210:213], v[80:83]
	v_mfma_f32_16x16x32_bf16 v[68:71], v[148:151], v[218:221], v[68:71]
	v_mfma_f32_16x16x32_bf16 v[64:67], v[174:177], v[218:221], v[64:67]
	s_setprio 0
	s_barrier
	s_add_u32 s98, s40, s20
	s_addc_u32 s99, s41, s21
	s_add_u32 s100, s42, s20
	s_addc_u32 s101, s43, s21
	s_add_i32 s36, s54, s44
	s_mov_b32 m0, s36
	ds_read_b128 v[178:181], v196 offset:16384
	ds_read_b128 v[182:185], v196 offset:17408
	ds_read_b128 v[186:189], v196 offset:18432
	ds_read_b128 v[198:201], v196 offset:19456
	ds_read_b128 v[202:205], v196 offset:20480
	ds_read_b128 v[210:213], v196 offset:21504
	ds_read_b128 v[214:217], v196 offset:22528
	ds_read_b128 v[218:221], v196 offset:23552
	global_load_lds_dwordx4 v154, s[40:41]
	s_add_i32 m0, s36, 0x2000
	s_add_u32 s36, s40, 0xb0000
	s_addc_u32 s37, s41, 0
	s_add_i32 s63, s55, s44
	global_load_lds_dwordx4 v158, s[40:41]
	s_mov_b32 m0, s63
	s_nop 0
	global_load_lds_dwordx4 v154, s[36:37]
	s_add_i32 m0, s63, 0x2000
	s_nop 0
	global_load_lds_dwordx4 v158, s[36:37]
	s_mov_b32 m0, s45
	s_nop 0
	global_load_lds_dwordx4 v152, s[42:43]
	s_mov_b32 m0, s46
	s_nop 0
	global_load_lds_dwordx4 v156, s[42:43]
	s_waitcnt vmcnt(8)
	s_waitcnt lgkmcnt(0)
	s_barrier
	s_setprio 1
	s_waitcnt lgkmcnt(0)
	v_mfma_f32_16x16x32_bf16 v[60:63], v[128:131], v[178:181], v[60:63]
	v_mfma_f32_16x16x32_bf16 v[56:59], v[136:139], v[178:181], v[56:59]
	v_mfma_f32_16x16x32_bf16 v[44:47], v[128:131], v[186:189], v[44:47]
	v_mfma_f32_16x16x32_bf16 v[40:43], v[136:139], v[186:189], v[40:43]
	v_mfma_f32_16x16x32_bf16 v[28:31], v[128:131], v[202:205], v[28:31]
	v_mfma_f32_16x16x32_bf16 v[24:27], v[136:139], v[202:205], v[24:27]
	v_mfma_f32_16x16x32_bf16 v[12:15], v[128:131], v[214:217], v[12:15]
	v_mfma_f32_16x16x32_bf16 v[8:11], v[136:139], v[214:217], v[8:11]
	v_mfma_f32_16x16x32_bf16 v[60:63], v[132:135], v[182:185], v[60:63]
	v_mfma_f32_16x16x32_bf16 v[56:59], v[140:143], v[182:185], v[56:59]
	v_mfma_f32_16x16x32_bf16 v[44:47], v[132:135], v[198:201], v[44:47]
	v_mfma_f32_16x16x32_bf16 v[40:43], v[140:143], v[198:201], v[40:43]
	v_mfma_f32_16x16x32_bf16 v[28:31], v[132:135], v[210:213], v[28:31]
	v_mfma_f32_16x16x32_bf16 v[24:27], v[140:143], v[210:213], v[24:27]
	v_mfma_f32_16x16x32_bf16 v[12:15], v[132:135], v[218:221], v[12:15]
	v_mfma_f32_16x16x32_bf16 v[8:11], v[140:143], v[218:221], v[8:11]
	v_mfma_f32_16x16x32_bf16 v[52:55], v[144:147], v[178:181], v[52:55]
	v_mfma_f32_16x16x32_bf16 v[48:51], v[168:171], v[178:181], v[48:51]
	v_mfma_f32_16x16x32_bf16 v[36:39], v[144:147], v[186:189], v[36:39]
	v_mfma_f32_16x16x32_bf16 v[32:35], v[168:171], v[186:189], v[32:35]
	v_mfma_f32_16x16x32_bf16 v[20:23], v[144:147], v[202:205], v[20:23]
	v_mfma_f32_16x16x32_bf16 v[16:19], v[168:171], v[202:205], v[16:19]
	v_mfma_f32_16x16x32_bf16 v[4:7], v[144:147], v[214:217], v[4:7]
	v_mfma_f32_16x16x32_bf16 v[0:3], v[168:171], v[214:217], v[0:3]
	v_mfma_f32_16x16x32_bf16 v[52:55], v[148:151], v[182:185], v[52:55]
	v_mfma_f32_16x16x32_bf16 v[48:51], v[174:177], v[182:185], v[48:51]
	v_mfma_f32_16x16x32_bf16 v[36:39], v[148:151], v[198:201], v[36:39]
	v_mfma_f32_16x16x32_bf16 v[32:35], v[174:177], v[198:201], v[32:35]
	v_mfma_f32_16x16x32_bf16 v[20:23], v[148:151], v[210:213], v[20:23]
	v_mfma_f32_16x16x32_bf16 v[16:19], v[174:177], v[210:213], v[16:19]
	v_mfma_f32_16x16x32_bf16 v[4:7], v[148:151], v[218:221], v[4:7]
	v_mfma_f32_16x16x32_bf16 v[0:3], v[174:177], v[218:221], v[0:3]
	s_setprio 0
	s_barrier
	s_add_i32 s63, 0, 0x18000
	s_add_i32 s64, 0, 0x1c000
	ds_read_b128 v[128:131], v248
	ds_read_b128 v[132:135], v248 offset:1024
	ds_read_b128 v[136:139], v248 offset:2048
	ds_read_b128 v[140:143], v248 offset:3072
	ds_read_b128 v[144:147], v249
	ds_read_b128 v[148:151], v249 offset:1024
	ds_read_b128 v[168:171], v249 offset:2048
	ds_read_b128 v[174:177], v249 offset:3072
	s_add_u32 s36, s42, 0xb0000
	s_addc_u32 s37, s43, 0
	s_mov_b32 m0, s47
	ds_read_b128 v[178:181], v196 offset:32768
	ds_read_b128 v[182:185], v196 offset:33792
	ds_read_b128 v[186:189], v196 offset:34816
	ds_read_b128 v[198:201], v196 offset:35840
	ds_read_b128 v[202:205], v196 offset:36864
	ds_read_b128 v[210:213], v196 offset:37888
	ds_read_b128 v[214:217], v196 offset:38912
	ds_read_b128 v[218:221], v196 offset:39936
	global_load_lds_dwordx4 v152, s[36:37]
	s_mov_b32 m0, s48
	s_nop 0
	global_load_lds_dwordx4 v156, s[36:37]
	s_waitcnt vmcnt(8)
	s_waitcnt lgkmcnt(0)
	s_barrier
	s_setprio 1
	s_waitcnt lgkmcnt(0)
	v_mfma_f32_16x16x32_bf16 v[124:127], v[128:131], v[178:181], v[124:127]
	v_mfma_f32_16x16x32_bf16 v[120:123], v[136:139], v[178:181], v[120:123]
	v_mfma_f32_16x16x32_bf16 v[108:111], v[128:131], v[186:189], v[108:111]
	v_mfma_f32_16x16x32_bf16 v[104:107], v[136:139], v[186:189], v[104:107]
	v_mfma_f32_16x16x32_bf16 v[92:95], v[128:131], v[202:205], v[92:95]
	v_mfma_f32_16x16x32_bf16 v[88:91], v[136:139], v[202:205], v[88:91]
	v_mfma_f32_16x16x32_bf16 v[76:79], v[128:131], v[214:217], v[76:79]
	v_mfma_f32_16x16x32_bf16 v[72:75], v[136:139], v[214:217], v[72:75]
	v_mfma_f32_16x16x32_bf16 v[124:127], v[132:135], v[182:185], v[124:127]
	v_mfma_f32_16x16x32_bf16 v[120:123], v[140:143], v[182:185], v[120:123]
	v_mfma_f32_16x16x32_bf16 v[108:111], v[132:135], v[198:201], v[108:111]
	v_mfma_f32_16x16x32_bf16 v[104:107], v[140:143], v[198:201], v[104:107]
	v_mfma_f32_16x16x32_bf16 v[92:95], v[132:135], v[210:213], v[92:95]
	v_mfma_f32_16x16x32_bf16 v[88:91], v[140:143], v[210:213], v[88:91]
	v_mfma_f32_16x16x32_bf16 v[76:79], v[132:135], v[218:221], v[76:79]
	v_mfma_f32_16x16x32_bf16 v[72:75], v[140:143], v[218:221], v[72:75]
	v_mfma_f32_16x16x32_bf16 v[116:119], v[144:147], v[178:181], v[116:119]
	v_mfma_f32_16x16x32_bf16 v[112:115], v[168:171], v[178:181], v[112:115]
	v_mfma_f32_16x16x32_bf16 v[100:103], v[144:147], v[186:189], v[100:103]
	v_mfma_f32_16x16x32_bf16 v[96:99], v[168:171], v[186:189], v[96:99]
	v_mfma_f32_16x16x32_bf16 v[84:87], v[144:147], v[202:205], v[84:87]
	v_mfma_f32_16x16x32_bf16 v[80:83], v[168:171], v[202:205], v[80:83]
	v_mfma_f32_16x16x32_bf16 v[68:71], v[144:147], v[214:217], v[68:71]
	v_mfma_f32_16x16x32_bf16 v[64:67], v[168:171], v[214:217], v[64:67]
	v_mfma_f32_16x16x32_bf16 v[116:119], v[148:151], v[182:185], v[116:119]
	v_mfma_f32_16x16x32_bf16 v[112:115], v[174:177], v[182:185], v[112:115]
	v_mfma_f32_16x16x32_bf16 v[100:103], v[148:151], v[198:201], v[100:103]
	v_mfma_f32_16x16x32_bf16 v[96:99], v[174:177], v[198:201], v[96:99]
	v_mfma_f32_16x16x32_bf16 v[84:87], v[148:151], v[210:213], v[84:87]
	v_mfma_f32_16x16x32_bf16 v[80:83], v[174:177], v[210:213], v[80:83]
	v_mfma_f32_16x16x32_bf16 v[68:71], v[148:151], v[218:221], v[68:71]
	v_mfma_f32_16x16x32_bf16 v[64:67], v[174:177], v[218:221], v[64:67]
	s_setprio 0
	s_barrier
	s_add_i32 s36, s63, s44
	s_mov_b32 m0, s36
	ds_read_b128 v[178:181], v196 offset:49152
	ds_read_b128 v[182:185], v196 offset:50176
	ds_read_b128 v[186:189], v196 offset:51200
	ds_read_b128 v[198:201], v196 offset:52224
	ds_read_b128 v[202:205], v196 offset:53248
	ds_read_b128 v[210:213], v196 offset:54272
	ds_read_b128 v[214:217], v196 offset:55296
	ds_read_b128 v[218:221], v196 offset:56320
	global_load_lds_dwordx4 v154, s[98:99]
	s_add_i32 m0, s36, 0x2000
	s_add_u32 s36, s40, 0xb0080
	s_addc_u32 s37, s41, 0
	s_add_i32 s40, s64, s44
	global_load_lds_dwordx4 v158, s[98:99]
	s_mov_b32 m0, s40
	s_nop 0
	global_load_lds_dwordx4 v154, s[36:37]
	s_add_i32 m0, s40, 0x2000
	s_nop 0
	global_load_lds_dwordx4 v158, s[36:37]
	s_mov_b32 m0, s50
	s_nop 0
	global_load_lds_dwordx4 v152, s[100:101]
	s_mov_b32 m0, s51
	s_nop 0
	global_load_lds_dwordx4 v156, s[100:101]
	s_waitcnt vmcnt(8)
	s_waitcnt lgkmcnt(0)
	s_barrier
	s_setprio 1
	s_waitcnt lgkmcnt(0)
	v_mfma_f32_16x16x32_bf16 v[60:63], v[128:131], v[178:181], v[60:63]
	v_mfma_f32_16x16x32_bf16 v[56:59], v[136:139], v[178:181], v[56:59]
	v_mfma_f32_16x16x32_bf16 v[44:47], v[128:131], v[186:189], v[44:47]
	v_mfma_f32_16x16x32_bf16 v[40:43], v[136:139], v[186:189], v[40:43]
	v_mfma_f32_16x16x32_bf16 v[28:31], v[128:131], v[202:205], v[28:31]
	v_mfma_f32_16x16x32_bf16 v[24:27], v[136:139], v[202:205], v[24:27]
	v_mfma_f32_16x16x32_bf16 v[12:15], v[128:131], v[214:217], v[12:15]
	v_mfma_f32_16x16x32_bf16 v[8:11], v[136:139], v[214:217], v[8:11]
	v_mfma_f32_16x16x32_bf16 v[60:63], v[132:135], v[182:185], v[60:63]
	v_mfma_f32_16x16x32_bf16 v[56:59], v[140:143], v[182:185], v[56:59]
	v_mfma_f32_16x16x32_bf16 v[44:47], v[132:135], v[198:201], v[44:47]
	v_mfma_f32_16x16x32_bf16 v[40:43], v[140:143], v[198:201], v[40:43]
	v_mfma_f32_16x16x32_bf16 v[28:31], v[132:135], v[210:213], v[28:31]
	v_mfma_f32_16x16x32_bf16 v[24:27], v[140:143], v[210:213], v[24:27]
	v_mfma_f32_16x16x32_bf16 v[12:15], v[132:135], v[218:221], v[12:15]
	v_mfma_f32_16x16x32_bf16 v[8:11], v[140:143], v[218:221], v[8:11]
	v_mfma_f32_16x16x32_bf16 v[52:55], v[144:147], v[178:181], v[52:55]
	v_mfma_f32_16x16x32_bf16 v[48:51], v[168:171], v[178:181], v[48:51]
	v_mfma_f32_16x16x32_bf16 v[36:39], v[144:147], v[186:189], v[36:39]
	v_mfma_f32_16x16x32_bf16 v[32:35], v[168:171], v[186:189], v[32:35]
	v_mfma_f32_16x16x32_bf16 v[20:23], v[144:147], v[202:205], v[20:23]
	v_mfma_f32_16x16x32_bf16 v[16:19], v[168:171], v[202:205], v[16:19]
	v_mfma_f32_16x16x32_bf16 v[4:7], v[144:147], v[214:217], v[4:7]
	v_mfma_f32_16x16x32_bf16 v[0:3], v[168:171], v[214:217], v[0:3]
	v_mfma_f32_16x16x32_bf16 v[52:55], v[148:151], v[182:185], v[52:55]
	v_mfma_f32_16x16x32_bf16 v[48:51], v[174:177], v[182:185], v[48:51]
	v_mfma_f32_16x16x32_bf16 v[36:39], v[148:151], v[198:201], v[36:39]
	v_mfma_f32_16x16x32_bf16 v[32:35], v[174:177], v[198:201], v[32:35]
	v_mfma_f32_16x16x32_bf16 v[20:23], v[148:151], v[210:213], v[20:23]
	v_mfma_f32_16x16x32_bf16 v[16:19], v[174:177], v[210:213], v[16:19]
	v_mfma_f32_16x16x32_bf16 v[4:7], v[148:151], v[218:221], v[4:7]
	v_mfma_f32_16x16x32_bf16 v[0:3], v[174:177], v[218:221], v[0:3]
	s_setprio 0
	s_barrier
	s_add_i32 s62, s62, 2
	s_add_u32 s60, s60, 0x100
	s_addc_u32 s61, s61, 0
	s_cmp_gt_u32 s62, 41
	s_mov_b64 s[36:37], s[38:39]
	s_cbranch_scc0 .LBB0_741

.LBB0_835:
	s_ashr_i32 s29, s28, 31
	s_lshl_b64 s[30:31], s[28:29], 19
	s_add_u32 s30, s12, s30
	s_addc_u32 s31, s13, s31
	s_and_b64 s[34:35], s[4:5], exec
	s_cselect_b32 s29, s31, s41
	s_cselect_b32 s37, s30, s40
	s_ashr_i32 s27, s26, 31
	s_lshl_b64 s[34:35], s[26:27], 19
	s_add_u32 s34, s2, s34
	s_addc_u32 s35, s46, s35
	s_and_b64 s[44:45], s[4:5], exec
	s_cselect_b32 s27, s35, s43
	s_cselect_b32 s39, s34, s42
	s_add_u32 s40, s40, 0x40080
	s_addc_u32 s41, s41, 0
	s_add_u32 s61, s42, 0x100
	s_addc_u32 s62, s43, 0
	s_mov_b32 s63, -2
	ds_read_b128 v[88:91], v235
	ds_read_b128 v[92:95], v235 offset:1024
	ds_read_b128 v[104:107], v235 offset:2048
	ds_read_b128 v[108:111], v235 offset:3072
	ds_read_b128 v[136:139], v236
	ds_read_b128 v[140:143], v236 offset:1024
	ds_read_b128 v[148:151], v236 offset:2048
	ds_read_b128 v[152:155], v236 offset:3072
	s_add_u32 s42, s40, 0xfffc0080
	s_addc_u32 s43, s41, -1
	s_cmp_eq_u32 s63, 12
	s_cselect_b32 s45, s29, s43
	s_cselect_b32 s44, s37, s42
	s_cselect_b32 s43, s27, s62
	s_cselect_b32 s42, s39, s61
	s_add_i32 m0, s48, 0xc000
	ds_read_b128 v[160:163], v237
	ds_read_b128 v[164:167], v237 offset:1024
	ds_read_b128 v[168:171], v237 offset:2048
	ds_read_b128 v[172:175], v237 offset:3072
	ds_read_b128 v[176:179], v237 offset:4096
	ds_read_b128 v[180:183], v237 offset:5120
	ds_read_b128 v[184:187], v237 offset:6144
	ds_read_b128 v[188:191], v237 offset:7168
	global_load_lds_dwordx4 v200, s[40:41]
	s_add_i32 m0, s48, 0xe000
	s_nop 0
	global_load_lds_dwordx4 v202, s[40:41]
	s_waitcnt vmcnt(8)
	s_waitcnt lgkmcnt(0)
	s_barrier
	s_setprio 1
	s_waitcnt lgkmcnt(0)
	v_mfma_f32_16x16x32_bf16 v[124:127], v[88:91], v[160:163], 0
	v_mfma_f32_16x16x32_bf16 v[120:123], v[104:107], v[160:163], 0
	v_mfma_f32_16x16x32_bf16 v[156:159], v[88:91], v[168:171], 0
	v_mfma_f32_16x16x32_bf16 v[144:147], v[104:107], v[168:171], 0
	v_mfma_f32_16x16x32_bf16 v[100:103], v[88:91], v[176:179], 0
	v_mfma_f32_16x16x32_bf16 v[96:99], v[104:107], v[176:179], 0
	v_mfma_f32_16x16x32_bf16 v[76:79], v[88:91], v[184:187], 0
	v_mfma_f32_16x16x32_bf16 v[72:75], v[104:107], v[184:187], 0
	v_mfma_f32_16x16x32_bf16 v[124:127], v[92:95], v[164:167], v[124:127]
	v_mfma_f32_16x16x32_bf16 v[120:123], v[108:111], v[164:167], v[120:123]
	v_mfma_f32_16x16x32_bf16 v[156:159], v[92:95], v[172:175], v[156:159]
	v_mfma_f32_16x16x32_bf16 v[144:147], v[108:111], v[172:175], v[144:147]
	v_mfma_f32_16x16x32_bf16 v[100:103], v[92:95], v[180:183], v[100:103]
	v_mfma_f32_16x16x32_bf16 v[96:99], v[108:111], v[180:183], v[96:99]
	v_mfma_f32_16x16x32_bf16 v[76:79], v[92:95], v[188:191], v[76:79]
	v_mfma_f32_16x16x32_bf16 v[72:75], v[108:111], v[188:191], v[72:75]
	v_mfma_f32_16x16x32_bf16 v[116:119], v[136:139], v[160:163], 0
	v_mfma_f32_16x16x32_bf16 v[112:115], v[148:151], v[160:163], 0
	v_mfma_f32_16x16x32_bf16 v[132:135], v[136:139], v[168:171], 0
	v_mfma_f32_16x16x32_bf16 v[128:131], v[148:151], v[168:171], 0
	v_mfma_f32_16x16x32_bf16 v[84:87], v[136:139], v[176:179], 0
	v_mfma_f32_16x16x32_bf16 v[80:83], v[148:151], v[176:179], 0
	v_mfma_f32_16x16x32_bf16 v[68:71], v[136:139], v[184:187], 0
	v_mfma_f32_16x16x32_bf16 v[64:67], v[148:151], v[184:187], 0
	v_mfma_f32_16x16x32_bf16 v[116:119], v[140:143], v[164:167], v[116:119]
	v_mfma_f32_16x16x32_bf16 v[112:115], v[152:155], v[164:167], v[112:115]
	v_mfma_f32_16x16x32_bf16 v[132:135], v[140:143], v[172:175], v[132:135]
	v_mfma_f32_16x16x32_bf16 v[128:131], v[152:155], v[172:175], v[128:131]
	v_mfma_f32_16x16x32_bf16 v[84:87], v[140:143], v[180:183], v[84:87]
	v_mfma_f32_16x16x32_bf16 v[80:83], v[152:155], v[180:183], v[80:83]
	v_mfma_f32_16x16x32_bf16 v[68:71], v[140:143], v[188:191], v[68:71]
	v_mfma_f32_16x16x32_bf16 v[64:67], v[152:155], v[188:191], v[64:67]
	s_setprio 0
	s_barrier
	s_add_u32 s98, s42, s22
	s_addc_u32 s99, s43, s23
	s_add_u32 s100, s44, s22
	s_addc_u32 s101, s45, s23
	s_add_i32 s64, s59, s47
	s_mov_b32 m0, s64
	ds_read_b128 v[160:163], v237 offset:16384
	ds_read_b128 v[164:167], v237 offset:17408
	ds_read_b128 v[168:171], v237 offset:18432
	ds_read_b128 v[172:175], v237 offset:19456
	ds_read_b128 v[176:179], v237 offset:20480
	ds_read_b128 v[180:183], v237 offset:21504
	ds_read_b128 v[184:187], v237 offset:22528
	ds_read_b128 v[188:191], v237 offset:23552
	global_load_lds_dwordx4 v194, s[42:43]
	s_add_i32 m0, s64, 0x2000
	s_add_u32 s64, s42, 0x40000
	s_addc_u32 s65, s43, 0
	s_add_i32 s66, s60, s47
	global_load_lds_dwordx4 v198, s[42:43]
	s_mov_b32 m0, s66
	s_nop 0
	global_load_lds_dwordx4 v194, s[64:65]
	s_add_i32 m0, s66, 0x2000
	s_nop 0
	global_load_lds_dwordx4 v198, s[64:65]
	s_mov_b32 m0, s48
	s_nop 0
	global_load_lds_dwordx4 v192, s[44:45]
	s_mov_b32 m0, s49
	s_nop 0
	global_load_lds_dwordx4 v196, s[44:45]
	s_waitcnt vmcnt(8)
	s_waitcnt lgkmcnt(0)
	s_barrier
	s_setprio 1
	s_waitcnt lgkmcnt(0)
	v_mfma_f32_16x16x32_bf16 v[60:63], v[88:91], v[160:163], 0
	v_mfma_f32_16x16x32_bf16 v[56:59], v[104:107], v[160:163], 0
	v_mfma_f32_16x16x32_bf16 v[44:47], v[88:91], v[168:171], 0
	v_mfma_f32_16x16x32_bf16 v[40:43], v[104:107], v[168:171], 0
	v_mfma_f32_16x16x32_bf16 v[28:31], v[88:91], v[176:179], 0
	v_mfma_f32_16x16x32_bf16 v[24:27], v[104:107], v[176:179], 0
	v_mfma_f32_16x16x32_bf16 v[12:15], v[88:91], v[184:187], 0
	v_mfma_f32_16x16x32_bf16 v[8:11], v[104:107], v[184:187], 0
	v_mfma_f32_16x16x32_bf16 v[60:63], v[92:95], v[164:167], v[60:63]
	v_mfma_f32_16x16x32_bf16 v[56:59], v[108:111], v[164:167], v[56:59]
	v_mfma_f32_16x16x32_bf16 v[44:47], v[92:95], v[172:175], v[44:47]
	v_mfma_f32_16x16x32_bf16 v[40:43], v[108:111], v[172:175], v[40:43]
	v_mfma_f32_16x16x32_bf16 v[28:31], v[92:95], v[180:183], v[28:31]
	v_mfma_f32_16x16x32_bf16 v[24:27], v[108:111], v[180:183], v[24:27]
	v_mfma_f32_16x16x32_bf16 v[12:15], v[92:95], v[188:191], v[12:15]
	v_mfma_f32_16x16x32_bf16 v[8:11], v[108:111], v[188:191], v[8:11]
	v_mfma_f32_16x16x32_bf16 v[52:55], v[136:139], v[160:163], 0
	v_mfma_f32_16x16x32_bf16 v[48:51], v[148:151], v[160:163], 0
	v_mfma_f32_16x16x32_bf16 v[36:39], v[136:139], v[168:171], 0
	v_mfma_f32_16x16x32_bf16 v[32:35], v[148:151], v[168:171], 0
	v_mfma_f32_16x16x32_bf16 v[20:23], v[136:139], v[176:179], 0
	v_mfma_f32_16x16x32_bf16 v[16:19], v[148:151], v[176:179], 0
	v_mfma_f32_16x16x32_bf16 v[4:7], v[136:139], v[184:187], 0
	v_mfma_f32_16x16x32_bf16 v[0:3], v[148:151], v[184:187], 0
	v_mfma_f32_16x16x32_bf16 v[52:55], v[140:143], v[164:167], v[52:55]
	v_mfma_f32_16x16x32_bf16 v[48:51], v[152:155], v[164:167], v[48:51]
	v_mfma_f32_16x16x32_bf16 v[36:39], v[140:143], v[172:175], v[36:39]
	v_mfma_f32_16x16x32_bf16 v[32:35], v[152:155], v[172:175], v[32:35]
	v_mfma_f32_16x16x32_bf16 v[20:23], v[140:143], v[180:183], v[20:23]
	v_mfma_f32_16x16x32_bf16 v[16:19], v[152:155], v[180:183], v[16:19]
	v_mfma_f32_16x16x32_bf16 v[4:7], v[140:143], v[188:191], v[4:7]
	v_mfma_f32_16x16x32_bf16 v[0:3], v[152:155], v[188:191], v[0:3]
	s_setprio 0
	s_barrier
	s_add_i32 s64, 0, 0x18000
	s_add_i32 s65, 0, 0x1c000
	v_add_u32_e32 v108, s64, v233
	v_add_u32_e32 v152, s65, v233
	ds_read_b128 v[88:91], v108
	ds_read_b128 v[92:95], v108 offset:1024
	ds_read_b128 v[104:107], v108 offset:2048
	ds_read_b128 v[108:111], v108 offset:3072
	ds_read_b128 v[136:139], v152
	ds_read_b128 v[140:143], v152 offset:1024
	ds_read_b128 v[148:151], v152 offset:2048
	ds_read_b128 v[152:155], v152 offset:3072
	s_add_u32 s44, s44, 0x40000
	s_addc_u32 s45, s45, 0
	s_mov_b32 m0, s50
	ds_read_b128 v[160:163], v237 offset:32768
	ds_read_b128 v[164:167], v237 offset:33792
	ds_read_b128 v[168:171], v237 offset:34816
	ds_read_b128 v[172:175], v237 offset:35840
	ds_read_b128 v[176:179], v237 offset:36864
	ds_read_b128 v[180:183], v237 offset:37888
	ds_read_b128 v[184:187], v237 offset:38912
	ds_read_b128 v[188:191], v237 offset:39936
	global_load_lds_dwordx4 v192, s[44:45]
	s_mov_b32 m0, s51
	s_nop 0
	global_load_lds_dwordx4 v196, s[44:45]
	s_waitcnt vmcnt(8)
	s_waitcnt lgkmcnt(0)
	s_barrier
	s_setprio 1
	s_waitcnt lgkmcnt(0)
	v_mfma_f32_16x16x32_bf16 v[124:127], v[88:91], v[160:163], v[124:127]
	v_mfma_f32_16x16x32_bf16 v[120:123], v[104:107], v[160:163], v[120:123]
	v_mfma_f32_16x16x32_bf16 v[156:159], v[88:91], v[168:171], v[156:159]
	v_mfma_f32_16x16x32_bf16 v[144:147], v[104:107], v[168:171], v[144:147]
	v_mfma_f32_16x16x32_bf16 v[100:103], v[88:91], v[176:179], v[100:103]
	v_mfma_f32_16x16x32_bf16 v[96:99], v[104:107], v[176:179], v[96:99]
	v_mfma_f32_16x16x32_bf16 v[76:79], v[88:91], v[184:187], v[76:79]
	v_mfma_f32_16x16x32_bf16 v[72:75], v[104:107], v[184:187], v[72:75]
	v_mfma_f32_16x16x32_bf16 v[124:127], v[92:95], v[164:167], v[124:127]
	v_mfma_f32_16x16x32_bf16 v[120:123], v[108:111], v[164:167], v[120:123]
	v_mfma_f32_16x16x32_bf16 v[156:159], v[92:95], v[172:175], v[156:159]
	v_mfma_f32_16x16x32_bf16 v[144:147], v[108:111], v[172:175], v[144:147]
	v_mfma_f32_16x16x32_bf16 v[100:103], v[92:95], v[180:183], v[100:103]
	v_mfma_f32_16x16x32_bf16 v[96:99], v[108:111], v[180:183], v[96:99]
	v_mfma_f32_16x16x32_bf16 v[76:79], v[92:95], v[188:191], v[76:79]
	v_mfma_f32_16x16x32_bf16 v[72:75], v[108:111], v[188:191], v[72:75]
	v_mfma_f32_16x16x32_bf16 v[116:119], v[136:139], v[160:163], v[116:119]
	v_mfma_f32_16x16x32_bf16 v[112:115], v[148:151], v[160:163], v[112:115]
	v_mfma_f32_16x16x32_bf16 v[132:135], v[136:139], v[168:171], v[132:135]
	v_mfma_f32_16x16x32_bf16 v[128:131], v[148:151], v[168:171], v[128:131]
	v_mfma_f32_16x16x32_bf16 v[84:87], v[136:139], v[176:179], v[84:87]
	v_mfma_f32_16x16x32_bf16 v[80:83], v[148:151], v[176:179], v[80:83]
	v_mfma_f32_16x16x32_bf16 v[68:71], v[136:139], v[184:187], v[68:71]
	v_mfma_f32_16x16x32_bf16 v[64:67], v[148:151], v[184:187], v[64:67]
	v_mfma_f32_16x16x32_bf16 v[116:119], v[140:143], v[164:167], v[116:119]
	v_mfma_f32_16x16x32_bf16 v[112:115], v[152:155], v[164:167], v[112:115]
	v_mfma_f32_16x16x32_bf16 v[132:135], v[140:143], v[172:175], v[132:135]
	v_mfma_f32_16x16x32_bf16 v[128:131], v[152:155], v[172:175], v[128:131]
	v_mfma_f32_16x16x32_bf16 v[84:87], v[140:143], v[180:183], v[84:87]
	v_mfma_f32_16x16x32_bf16 v[80:83], v[152:155], v[180:183], v[80:83]
	v_mfma_f32_16x16x32_bf16 v[68:71], v[140:143], v[188:191], v[68:71]
	v_mfma_f32_16x16x32_bf16 v[64:67], v[152:155], v[188:191], v[64:67]
	s_setprio 0
	s_barrier
	s_add_i32 s44, s64, s47
	s_mov_b32 m0, s44
	ds_read_b128 v[160:163], v237 offset:49152
	ds_read_b128 v[164:167], v237 offset:50176
	ds_read_b128 v[168:171], v237 offset:51200
	ds_read_b128 v[172:175], v237 offset:52224
	ds_read_b128 v[176:179], v237 offset:53248
	ds_read_b128 v[180:183], v237 offset:54272
	ds_read_b128 v[184:187], v237 offset:55296
	ds_read_b128 v[188:191], v237 offset:56320
	global_load_lds_dwordx4 v194, s[98:99]
	s_add_i32 m0, s44, 0x2000
	s_add_u32 s42, s42, 0x40080
	s_addc_u32 s43, s43, 0
	s_add_i32 s44, s65, s47
	global_load_lds_dwordx4 v198, s[98:99]
	s_mov_b32 m0, s44
	s_nop 0
	global_load_lds_dwordx4 v194, s[42:43]
	s_add_i32 m0, s44, 0x2000
	s_nop 0
	global_load_lds_dwordx4 v198, s[42:43]
	s_mov_b32 m0, s55
	s_nop 0
	global_load_lds_dwordx4 v192, s[100:101]
	s_mov_b32 m0, s56
	s_nop 0
	global_load_lds_dwordx4 v196, s[100:101]
	s_waitcnt vmcnt(8)
	s_waitcnt lgkmcnt(0)
	s_barrier
	s_setprio 1
	s_waitcnt lgkmcnt(0)
	v_mfma_f32_16x16x32_bf16 v[60:63], v[88:91], v[160:163], v[60:63]
	v_mfma_f32_16x16x32_bf16 v[56:59], v[104:107], v[160:163], v[56:59]
	v_mfma_f32_16x16x32_bf16 v[44:47], v[88:91], v[168:171], v[44:47]
	v_mfma_f32_16x16x32_bf16 v[40:43], v[104:107], v[168:171], v[40:43]
	v_mfma_f32_16x16x32_bf16 v[28:31], v[88:91], v[176:179], v[28:31]
	v_mfma_f32_16x16x32_bf16 v[24:27], v[104:107], v[176:179], v[24:27]
	v_mfma_f32_16x16x32_bf16 v[12:15], v[88:91], v[184:187], v[12:15]
	v_mfma_f32_16x16x32_bf16 v[8:11], v[104:107], v[184:187], v[8:11]
	v_mfma_f32_16x16x32_bf16 v[60:63], v[92:95], v[164:167], v[60:63]
	v_mfma_f32_16x16x32_bf16 v[56:59], v[108:111], v[164:167], v[56:59]
	v_mfma_f32_16x16x32_bf16 v[44:47], v[92:95], v[172:175], v[44:47]
	v_mfma_f32_16x16x32_bf16 v[40:43], v[108:111], v[172:175], v[40:43]
	v_mfma_f32_16x16x32_bf16 v[28:31], v[92:95], v[180:183], v[28:31]
	v_mfma_f32_16x16x32_bf16 v[24:27], v[108:111], v[180:183], v[24:27]
	v_mfma_f32_16x16x32_bf16 v[12:15], v[92:95], v[188:191], v[12:15]
	v_mfma_f32_16x16x32_bf16 v[8:11], v[108:111], v[188:191], v[8:11]
	v_mfma_f32_16x16x32_bf16 v[52:55], v[136:139], v[160:163], v[52:55]
	v_mfma_f32_16x16x32_bf16 v[48:51], v[148:151], v[160:163], v[48:51]
	v_mfma_f32_16x16x32_bf16 v[36:39], v[136:139], v[168:171], v[36:39]
	v_mfma_f32_16x16x32_bf16 v[32:35], v[148:151], v[168:171], v[32:35]
	v_mfma_f32_16x16x32_bf16 v[20:23], v[136:139], v[176:179], v[20:23]
	v_mfma_f32_16x16x32_bf16 v[16:19], v[148:151], v[176:179], v[16:19]
	v_mfma_f32_16x16x32_bf16 v[4:7], v[136:139], v[184:187], v[4:7]
	v_mfma_f32_16x16x32_bf16 v[0:3], v[148:151], v[184:187], v[0:3]
	v_mfma_f32_16x16x32_bf16 v[52:55], v[140:143], v[164:167], v[52:55]
	v_mfma_f32_16x16x32_bf16 v[48:51], v[152:155], v[164:167], v[48:51]
	v_mfma_f32_16x16x32_bf16 v[36:39], v[140:143], v[172:175], v[36:39]
	v_mfma_f32_16x16x32_bf16 v[32:35], v[152:155], v[172:175], v[32:35]
	v_mfma_f32_16x16x32_bf16 v[20:23], v[140:143], v[180:183], v[20:23]
	v_mfma_f32_16x16x32_bf16 v[16:19], v[152:155], v[180:183], v[16:19]
	v_mfma_f32_16x16x32_bf16 v[4:7], v[140:143], v[188:191], v[4:7]
	v_mfma_f32_16x16x32_bf16 v[0:3], v[152:155], v[188:191], v[0:3]
	s_setprio 0
	s_barrier
	s_add_i32 s63, s63, 2
	s_add_u32 s40, s40, 0x100
	s_addc_u32 s41, s41, 0
	s_add_u32 s61, s61, 0x100
	s_addc_u32 s62, s62, 0
	s_cmp_gt_u32 s63, 13
	s_cbranch_scc1 .Lkexit_4
	v_add_u32_e32 v248, 0x18000, v233
	v_add_u32_e32 v249, 0x1c000, v233
.LBB0_836:
	ds_read_b128 v[88:91], v235
	ds_read_b128 v[92:95], v235 offset:1024
	ds_read_b128 v[104:107], v235 offset:2048
	ds_read_b128 v[108:111], v235 offset:3072
	ds_read_b128 v[136:139], v236
	ds_read_b128 v[140:143], v236 offset:1024
	ds_read_b128 v[148:151], v236 offset:2048
	ds_read_b128 v[152:155], v236 offset:3072
	s_add_u32 s42, s40, 0xfffc0080
	s_addc_u32 s43, s41, -1
	s_cmp_eq_u32 s63, 12
	s_cselect_b32 s45, s29, s43
	s_cselect_b32 s44, s37, s42
	s_cselect_b32 s43, s27, s62
	s_cselect_b32 s42, s39, s61
	s_add_i32 m0, s48, 0xc000
	ds_read_b128 v[160:163], v237
	ds_read_b128 v[164:167], v237 offset:1024
	ds_read_b128 v[168:171], v237 offset:2048
	ds_read_b128 v[172:175], v237 offset:3072
	ds_read_b128 v[176:179], v237 offset:4096
	ds_read_b128 v[180:183], v237 offset:5120
	ds_read_b128 v[184:187], v237 offset:6144
	ds_read_b128 v[188:191], v237 offset:7168
	global_load_lds_dwordx4 v200, s[40:41]
	s_add_i32 m0, s48, 0xe000
	s_nop 0
	global_load_lds_dwordx4 v202, s[40:41]
	s_waitcnt vmcnt(8)
	s_waitcnt lgkmcnt(0)
	s_barrier
	s_setprio 1
	s_waitcnt lgkmcnt(0)
	v_mfma_f32_16x16x32_bf16 v[124:127], v[88:91], v[160:163], v[124:127]
	v_mfma_f32_16x16x32_bf16 v[120:123], v[104:107], v[160:163], v[120:123]
	v_mfma_f32_16x16x32_bf16 v[156:159], v[88:91], v[168:171], v[156:159]
	v_mfma_f32_16x16x32_bf16 v[144:147], v[104:107], v[168:171], v[144:147]
	v_mfma_f32_16x16x32_bf16 v[100:103], v[88:91], v[176:179], v[100:103]
	v_mfma_f32_16x16x32_bf16 v[96:99], v[104:107], v[176:179], v[96:99]
	v_mfma_f32_16x16x32_bf16 v[76:79], v[88:91], v[184:187], v[76:79]
	v_mfma_f32_16x16x32_bf16 v[72:75], v[104:107], v[184:187], v[72:75]
	v_mfma_f32_16x16x32_bf16 v[124:127], v[92:95], v[164:167], v[124:127]
	v_mfma_f32_16x16x32_bf16 v[120:123], v[108:111], v[164:167], v[120:123]
	v_mfma_f32_16x16x32_bf16 v[156:159], v[92:95], v[172:175], v[156:159]
	v_mfma_f32_16x16x32_bf16 v[144:147], v[108:111], v[172:175], v[144:147]
	v_mfma_f32_16x16x32_bf16 v[100:103], v[92:95], v[180:183], v[100:103]
	v_mfma_f32_16x16x32_bf16 v[96:99], v[108:111], v[180:183], v[96:99]
	v_mfma_f32_16x16x32_bf16 v[76:79], v[92:95], v[188:191], v[76:79]
	v_mfma_f32_16x16x32_bf16 v[72:75], v[108:111], v[188:191], v[72:75]
	v_mfma_f32_16x16x32_bf16 v[116:119], v[136:139], v[160:163], v[116:119]
	v_mfma_f32_16x16x32_bf16 v[112:115], v[148:151], v[160:163], v[112:115]
	v_mfma_f32_16x16x32_bf16 v[132:135], v[136:139], v[168:171], v[132:135]
	v_mfma_f32_16x16x32_bf16 v[128:131], v[148:151], v[168:171], v[128:131]
	v_mfma_f32_16x16x32_bf16 v[84:87], v[136:139], v[176:179], v[84:87]
	v_mfma_f32_16x16x32_bf16 v[80:83], v[148:151], v[176:179], v[80:83]
	v_mfma_f32_16x16x32_bf16 v[68:71], v[136:139], v[184:187], v[68:71]
	v_mfma_f32_16x16x32_bf16 v[64:67], v[148:151], v[184:187], v[64:67]
	v_mfma_f32_16x16x32_bf16 v[116:119], v[140:143], v[164:167], v[116:119]
	v_mfma_f32_16x16x32_bf16 v[112:115], v[152:155], v[164:167], v[112:115]
	v_mfma_f32_16x16x32_bf16 v[132:135], v[140:143], v[172:175], v[132:135]
	v_mfma_f32_16x16x32_bf16 v[128:131], v[152:155], v[172:175], v[128:131]
	v_mfma_f32_16x16x32_bf16 v[84:87], v[140:143], v[180:183], v[84:87]
	v_mfma_f32_16x16x32_bf16 v[80:83], v[152:155], v[180:183], v[80:83]
	v_mfma_f32_16x16x32_bf16 v[68:71], v[140:143], v[188:191], v[68:71]
	v_mfma_f32_16x16x32_bf16 v[64:67], v[152:155], v[188:191], v[64:67]
	s_setprio 0
	s_barrier
	s_add_u32 s98, s42, s22
	s_addc_u32 s99, s43, s23
	s_add_u32 s100, s44, s22
	s_addc_u32 s101, s45, s23
	s_add_i32 s64, s59, s47
	s_mov_b32 m0, s64
	ds_read_b128 v[160:163], v237 offset:16384
	ds_read_b128 v[164:167], v237 offset:17408
	ds_read_b128 v[168:171], v237 offset:18432
	ds_read_b128 v[172:175], v237 offset:19456
	ds_read_b128 v[176:179], v237 offset:20480
	ds_read_b128 v[180:183], v237 offset:21504
	ds_read_b128 v[184:187], v237 offset:22528
	ds_read_b128 v[188:191], v237 offset:23552
	global_load_lds_dwordx4 v194, s[42:43]
	s_add_i32 m0, s64, 0x2000
	s_add_u32 s64, s42, 0x40000
	s_addc_u32 s65, s43, 0
	s_add_i32 s66, s60, s47
	global_load_lds_dwordx4 v198, s[42:43]
	s_mov_b32 m0, s66
	s_nop 0
	global_load_lds_dwordx4 v194, s[64:65]
	s_add_i32 m0, s66, 0x2000
	s_nop 0
	global_load_lds_dwordx4 v198, s[64:65]
	s_mov_b32 m0, s48
	s_nop 0
	global_load_lds_dwordx4 v192, s[44:45]
	s_mov_b32 m0, s49
	s_nop 0
	global_load_lds_dwordx4 v196, s[44:45]
	s_waitcnt vmcnt(8)
	s_waitcnt lgkmcnt(0)
	s_barrier
	s_setprio 1
	s_waitcnt lgkmcnt(0)
	v_mfma_f32_16x16x32_bf16 v[60:63], v[88:91], v[160:163], v[60:63]
	v_mfma_f32_16x16x32_bf16 v[56:59], v[104:107], v[160:163], v[56:59]
	v_mfma_f32_16x16x32_bf16 v[44:47], v[88:91], v[168:171], v[44:47]
	v_mfma_f32_16x16x32_bf16 v[40:43], v[104:107], v[168:171], v[40:43]
	v_mfma_f32_16x16x32_bf16 v[28:31], v[88:91], v[176:179], v[28:31]
	v_mfma_f32_16x16x32_bf16 v[24:27], v[104:107], v[176:179], v[24:27]
	v_mfma_f32_16x16x32_bf16 v[12:15], v[88:91], v[184:187], v[12:15]
	v_mfma_f32_16x16x32_bf16 v[8:11], v[104:107], v[184:187], v[8:11]
	v_mfma_f32_16x16x32_bf16 v[60:63], v[92:95], v[164:167], v[60:63]
	v_mfma_f32_16x16x32_bf16 v[56:59], v[108:111], v[164:167], v[56:59]
	v_mfma_f32_16x16x32_bf16 v[44:47], v[92:95], v[172:175], v[44:47]
	v_mfma_f32_16x16x32_bf16 v[40:43], v[108:111], v[172:175], v[40:43]
	v_mfma_f32_16x16x32_bf16 v[28:31], v[92:95], v[180:183], v[28:31]
	v_mfma_f32_16x16x32_bf16 v[24:27], v[108:111], v[180:183], v[24:27]
	v_mfma_f32_16x16x32_bf16 v[12:15], v[92:95], v[188:191], v[12:15]
	v_mfma_f32_16x16x32_bf16 v[8:11], v[108:111], v[188:191], v[8:11]
	v_mfma_f32_16x16x32_bf16 v[52:55], v[136:139], v[160:163], v[52:55]
	v_mfma_f32_16x16x32_bf16 v[48:51], v[148:151], v[160:163], v[48:51]
	v_mfma_f32_16x16x32_bf16 v[36:39], v[136:139], v[168:171], v[36:39]
	v_mfma_f32_16x16x32_bf16 v[32:35], v[148:151], v[168:171], v[32:35]
	v_mfma_f32_16x16x32_bf16 v[20:23], v[136:139], v[176:179], v[20:23]
	v_mfma_f32_16x16x32_bf16 v[16:19], v[148:151], v[176:179], v[16:19]
	v_mfma_f32_16x16x32_bf16 v[4:7], v[136:139], v[184:187], v[4:7]
	v_mfma_f32_16x16x32_bf16 v[0:3], v[148:151], v[184:187], v[0:3]
	v_mfma_f32_16x16x32_bf16 v[52:55], v[140:143], v[164:167], v[52:55]
	v_mfma_f32_16x16x32_bf16 v[48:51], v[152:155], v[164:167], v[48:51]
	v_mfma_f32_16x16x32_bf16 v[36:39], v[140:143], v[172:175], v[36:39]
	v_mfma_f32_16x16x32_bf16 v[32:35], v[152:155], v[172:175], v[32:35]
	v_mfma_f32_16x16x32_bf16 v[20:23], v[140:143], v[180:183], v[20:23]
	v_mfma_f32_16x16x32_bf16 v[16:19], v[152:155], v[180:183], v[16:19]
	v_mfma_f32_16x16x32_bf16 v[4:7], v[140:143], v[188:191], v[4:7]
	v_mfma_f32_16x16x32_bf16 v[0:3], v[152:155], v[188:191], v[0:3]
	s_setprio 0
	s_barrier
	s_add_i32 s64, 0, 0x18000
	s_add_i32 s65, 0, 0x1c000
	ds_read_b128 v[88:91], v248
	ds_read_b128 v[92:95], v248 offset:1024
	ds_read_b128 v[104:107], v248 offset:2048
	ds_read_b128 v[108:111], v248 offset:3072
	ds_read_b128 v[136:139], v249
	ds_read_b128 v[140:143], v249 offset:1024
	ds_read_b128 v[148:151], v249 offset:2048
	ds_read_b128 v[152:155], v249 offset:3072
	s_add_u32 s44, s44, 0x40000
	s_addc_u32 s45, s45, 0
	s_mov_b32 m0, s50
	ds_read_b128 v[160:163], v237 offset:32768
	ds_read_b128 v[164:167], v237 offset:33792
	ds_read_b128 v[168:171], v237 offset:34816
	ds_read_b128 v[172:175], v237 offset:35840
	ds_read_b128 v[176:179], v237 offset:36864
	ds_read_b128 v[180:183], v237 offset:37888
	ds_read_b128 v[184:187], v237 offset:38912
	ds_read_b128 v[188:191], v237 offset:39936
	global_load_lds_dwordx4 v192, s[44:45]
	s_mov_b32 m0, s51
	s_nop 0
	global_load_lds_dwordx4 v196, s[44:45]
	s_waitcnt vmcnt(8)
	s_waitcnt lgkmcnt(0)
	s_barrier
	s_setprio 1
	s_waitcnt lgkmcnt(0)
	v_mfma_f32_16x16x32_bf16 v[124:127], v[88:91], v[160:163], v[124:127]
	v_mfma_f32_16x16x32_bf16 v[120:123], v[104:107], v[160:163], v[120:123]
	v_mfma_f32_16x16x32_bf16 v[156:159], v[88:91], v[168:171], v[156:159]
	v_mfma_f32_16x16x32_bf16 v[144:147], v[104:107], v[168:171], v[144:147]
	v_mfma_f32_16x16x32_bf16 v[100:103], v[88:91], v[176:179], v[100:103]
	v_mfma_f32_16x16x32_bf16 v[96:99], v[104:107], v[176:179], v[96:99]
	v_mfma_f32_16x16x32_bf16 v[76:79], v[88:91], v[184:187], v[76:79]
	v_mfma_f32_16x16x32_bf16 v[72:75], v[104:107], v[184:187], v[72:75]
	v_mfma_f32_16x16x32_bf16 v[124:127], v[92:95], v[164:167], v[124:127]
	v_mfma_f32_16x16x32_bf16 v[120:123], v[108:111], v[164:167], v[120:123]
	v_mfma_f32_16x16x32_bf16 v[156:159], v[92:95], v[172:175], v[156:159]
	v_mfma_f32_16x16x32_bf16 v[144:147], v[108:111], v[172:175], v[144:147]
	v_mfma_f32_16x16x32_bf16 v[100:103], v[92:95], v[180:183], v[100:103]
	v_mfma_f32_16x16x32_bf16 v[96:99], v[108:111], v[180:183], v[96:99]
	v_mfma_f32_16x16x32_bf16 v[76:79], v[92:95], v[188:191], v[76:79]
	v_mfma_f32_16x16x32_bf16 v[72:75], v[108:111], v[188:191], v[72:75]
	v_mfma_f32_16x16x32_bf16 v[116:119], v[136:139], v[160:163], v[116:119]
	v_mfma_f32_16x16x32_bf16 v[112:115], v[148:151], v[160:163], v[112:115]
	v_mfma_f32_16x16x32_bf16 v[132:135], v[136:139], v[168:171], v[132:135]
	v_mfma_f32_16x16x32_bf16 v[128:131], v[148:151], v[168:171], v[128:131]
	v_mfma_f32_16x16x32_bf16 v[84:87], v[136:139], v[176:179], v[84:87]
	v_mfma_f32_16x16x32_bf16 v[80:83], v[148:151], v[176:179], v[80:83]
	v_mfma_f32_16x16x32_bf16 v[68:71], v[136:139], v[184:187], v[68:71]
	v_mfma_f32_16x16x32_bf16 v[64:67], v[148:151], v[184:187], v[64:67]
	v_mfma_f32_16x16x32_bf16 v[116:119], v[140:143], v[164:167], v[116:119]
	v_mfma_f32_16x16x32_bf16 v[112:115], v[152:155], v[164:167], v[112:115]
	v_mfma_f32_16x16x32_bf16 v[132:135], v[140:143], v[172:175], v[132:135]
	v_mfma_f32_16x16x32_bf16 v[128:131], v[152:155], v[172:175], v[128:131]
	v_mfma_f32_16x16x32_bf16 v[84:87], v[140:143], v[180:183], v[84:87]
	v_mfma_f32_16x16x32_bf16 v[80:83], v[152:155], v[180:183], v[80:83]
	v_mfma_f32_16x16x32_bf16 v[68:71], v[140:143], v[188:191], v[68:71]
	v_mfma_f32_16x16x32_bf16 v[64:67], v[152:155], v[188:191], v[64:67]
	s_setprio 0
	s_barrier
	s_add_i32 s44, s64, s47
	s_mov_b32 m0, s44
	ds_read_b128 v[160:163], v237 offset:49152
	ds_read_b128 v[164:167], v237 offset:50176
	ds_read_b128 v[168:171], v237 offset:51200
	ds_read_b128 v[172:175], v237 offset:52224
	ds_read_b128 v[176:179], v237 offset:53248
	ds_read_b128 v[180:183], v237 offset:54272
	ds_read_b128 v[184:187], v237 offset:55296
	ds_read_b128 v[188:191], v237 offset:56320
	global_load_lds_dwordx4 v194, s[98:99]
	s_add_i32 m0, s44, 0x2000
	s_add_u32 s42, s42, 0x40080
	s_addc_u32 s43, s43, 0
	s_add_i32 s44, s65, s47
	global_load_lds_dwordx4 v198, s[98:99]
	s_mov_b32 m0, s44
	s_nop 0
	global_load_lds_dwordx4 v194, s[42:43]
	s_add_i32 m0, s44, 0x2000
	s_nop 0
	global_load_lds_dwordx4 v198, s[42:43]
	s_mov_b32 m0, s55
	s_nop 0
	global_load_lds_dwordx4 v192, s[100:101]
	s_mov_b32 m0, s56
	s_nop 0
	global_load_lds_dwordx4 v196, s[100:101]
	s_waitcnt vmcnt(8)
	s_waitcnt lgkmcnt(0)
	s_barrier
	s_setprio 1
	s_waitcnt lgkmcnt(0)
	v_mfma_f32_16x16x32_bf16 v[60:63], v[88:91], v[160:163], v[60:63]
	v_mfma_f32_16x16x32_bf16 v[56:59], v[104:107], v[160:163], v[56:59]
	v_mfma_f32_16x16x32_bf16 v[44:47], v[88:91], v[168:171], v[44:47]
	v_mfma_f32_16x16x32_bf16 v[40:43], v[104:107], v[168:171], v[40:43]
	v_mfma_f32_16x16x32_bf16 v[28:31], v[88:91], v[176:179], v[28:31]
	v_mfma_f32_16x16x32_bf16 v[24:27], v[104:107], v[176:179], v[24:27]
	v_mfma_f32_16x16x32_bf16 v[12:15], v[88:91], v[184:187], v[12:15]
	v_mfma_f32_16x16x32_bf16 v[8:11], v[104:107], v[184:187], v[8:11]
	v_mfma_f32_16x16x32_bf16 v[60:63], v[92:95], v[164:167], v[60:63]
	v_mfma_f32_16x16x32_bf16 v[56:59], v[108:111], v[164:167], v[56:59]
	v_mfma_f32_16x16x32_bf16 v[44:47], v[92:95], v[172:175], v[44:47]
	v_mfma_f32_16x16x32_bf16 v[40:43], v[108:111], v[172:175], v[40:43]
	v_mfma_f32_16x16x32_bf16 v[28:31], v[92:95], v[180:183], v[28:31]
	v_mfma_f32_16x16x32_bf16 v[24:27], v[108:111], v[180:183], v[24:27]
	v_mfma_f32_16x16x32_bf16 v[12:15], v[92:95], v[188:191], v[12:15]
	v_mfma_f32_16x16x32_bf16 v[8:11], v[108:111], v[188:191], v[8:11]
	v_mfma_f32_16x16x32_bf16 v[52:55], v[136:139], v[160:163], v[52:55]
	v_mfma_f32_16x16x32_bf16 v[48:51], v[148:151], v[160:163], v[48:51]
	v_mfma_f32_16x16x32_bf16 v[36:39], v[136:139], v[168:171], v[36:39]
	v_mfma_f32_16x16x32_bf16 v[32:35], v[148:151], v[168:171], v[32:35]
	v_mfma_f32_16x16x32_bf16 v[20:23], v[136:139], v[176:179], v[20:23]
	v_mfma_f32_16x16x32_bf16 v[16:19], v[148:151], v[176:179], v[16:19]
	v_mfma_f32_16x16x32_bf16 v[4:7], v[136:139], v[184:187], v[4:7]
	v_mfma_f32_16x16x32_bf16 v[0:3], v[148:151], v[184:187], v[0:3]
	v_mfma_f32_16x16x32_bf16 v[52:55], v[140:143], v[164:167], v[52:55]
	v_mfma_f32_16x16x32_bf16 v[48:51], v[152:155], v[164:167], v[48:51]
	v_mfma_f32_16x16x32_bf16 v[36:39], v[140:143], v[172:175], v[36:39]
	v_mfma_f32_16x16x32_bf16 v[32:35], v[152:155], v[172:175], v[32:35]
	v_mfma_f32_16x16x32_bf16 v[20:23], v[140:143], v[180:183], v[20:23]
	v_mfma_f32_16x16x32_bf16 v[16:19], v[152:155], v[180:183], v[16:19]
	v_mfma_f32_16x16x32_bf16 v[4:7], v[140:143], v[188:191], v[4:7]
	v_mfma_f32_16x16x32_bf16 v[0:3], v[152:155], v[188:191], v[0:3]
	s_setprio 0
	s_barrier
	s_add_i32 s63, s63, 2
	s_add_u32 s40, s40, 0x100
	s_addc_u32 s41, s41, 0
	s_add_u32 s61, s61, 0x100
	s_addc_u32 s62, s62, 0
	s_cmp_gt_u32 s63, 13
	s_cbranch_scc0 .LBB0_836
